# gMLP item: spatial-weight fragments of groups 1..3 loaded before the preceding LayerNorm commit and copied in at the group top (counted waits behind the removed loads lowered by 4)
# baseline (speedup 1.0000x reference)
.LBB0_897:
	s_or_b64 exec, exec, s[12:13]
	v_bfe_u32 v32, v4, 2, 7
	v_lshl_add_u64 v[0:1], s[4:5], 0, v[32:33]
	v_mad_u64_u32 v[2:3], s[12:13], v0, s9, v[34:35]
	v_mov_b32_e32 v0, v3
	v_mad_u64_u32 v[0:1], s[12:13], v1, s9, v[0:1]
	v_mov_b32_e32 v3, v0
	v_lshlrev_b32_e32 v0, 3, v4
	v_and_b32_e32 v5, 24, v0
	v_lshlrev_b32_e32 v0, 1, v5
	v_mov_b32_e32 v1, v33
	v_lshl_add_u64 v[46:47], v[2:3], 0, v[0:1]
	global_load_dwordx4 v[8:11], v[46:47], off offset:2048
	v_lshlrev_b32_e32 v157, 2, v5
	global_load_dwordx4 v[12:15], v[46:47], off offset:2112
	global_load_dwordx4 v[16:19], v[46:47], off offset:2176
	global_load_dwordx4 v[0:3], v[46:47], off offset:2240
	s_waitcnt lgkmcnt(0)
	s_barrier
	global_load_dwordx4 v[20:23], v157, s[48:49]
	global_load_dwordx4 v[24:27], v157, s[50:51]
	global_load_dwordx4 v[28:31], v157, s[48:49] offset:16
	global_load_dwordx4 v[36:39], v157, s[50:51] offset:16
	global_load_dwordx4 v[178:181], v157, s[48:49] offset:128
	global_load_dwordx4 v[182:185], v157, s[50:51] offset:128
	global_load_dwordx4 v[186:189], v157, s[48:49] offset:144
	global_load_dwordx4 v[190:193], v157, s[50:51] offset:144
	global_load_dwordx4 v[194:197], v157, s[48:49] offset:256
	global_load_dwordx4 v[198:201], v157, s[50:51] offset:256
	global_load_dwordx4 v[202:205], v157, s[48:49] offset:272
	global_load_dwordx4 v[206:209], v157, s[50:51] offset:272
	global_load_dwordx4 v[210:213], v157, s[48:49] offset:384
	global_load_dwordx4 v[214:217], v157, s[50:51] offset:384
	global_load_dwordx4 v[218:221], v157, s[48:49] offset:400
	global_load_dwordx4 v[238:241], v157, s[50:51] offset:400
	v_lshl_add_u32 v6, v32, 3, 0
	v_lshlrev_b32_e32 v7, 1, v32
	v_add_u32_e32 v160, 0x11000, v6
	v_mul_u32_u24_e32 v5, 0x110, v5
	v_add3_u32 v155, 0, v7, v5
	ds_read_b64 v[6:7], v160
	v_ashrrev_i32_e32 v44, 2, v4
	v_and_b32_e32 v50, 15, v4
	v_mov_b32_e32 v49, v33
	v_readlane_b32 s56, v254, 12
	v_readlane_b32 s58, v254, 14
	v_readlane_b32 s59, v254, 15
	v_readlane_b32 s57, v254, 13
	v_readlane_b32 s60, v254, 16
	v_readlane_b32 s61, v254, 17
	v_readlane_b32 s62, v254, 18
	v_readlane_b32 s63, v254, 19
	v_readlane_b32 s64, v254, 20
	v_readlane_b32 s65, v254, 21
	v_readlane_b32 s66, v254, 22
	v_readlane_b32 s67, v254, 23
	v_readlane_b32 s68, v254, 24
	v_readlane_b32 s69, v254, 25
	v_readlane_b32 s70, v254, 26
	v_readlane_b32 s71, v254, 27
	s_waitcnt vmcnt(7)
	v_lshlrev_b32_e32 v5, 16, v8
	s_waitcnt lgkmcnt(0)
	v_sub_f32_e32 v5, v5, v6
	v_and_b32_e32 v8, 0xffff0000, v8
	v_mul_f32_e32 v5, v7, v5
	v_lshlrev_b32_e32 v32, 16, v9
	v_sub_f32_e32 v8, v8, v6
	s_waitcnt vmcnt(2)
	v_fma_f32 v5, v20, v5, v24
	v_and_b32_e32 v9, 0xffff0000, v9
	v_sub_f32_e32 v32, v32, v6
	v_mul_f32_e32 v8, v7, v8
	v_cvt_pk_bf16_f32 v5, v5, v33
	v_lshlrev_b32_e32 v40, 16, v10
	v_sub_f32_e32 v9, v9, v6
	v_mul_f32_e32 v32, v7, v32
	v_fma_f32 v8, v21, v8, v25
	ds_write_b16 v155, v5
	v_cvt_pk_bf16_f32 v5, v8, v33
	v_and_b32_e32 v10, 0xffff0000, v10
	v_sub_f32_e32 v40, v40, v6
	v_mul_f32_e32 v9, v7, v9
	v_fma_f32 v20, v22, v32, v26
	ds_write_b16 v155, v5 offset:272
	v_cvt_pk_bf16_f32 v5, v20, v33
	v_lshlrev_b32_e32 v41, 16, v11
	v_sub_f32_e32 v10, v10, v6
	v_mul_f32_e32 v40, v7, v40
	v_fmac_f32_e32 v27, v23, v9
	ds_write_b16 v155, v5 offset:544
	v_cvt_pk_bf16_f32 v5, v27, v33
	v_and_b32_e32 v11, 0xffff0000, v11
	v_sub_f32_e32 v41, v41, v6
	v_mul_f32_e32 v10, v7, v10
	s_waitcnt vmcnt(0)
	v_fma_f32 v9, v40, v28, v36
	ds_write_b16 v155, v5 offset:816
	v_cvt_pk_bf16_f32 v5, v9, v33
	v_sub_f32_e32 v11, v11, v6
	v_mul_f32_e32 v41, v7, v41
	v_fma_f32 v10, v10, v29, v37
	ds_write_b16 v155, v5 offset:1088
	v_cvt_pk_bf16_f32 v5, v10, v33
	v_mul_f32_e32 v11, v7, v11
	v_fma_f32 v21, v41, v30, v38
	ds_write_b16 v155, v5 offset:1360
	v_cvt_pk_bf16_f32 v5, v21, v33
	v_fmac_f32_e32 v39, v11, v31
	ds_write_b16 v155, v5 offset:1632
	v_cvt_pk_bf16_f32 v5, v39, v33
	v_mov_b64_e32 v[8:9], v[178:179]
	v_mov_b64_e32 v[10:11], v[180:181]
	v_mov_b64_e32 v[20:21], v[182:183]
	v_mov_b64_e32 v[22:23], v[184:185]
	v_mov_b64_e32 v[24:25], v[186:187]
	v_mov_b64_e32 v[26:27], v[188:189]
	v_mov_b64_e32 v[28:29], v[190:191]
	v_mov_b64_e32 v[30:31], v[192:193]
	v_lshlrev_b32_e32 v32, 16, v12
	v_sub_f32_e32 v32, v32, v6
	v_and_b32_e32 v12, 0xffff0000, v12
	v_mul_f32_e32 v32, v7, v32
	v_lshlrev_b32_e32 v36, 16, v13
	v_sub_f32_e32 v12, v12, v6
	ds_write_b16 v155, v5 offset:1904
	v_and_b32_e32 v13, 0xffff0000, v13
	v_sub_f32_e32 v36, v36, v6
	v_mul_f32_e32 v12, v7, v12
	v_lshlrev_b32_e32 v37, 16, v14
	v_sub_f32_e32 v13, v13, v6
	v_mul_f32_e32 v36, v7, v36
	v_and_b32_e32 v14, 0xffff0000, v14
	v_sub_f32_e32 v37, v37, v6
	v_mul_f32_e32 v13, v7, v13
	v_lshlrev_b32_e32 v38, 16, v15
	v_sub_f32_e32 v14, v14, v6
	v_mul_f32_e32 v37, v7, v37
	v_and_b32_e32 v15, 0xffff0000, v15
	v_sub_f32_e32 v38, v38, v6
	v_mul_f32_e32 v14, v7, v14
	v_sub_f32_e32 v15, v15, v6
	v_mul_f32_e32 v38, v7, v38
	v_mul_f32_e32 v15, v7, v15
	s_waitcnt vmcnt(2)
	v_fma_f32 v5, v32, v8, v20
	v_cvt_pk_bf16_f32 v5, v5, v33
	v_fma_f32 v8, v12, v9, v21
	ds_write_b16 v155, v5 offset:8704
	v_cvt_pk_bf16_f32 v5, v8, v33
	v_fma_f32 v9, v36, v10, v22
	ds_write_b16 v155, v5 offset:8976
	v_cvt_pk_bf16_f32 v5, v9, v33
	v_fmac_f32_e32 v23, v13, v11
	ds_write_b16 v155, v5 offset:9248
	v_cvt_pk_bf16_f32 v5, v23, v33
	s_waitcnt vmcnt(0)
	v_fma_f32 v10, v37, v24, v28
	ds_write_b16 v155, v5 offset:9520
	v_cvt_pk_bf16_f32 v5, v10, v33
	v_fma_f32 v11, v14, v25, v29
	ds_write_b16 v155, v5 offset:9792
	v_cvt_pk_bf16_f32 v5, v11, v33
	v_fma_f32 v12, v38, v26, v30
	ds_write_b16 v155, v5 offset:10064
	v_cvt_pk_bf16_f32 v5, v12, v33
	v_fmac_f32_e32 v31, v15, v27
	ds_write_b16 v155, v5 offset:10336
	v_cvt_pk_bf16_f32 v5, v31, v33
	v_mov_b64_e32 v[8:9], v[194:195]
	v_mov_b64_e32 v[10:11], v[196:197]
	v_mov_b64_e32 v[12:13], v[198:199]
	v_mov_b64_e32 v[14:15], v[200:201]
	v_mov_b64_e32 v[20:21], v[202:203]
	v_mov_b64_e32 v[22:23], v[204:205]
	v_mov_b64_e32 v[24:25], v[206:207]
	v_mov_b64_e32 v[26:27], v[208:209]
	v_lshlrev_b32_e32 v28, 16, v16
	v_sub_f32_e32 v28, v28, v6
	v_and_b32_e32 v16, 0xffff0000, v16
	v_mul_f32_e32 v28, v7, v28
	v_lshlrev_b32_e32 v29, 16, v17
	v_sub_f32_e32 v16, v16, v6
	ds_write_b16 v155, v5 offset:10608
	v_and_b32_e32 v17, 0xffff0000, v17
	v_sub_f32_e32 v29, v29, v6
	v_mul_f32_e32 v16, v7, v16
	v_lshlrev_b32_e32 v30, 16, v18
	v_sub_f32_e32 v17, v17, v6
	v_mul_f32_e32 v29, v7, v29
	v_and_b32_e32 v18, 0xffff0000, v18
	v_sub_f32_e32 v30, v30, v6
	v_mul_f32_e32 v17, v7, v17
	v_lshlrev_b32_e32 v31, 16, v19
	v_sub_f32_e32 v18, v18, v6
	v_mul_f32_e32 v30, v7, v30
	v_and_b32_e32 v19, 0xffff0000, v19
	v_sub_f32_e32 v31, v31, v6
	v_mul_f32_e32 v18, v7, v18
	v_sub_f32_e32 v19, v19, v6
	v_mul_f32_e32 v31, v7, v31
	v_mul_f32_e32 v19, v7, v19
	s_waitcnt vmcnt(2)
	v_fma_f32 v5, v28, v8, v12
	v_cvt_pk_bf16_f32 v5, v5, v33
	v_fma_f32 v8, v16, v9, v13
	ds_write_b16 v155, v5 offset:17408
	v_cvt_pk_bf16_f32 v5, v8, v33
	v_fma_f32 v9, v29, v10, v14
	ds_write_b16 v155, v5 offset:17680
	v_cvt_pk_bf16_f32 v5, v9, v33
	v_fmac_f32_e32 v15, v17, v11
	ds_write_b16 v155, v5 offset:17952
	v_cvt_pk_bf16_f32 v5, v15, v33
	s_waitcnt vmcnt(0)
	v_fma_f32 v10, v30, v20, v24
	ds_write_b16 v155, v5 offset:18224
	v_cvt_pk_bf16_f32 v5, v10, v33
	v_fma_f32 v11, v18, v21, v25
	ds_write_b16 v155, v5 offset:18496
	v_cvt_pk_bf16_f32 v5, v11, v33
	v_fma_f32 v12, v31, v22, v26
	ds_write_b16 v155, v5 offset:18768
	v_cvt_pk_bf16_f32 v5, v12, v33
	v_fmac_f32_e32 v27, v19, v23
	ds_write_b16 v155, v5 offset:19040
	v_cvt_pk_bf16_f32 v5, v27, v33
	v_mov_b64_e32 v[8:9], v[210:211]
	v_mov_b64_e32 v[10:11], v[212:213]
	v_mov_b64_e32 v[12:13], v[214:215]
	v_mov_b64_e32 v[14:15], v[216:217]
	v_mov_b64_e32 v[16:17], v[218:219]
	v_mov_b64_e32 v[18:19], v[220:221]
	v_mov_b64_e32 v[20:21], v[238:239]
	v_mov_b64_e32 v[22:23], v[240:241]
	v_bfe_u32 v24, v4, 4, 2
	v_and_b32_e32 v26, -16, v44
	v_lshlrev_b32_e32 v32, 3, v24
	v_lshlrev_b32_e32 v48, 4, v24
	v_ashrrev_i32_e32 v25, 31, v26
	v_or_b32_e32 v24, v26, v50
	v_lshl_add_u64 v[26:27], s[0:1], 0, v[48:49]
	v_lshl_add_u64 v[36:37], s[4:5], 0, v[24:25]
	v_lshlrev_b64 v[24:25], 8, v[24:25]
	v_lshl_add_u64 v[42:43], v[26:27], 0, v[24:25]
	v_lshlrev_b32_e32 v24, 16, v0
	v_and_b32_e32 v0, 0xffff0000, v0
	v_lshlrev_b32_e32 v27, 16, v3
	v_and_b32_e32 v3, 0xffff0000, v3
	v_sub_f32_e32 v0, v0, v6
	v_lshlrev_b32_e32 v25, 16, v1
	v_and_b32_e32 v1, 0xffff0000, v1
	v_lshlrev_b32_e32 v26, 16, v2
	v_and_b32_e32 v2, 0xffff0000, v2
	v_sub_f32_e32 v24, v24, v6
	v_sub_f32_e32 v3, v3, v6
	v_mul_f32_e32 v0, v7, v0
	v_sub_f32_e32 v25, v25, v6
	v_sub_f32_e32 v1, v1, v6
	v_sub_f32_e32 v26, v26, v6
	v_sub_f32_e32 v2, v2, v6
	v_sub_f32_e32 v27, v27, v6
	v_mul_f32_e32 v6, v7, v24
	v_mul_f32_e32 v3, v7, v3
	v_mul_f32_e32 v24, v7, v25
	ds_write_b16 v155, v5 offset:19312
	v_mul_f32_e32 v1, v7, v1
	v_mul_f32_e32 v25, v7, v26
	v_mul_f32_e32 v2, v7, v2
	v_mul_f32_e32 v26, v7, v27
	v_mad_u64_u32 v[38:39], s[12:13], v36, s9, v[34:35]
	s_waitcnt vmcnt(2)
	v_fma_f32 v0, v0, v9, v13
	v_fma_f32 v5, v6, v8, v12
	s_waitcnt vmcnt(0)
	v_fmac_f32_e32 v23, v3, v19
	v_cvt_pk_bf16_f32 v3, v5, v33
	ds_write_b16 v155, v3 offset:26112
	v_cvt_pk_bf16_f32 v0, v0, v33
	v_fma_f32 v6, v24, v10, v14
	ds_write_b16 v155, v0 offset:26384
	v_cvt_pk_bf16_f32 v0, v6, v33
	v_fmac_f32_e32 v15, v1, v11
	ds_write_b16 v155, v0 offset:26656
	v_cvt_pk_bf16_f32 v0, v15, v33
	v_fma_f32 v1, v25, v16, v20
	ds_write_b16 v155, v0 offset:26928
	v_cvt_pk_bf16_f32 v0, v1, v33
	v_fma_f32 v2, v2, v17, v21
	ds_write_b16 v155, v0 offset:27200
	v_cvt_pk_bf16_f32 v0, v2, v33
	v_fma_f32 v7, v26, v18, v22
	ds_write_b16 v155, v0 offset:27472
	v_cvt_pk_bf16_f32 v0, v7, v33
	ds_write_b16 v155, v0 offset:27744
	v_cvt_pk_bf16_f32 v0, v23, v33
	ds_write_b16 v155, v0 offset:28016
	s_waitcnt lgkmcnt(0)
	s_barrier
	global_load_dwordx4 v[20:23], v[42:43], off
	global_load_dwordx4 v[24:27], v[42:43], off offset:64
	v_mov_b32_e32 v0, v39
	v_mad_u64_u32 v[0:1], s[12:13], v37, s9, v[0:1]
	v_mov_b32_e32 v39, v0
	v_lshl_add_u64 v[40:41], v[38:39], 0, v[32:33]
	global_load_dwordx2 v[224:225], v[40:41], off offset:1056
	global_load_dwordx2 v[226:227], v[40:41], off offset:1088
	global_load_dwordx2 v[228:229], v[40:41], off offset:1120
	global_load_dwordx2 v[230:231], v[40:41], off offset:1152
	global_load_dwordx2 v[232:233], v[40:41], off offset:1184
	global_load_dwordx2 v[234:235], v[40:41], off offset:1216
	global_load_dwordx2 v[236:237], v[40:41], off offset:1248
	global_load_dwordx2 v[52:53], v[40:41], off offset:1024
	global_load_dwordx4 v[28:31], v[42:43], off offset:128
	global_load_dwordx4 v[16:19], v[42:43], off offset:192
	v_bfi_b32 v0, -16, v44, v4
	v_ashrrev_i32_e32 v1, 31, v0
	v_lshl_add_u64 v[44:45], v[0:1], 2, s[58:59]
	global_load_dword v54, v[44:45], off
	v_mul_u32_u24_e32 v0, 0x110, v50
	v_add3_u32 v152, 0, v48, v0
	ds_read_b128 v[0:3], v152
	ds_read_b128 v[4:7], v152 offset:64
	ds_read_b128 v[48:51], v152 offset:128
	s_waitcnt vmcnt(5) lgkmcnt(2)
	v_mfma_f32_16x16x32_bf16 v[0:3], v[0:3], v[20:23], 0
	global_load_dwordx4 v[12:15], v[46:47], off offset:2304
	global_load_dwordx4 v[8:11], v[46:47], off offset:2368
	ds_read_b128 v[56:59], v152 offset:192
	s_waitcnt vmcnt(5)
	v_lshlrev_b32_e32 v64, 16, v52
	s_waitcnt lgkmcnt(2)
	v_mfma_f32_16x16x32_bf16 v[60:63], v[4:7], v[24:27], v[0:3]
	v_and_b32_e32 v65, 0xffff0000, v52
	v_lshlrev_b32_e32 v52, 16, v53
	v_and_b32_e32 v53, 0xffff0000, v53
	s_waitcnt vmcnt(4) lgkmcnt(1)
	v_mfma_f32_16x16x32_bf16 v[48:51], v[48:51], v[28:31], v[60:63]
	global_load_dwordx4 v[4:7], v[46:47], off offset:2432
	global_load_dwordx4 v[0:3], v[46:47], off offset:2496
	s_waitcnt vmcnt(0)
	v_lshlrev_b32_e32 v101, 16, v2
	s_waitcnt lgkmcnt(0)
	v_mfma_f32_16x16x32_bf16 v[48:51], v[56:59], v[16:19], v[48:51]
	v_and_b32_e32 v102, 0xffff0000, v2
	v_and_b32_e32 v100, 0xffff0000, v1
	v_lshlrev_b32_e32 v103, 16, v3
	v_and_b32_e32 v104, 0xffff0000, v3
	s_nop 3
	v_pk_add_f32 v[48:49], v[54:55], v[48:49] op_sel_hi:[0,1]
	v_pk_add_f32 v[50:51], v[54:55], v[50:51] op_sel_hi:[0,1]
	v_pk_mul_f32 v[48:49], v[48:49], v[64:65]
	v_pk_mul_f32 v[50:51], v[50:51], v[52:53]
	v_cvt_pk_bf16_f32 v150, v48, v49
	v_mul_f32_e32 v2, v49, v49
	v_cvt_pk_bf16_f32 v148, v50, v51
	ds_read_b128 v[56:59], v152 offset:4352
	ds_read_b128 v[60:63], v152 offset:4416
	s_waitcnt lgkmcnt(1)
	v_mfma_f32_16x16x32_bf16 v[56:59], v[56:59], v[20:23], 0
	v_pk_fma_f32 v[2:3], v[48:49], v[48:49], v[2:3] op_sel_hi:[1,1,0]
	s_nop 0
	v_mov_b32_e32 v84, v2
	s_waitcnt lgkmcnt(0)
	v_mfma_f32_16x16x32_bf16 v[56:59], v[60:63], v[24:27], v[56:59]
	ds_read_b128 v[60:63], v152 offset:4480
	ds_read_b128 v[64:67], v152 offset:4544
	v_mov_b64_e32 v[52:53], v[224:225]
	s_waitcnt lgkmcnt(1)
	v_mfma_f32_16x16x32_bf16 v[56:59], v[60:63], v[28:31], v[56:59]
	s_waitcnt vmcnt(0)
	v_lshlrev_b32_e32 v60, 16, v52
	s_waitcnt lgkmcnt(0)
	v_mfma_f32_16x16x32_bf16 v[56:59], v[64:67], v[16:19], v[56:59]
	v_and_b32_e32 v61, 0xffff0000, v52
	v_lshlrev_b32_e32 v62, 16, v53
	v_and_b32_e32 v63, 0xffff0000, v53
	s_nop 4
	v_pk_add_f32 v[56:57], v[54:55], v[56:57] op_sel_hi:[0,1]
	v_pk_add_f32 v[58:59], v[54:55], v[58:59] op_sel_hi:[0,1]
	v_pk_mul_f32 v[52:53], v[56:57], v[60:61]
	v_pk_mul_f32 v[60:61], v[58:59], v[62:63]
	v_cvt_pk_bf16_f32 v145, v52, v53
	s_nop 0
	v_cvt_pk_bf16_f32 v142, v60, v61
	ds_read_b128 v[56:59], v152 offset:8704
	ds_read_b128 v[62:65], v152 offset:8768
	s_waitcnt lgkmcnt(1)
	v_mfma_f32_16x16x32_bf16 v[56:59], v[56:59], v[20:23], 0
	s_waitcnt lgkmcnt(0)
	v_mfma_f32_16x16x32_bf16 v[56:59], v[62:65], v[24:27], v[56:59]
	ds_read_b128 v[62:65], v152 offset:8832
	ds_read_b128 v[66:69], v152 offset:8896
	s_waitcnt lgkmcnt(1)
	v_mfma_f32_16x16x32_bf16 v[56:59], v[62:65], v[28:31], v[56:59]
	v_mov_b64_e32 v[62:63], v[226:227]
	s_waitcnt vmcnt(0)
	v_lshlrev_b32_e32 v65, 16, v63
	s_waitcnt lgkmcnt(0)
	v_mfma_f32_16x16x32_bf16 v[56:59], v[66:69], v[16:19], v[56:59]
	v_and_b32_e32 v63, 0xffff0000, v63
	s_nop 6
	v_add_f32_e32 v55, v54, v56
	v_add_f32_e32 v56, v54, v57
	v_add_f32_e32 v57, v54, v58
	v_add_f32_e32 v58, v54, v59
	v_lshlrev_b32_e32 v59, 16, v62
	v_and_b32_e32 v62, 0xffff0000, v62
	v_mul_f32_e32 v64, v55, v59
	v_mul_f32_e32 v68, v56, v62
	v_mul_f32_e32 v66, v57, v65
	v_mul_f32_e32 v62, v58, v63
	v_cvt_pk_bf16_f32 v139, v64, v68
	v_cvt_pk_bf16_f32 v137, v66, v62
	ds_read_b128 v[56:59], v152 offset:13056
	ds_read_b128 v[70:73], v152 offset:13120
	s_waitcnt lgkmcnt(1)
	v_mfma_f32_16x16x32_bf16 v[56:59], v[56:59], v[20:23], 0
	s_waitcnt lgkmcnt(0)
	v_mfma_f32_16x16x32_bf16 v[56:59], v[70:73], v[24:27], v[56:59]
	ds_read_b128 v[70:73], v152 offset:13184
	ds_read_b128 v[74:77], v152 offset:13248
	v_mov_b64_e32 v[78:79], v[228:229]
	s_waitcnt lgkmcnt(1)
	v_mfma_f32_16x16x32_bf16 v[56:59], v[70:73], v[28:31], v[56:59]
	v_mov_b32_e32 v70, v64
	v_mov_b32_e32 v72, v66
	s_waitcnt vmcnt(0)
	v_lshlrev_b32_e32 v71, 16, v79
	s_waitcnt lgkmcnt(0)
	v_mfma_f32_16x16x32_bf16 v[56:59], v[74:77], v[16:19], v[56:59]
	v_and_b32_e32 v73, 0xffff0000, v79
	s_nop 6
	v_add_f32_e32 v55, v54, v56
	v_add_f32_e32 v56, v54, v57
	v_add_f32_e32 v65, v54, v58
	v_add_f32_e32 v67, v54, v59
	v_lshlrev_b32_e32 v57, 16, v78
	v_and_b32_e32 v58, 0xffff0000, v78
	v_mul_f32_e32 v85, v55, v57
	v_mul_f32_e32 v75, v56, v58
	v_pk_mul_f32 v[86:87], v[64:65], v[70:71]
	v_pk_mul_f32 v[88:89], v[66:67], v[72:73]
	v_cvt_pk_bf16_f32 v136, v85, v75
	v_lshlrev_b32_e32 v72, 16, v15
	v_cvt_pk_bf16_f32 v133, v87, v89
	ds_read_b128 v[56:59], v152 offset:17408
	ds_read_b128 v[76:79], v152 offset:17472
	s_waitcnt lgkmcnt(1)
	v_mfma_f32_16x16x32_bf16 v[56:59], v[56:59], v[20:23], 0
	v_and_b32_e32 v15, 0xffff0000, v15
	v_pk_mul_f32 v[48:49], v[88:89], v[88:89]
	s_waitcnt lgkmcnt(0)
	v_mfma_f32_16x16x32_bf16 v[56:59], v[76:79], v[24:27], v[56:59]
	ds_read_b128 v[76:79], v152 offset:17536
	ds_read_b128 v[80:83], v152 offset:17600
	s_waitcnt lgkmcnt(1)
	v_mfma_f32_16x16x32_bf16 v[56:59], v[76:79], v[28:31], v[56:59]
	v_mov_b64_e32 v[76:77], v[230:231]
	s_waitcnt lgkmcnt(0)
	v_mfma_f32_16x16x32_bf16 v[56:59], v[80:83], v[16:19], v[56:59]
	s_nop 7
	v_mov_b32_e32 v78, v56
	v_mov_b32_e32 v79, v58
	v_mov_b32_e32 v58, v57
	v_pk_add_f32 v[56:57], v[54:55], v[78:79] op_sel_hi:[0,1]
	v_pk_add_f32 v[58:59], v[54:55], v[58:59] op_sel_hi:[0,1]
	s_waitcnt vmcnt(0)
	v_lshlrev_b32_e32 v79, 16, v77
	v_lshlrev_b32_e32 v78, 16, v76
	v_and_b32_e32 v77, 0xffff0000, v77
	v_and_b32_e32 v76, 0xffff0000, v76
	v_pk_mul_f32 v[90:91], v[56:57], v[78:79]
	v_pk_mul_f32 v[92:93], v[58:59], v[76:77]
	s_nop 0
	v_cvt_pk_bf16_f32 v134, v90, v92
	v_cvt_pk_bf16_f32 v132, v91, v93
	ds_read_b128 v[56:59], v152 offset:21760
	ds_read_b128 v[76:79], v152 offset:21824
	s_waitcnt lgkmcnt(1)
	v_mfma_f32_16x16x32_bf16 v[56:59], v[56:59], v[20:23], 0
	s_waitcnt lgkmcnt(0)
	v_mfma_f32_16x16x32_bf16 v[56:59], v[76:79], v[24:27], v[56:59]
	ds_read_b128 v[76:79], v152 offset:21888
	ds_read_b128 v[80:83], v152 offset:21952
	s_waitcnt lgkmcnt(1)
	v_mfma_f32_16x16x32_bf16 v[56:59], v[76:79], v[28:31], v[56:59]
	v_mov_b64_e32 v[76:77], v[232:233]
	s_waitcnt lgkmcnt(0)
	v_mfma_f32_16x16x32_bf16 v[56:59], v[80:83], v[16:19], v[56:59]
	s_nop 7
	v_pk_add_f32 v[56:57], v[54:55], v[56:57] op_sel_hi:[0,1]
	v_pk_add_f32 v[78:79], v[54:55], v[58:59] op_sel_hi:[0,1]
	s_waitcnt vmcnt(0)
	v_lshlrev_b32_e32 v58, 16, v76
	v_and_b32_e32 v59, 0xffff0000, v76
	v_lshlrev_b32_e32 v76, 16, v77
	v_and_b32_e32 v77, 0xffff0000, v77
	v_pk_mul_f32 v[58:59], v[56:57], v[58:59]
	v_pk_mul_f32 v[94:95], v[78:79], v[76:77]
	v_cvt_pk_bf16_f32 v130, v58, v59
	s_nop 0
	v_cvt_pk_bf16_f32 v129, v94, v95
	ds_read_b128 v[76:79], v152 offset:26112
	ds_read_b128 v[80:83], v152 offset:26176
	s_waitcnt lgkmcnt(1)
	v_mfma_f32_16x16x32_bf16 v[76:79], v[76:79], v[20:23], 0
	s_waitcnt lgkmcnt(0)
	v_mfma_f32_16x16x32_bf16 v[76:79], v[80:83], v[24:27], v[76:79]
	ds_read_b128 v[80:83], v152 offset:26240
	ds_read_b128 v[96:99], v152 offset:26304
	v_mov_b64_e32 v[56:57], v[234:235]
	s_waitcnt vmcnt(0)
	v_lshlrev_b32_e32 v66, 16, v56
	s_waitcnt lgkmcnt(1)
	v_mfma_f32_16x16x32_bf16 v[76:79], v[80:83], v[28:31], v[76:79]
	v_and_b32_e32 v56, 0xffff0000, v56
	v_lshlrev_b32_e32 v70, 16, v57
	v_and_b32_e32 v57, 0xffff0000, v57
	s_waitcnt lgkmcnt(0)
	v_mfma_f32_16x16x32_bf16 v[76:79], v[96:99], v[16:19], v[76:79]
	s_nop 7
	v_add_f32_e32 v55, v54, v76
	v_add_f32_e32 v63, v54, v77
	v_add_f32_e32 v64, v54, v78
	v_add_f32_e32 v69, v54, v79
	v_mul_f32_e32 v96, v55, v66
	v_mul_f32_e32 v66, v63, v56
	v_mul_f32_e32 v98, v64, v70
	v_mul_f32_e32 v64, v69, v57
	v_cvt_pk_bf16_f32 v128, v96, v66
	v_cvt_pk_bf16_f32 v127, v98, v64
	ds_read_b128 v[76:79], v152 offset:30464
	ds_read_b128 v[80:83], v152 offset:30528
	s_waitcnt lgkmcnt(1)
	v_mfma_f32_16x16x32_bf16 v[20:23], v[76:79], v[20:23], 0
	v_mov_b32_e32 v76, v96
	v_mov_b32_e32 v78, v98
	v_and_b32_e32 v56, 0xffff0000, v12
	s_waitcnt lgkmcnt(0)
	v_mfma_f32_16x16x32_bf16 v[20:23], v[80:83], v[24:27], v[20:23]
	ds_read_b128 v[24:27], v152 offset:30592
	ds_read_b128 v[80:83], v152 offset:30656
	v_lshlrev_b32_e32 v63, 16, v13
	v_and_b32_e32 v69, 0xffff0000, v13
	s_waitcnt lgkmcnt(1)
	v_mfma_f32_16x16x32_bf16 v[20:23], v[24:27], v[28:31], v[20:23]
	v_mov_b64_e32 v[24:25], v[236:237]
	v_lshlrev_b32_e32 v70, 16, v14
	v_and_b32_e32 v14, 0xffff0000, v14
	s_waitcnt lgkmcnt(0)
	v_mfma_f32_16x16x32_bf16 v[16:19], v[80:83], v[16:19], v[20:23]
	s_waitcnt vmcnt(0)
	v_lshlrev_b32_e32 v77, 16, v25
	s_nop 5
	v_add_f32_e32 v16, v54, v16
	v_add_f32_e32 v17, v54, v17
	v_add_f32_e32 v97, v54, v18
	v_add_f32_e32 v99, v54, v19
	v_lshlrev_b32_e32 v18, 16, v24
	v_and_b32_e32 v19, 0xffff0000, v24
	v_and_b32_e32 v79, 0xffff0000, v25
	v_mul_f32_e32 v57, v16, v18
	v_mul_f32_e32 v55, v17, v19
	v_pk_mul_f32 v[80:81], v[96:97], v[76:77]
	v_pk_mul_f32 v[82:83], v[98:99], v[78:79]
	v_cvt_pk_bf16_f32 v126, v57, v55
	v_lshlrev_b32_e32 v54, 16, v12
	v_cvt_pk_bf16_f32 v125, v81, v83
	v_add_co_u32_e32 v242, vcc, s26, v42
	s_nop 1
	v_addc_co_u32_e32 v243, vcc, 0, v43, vcc
	global_load_dwordx4 v[222:225], v[242:243], off
	global_load_dwordx4 v[226:229], v[242:243], off offset:64
	global_load_dwordx4 v[230:233], v[242:243], off offset:128
	global_load_dwordx4 v[234:237], v[242:243], off offset:192
	global_load_dwordx4 v[16:19], v157, s[48:49] offset:512
	global_load_dwordx4 v[20:23], v157, s[50:51] offset:512
	global_load_dwordx4 v[24:27], v157, s[48:49] offset:528
	global_load_dwordx4 v[28:31], v157, s[50:51] offset:528
	global_load_dwordx4 v[178:181], v157, s[48:49] offset:640
	global_load_dwordx4 v[182:185], v157, s[50:51] offset:640
	global_load_dwordx4 v[186:189], v157, s[48:49] offset:656
	global_load_dwordx4 v[190:193], v157, s[50:51] offset:656
	global_load_dwordx4 v[194:197], v157, s[48:49] offset:768
	global_load_dwordx4 v[198:201], v157, s[50:51] offset:768
	global_load_dwordx4 v[202:205], v157, s[48:49] offset:784
	global_load_dwordx4 v[206:209], v157, s[50:51] offset:784
	global_load_dwordx4 v[210:213], v157, s[48:49] offset:896
	global_load_dwordx4 v[214:217], v157, s[50:51] offset:896
	global_load_dwordx4 v[218:221], v157, s[48:49] offset:912
	global_load_dwordx4 v[238:241], v157, s[50:51] offset:912
	ds_read_b64 v[12:13], v160
	v_and_b32_e32 v96, 0xffff0000, v0
	v_lshlrev_b32_e32 v98, 16, v1
	v_mov_b32_e32 v76, v66
	v_mov_b32_e32 v78, v64
	s_waitcnt lgkmcnt(0)
	v_sub_f32_e32 v54, v54, v12
	v_sub_f32_e32 v15, v15, v12
	v_sub_f32_e32 v56, v56, v12
	v_mul_f32_e32 v54, v13, v54
	v_mul_f32_e32 v15, v13, v15
	v_sub_f32_e32 v63, v63, v12
	v_mul_f32_e32 v56, v13, v56
	v_sub_f32_e32 v69, v69, v12
	v_sub_f32_e32 v14, v14, v12
	v_mul_f32_e32 v63, v13, v63
	v_sub_f32_e32 v70, v70, v12
	v_mul_f32_e32 v69, v13, v69
	v_mul_f32_e32 v14, v13, v14
	v_sub_f32_e32 v72, v72, v12
	v_mul_f32_e32 v70, v13, v70
	v_mul_f32_e32 v72, v13, v72
	s_waitcnt vmcnt(2)
	v_fma_f32 v16, v16, v54, v20
	v_fma_f32 v17, v17, v56, v21
	s_waitcnt vmcnt(0)
	v_fmac_f32_e32 v31, v27, v15
	v_cvt_pk_bf16_f32 v15, v16, v33
	ds_write_b16 v155, v15 offset:34816
	v_cvt_pk_bf16_f32 v15, v17, v33
	v_fma_f32 v18, v18, v63, v22
	ds_write_b16 v155, v15 offset:35088
	v_cvt_pk_bf16_f32 v15, v18, v33
	v_fmac_f32_e32 v23, v19, v69
	v_fma_f32 v14, v25, v14, v29
	ds_write_b16 v155, v15 offset:35360
	v_cvt_pk_bf16_f32 v15, v23, v33
	v_fma_f32 v19, v24, v70, v28
	ds_write_b16 v155, v15 offset:35632
	v_cvt_pk_bf16_f32 v15, v19, v33
	ds_write_b16 v155, v15 offset:35904
	v_cvt_pk_bf16_f32 v14, v14, v33
	v_fma_f32 v20, v26, v72, v30
	ds_write_b16 v155, v14 offset:36176
	v_cvt_pk_bf16_f32 v14, v20, v33
	ds_write_b16 v155, v14 offset:36448
	v_cvt_pk_bf16_f32 v30, v31, v33
	v_mov_b64_e32 v[14:15], v[178:179]
	v_mov_b64_e32 v[16:17], v[180:181]
	v_mov_b64_e32 v[18:19], v[182:183]
	v_mov_b64_e32 v[20:21], v[184:185]
	v_mov_b64_e32 v[22:23], v[186:187]
	v_mov_b64_e32 v[24:25], v[188:189]
	v_mov_b64_e32 v[26:27], v[190:191]
	v_mov_b64_e32 v[28:29], v[192:193]
	v_lshlrev_b32_e32 v31, 16, v8
	v_and_b32_e32 v8, 0xffff0000, v8
	v_lshlrev_b32_e32 v63, 16, v11
	v_and_b32_e32 v11, 0xffff0000, v11
	v_sub_f32_e32 v8, v8, v12
	v_lshlrev_b32_e32 v54, 16, v9
	v_sub_f32_e32 v31, v31, v12
	v_sub_f32_e32 v11, v11, v12
	v_mul_f32_e32 v8, v13, v8
	v_and_b32_e32 v9, 0xffff0000, v9
	v_sub_f32_e32 v54, v54, v12
	v_mul_f32_e32 v31, v13, v31
	v_mul_f32_e32 v11, v13, v11
	v_lshlrev_b32_e32 v56, 16, v10
	v_sub_f32_e32 v9, v9, v12
	v_mul_f32_e32 v54, v13, v54
	ds_write_b16 v155, v30 offset:36720
	v_and_b32_e32 v10, 0xffff0000, v10
	v_sub_f32_e32 v56, v56, v12
	v_mul_f32_e32 v9, v13, v9
	v_sub_f32_e32 v10, v10, v12
	v_mul_f32_e32 v56, v13, v56
	v_sub_f32_e32 v63, v63, v12
	v_mul_f32_e32 v10, v13, v10
	v_mul_f32_e32 v63, v13, v63
	v_lshlrev_b32_e32 v30, 16, v7
	v_and_b32_e32 v7, 0xffff0000, v7
	v_sub_f32_e32 v7, v7, v12
	v_mul_f32_e32 v7, v13, v7
	v_sub_f32_e32 v30, v30, v12
	v_mul_f32_e32 v30, v13, v30
	v_mov_b32_e32 v69, v65
	v_mov_b32_e32 v70, v68
	v_mov_b32_e32 v72, v62
	v_mov_b32_e32 v65, v99
	s_waitcnt vmcnt(2)
	v_fma_f32 v8, v8, v15, v19
	v_fma_f32 v14, v31, v14, v18
	s_waitcnt vmcnt(0)
	v_fmac_f32_e32 v29, v11, v25
	v_cvt_pk_bf16_f32 v11, v14, v33
	ds_write_b16 v155, v11 offset:43520
	v_cvt_pk_bf16_f32 v8, v8, v33
	v_fma_f32 v15, v54, v16, v20
	ds_write_b16 v155, v8 offset:43792
	v_cvt_pk_bf16_f32 v8, v15, v33
	v_fmac_f32_e32 v21, v9, v17
	ds_write_b16 v155, v8 offset:44064
	v_cvt_pk_bf16_f32 v8, v21, v33
	v_fma_f32 v9, v56, v22, v26
	ds_write_b16 v155, v8 offset:44336
	v_cvt_pk_bf16_f32 v8, v9, v33
	v_fma_f32 v10, v10, v23, v27
	ds_write_b16 v155, v8 offset:44608
	v_cvt_pk_bf16_f32 v8, v10, v33
	v_fma_f32 v16, v63, v24, v28
	ds_write_b16 v155, v8 offset:44880
	v_cvt_pk_bf16_f32 v8, v16, v33
	ds_write_b16 v155, v8 offset:45152
	v_cvt_pk_bf16_f32 v26, v29, v33
	v_mov_b64_e32 v[8:9], v[194:195]
	v_mov_b64_e32 v[10:11], v[196:197]
	v_mov_b64_e32 v[14:15], v[198:199]
	v_mov_b64_e32 v[16:17], v[200:201]
	v_mov_b64_e32 v[18:19], v[202:203]
	v_mov_b64_e32 v[20:21], v[204:205]
	v_mov_b64_e32 v[22:23], v[206:207]
	v_mov_b64_e32 v[24:25], v[208:209]
	v_lshlrev_b32_e32 v27, 16, v4
	v_and_b32_e32 v4, 0xffff0000, v4
	v_sub_f32_e32 v4, v4, v12
	v_lshlrev_b32_e32 v28, 16, v5
	v_sub_f32_e32 v27, v27, v12
	v_mul_f32_e32 v4, v13, v4
	v_and_b32_e32 v5, 0xffff0000, v5
	v_sub_f32_e32 v28, v28, v12
	v_mul_f32_e32 v27, v13, v27
	v_lshlrev_b32_e32 v29, 16, v6
	v_sub_f32_e32 v5, v5, v12
	v_mul_f32_e32 v28, v13, v28
	ds_write_b16 v155, v26 offset:45424
	v_and_b32_e32 v6, 0xffff0000, v6
	v_sub_f32_e32 v29, v29, v12
	v_mul_f32_e32 v5, v13, v5
	v_sub_f32_e32 v6, v6, v12
	v_mul_f32_e32 v29, v13, v29
	v_mul_f32_e32 v6, v13, v6
	v_lshlrev_b32_e32 v56, 16, v0
	v_mul_f32_e32 v0, v51, v51
	v_pk_fma_f32 v[0:1], v[50:51], v[50:51], v[0:1] op_sel_hi:[1,1,0]
	v_mov_b32_e32 v63, v67
	v_mov_b32_e32 v67, v97
	s_waitcnt vmcnt(2)
	v_fma_f32 v4, v4, v9, v15
	v_fma_f32 v8, v27, v8, v14
	s_waitcnt vmcnt(0)
	v_fmac_f32_e32 v25, v7, v21
	v_cvt_pk_bf16_f32 v7, v8, v33
	ds_write_b16 v155, v7 offset:52224
	v_cvt_pk_bf16_f32 v4, v4, v33
	v_fma_f32 v9, v28, v10, v16
	ds_write_b16 v155, v4 offset:52496
	v_cvt_pk_bf16_f32 v4, v9, v33
	v_fmac_f32_e32 v17, v5, v11
	ds_write_b16 v155, v4 offset:52768
	v_cvt_pk_bf16_f32 v4, v17, v33
	v_fma_f32 v5, v29, v18, v22
	ds_write_b16 v155, v4 offset:53040
	v_cvt_pk_bf16_f32 v4, v5, v33
	v_fma_f32 v6, v6, v19, v23
	ds_write_b16 v155, v4 offset:53312
	v_cvt_pk_bf16_f32 v4, v6, v33
	v_fma_f32 v10, v30, v20, v24
	ds_write_b16 v155, v4 offset:53584
	v_cvt_pk_bf16_f32 v4, v10, v33
	ds_write_b16 v155, v4 offset:53856
	v_cvt_pk_bf16_f32 v54, v25, v33
	v_mov_b64_e32 v[4:5], v[210:211]
	v_mov_b64_e32 v[6:7], v[212:213]
	v_mov_b64_e32 v[8:9], v[214:215]
	v_mov_b64_e32 v[10:11], v[216:217]
	v_mov_b64_e32 v[14:15], v[218:219]
	v_mov_b64_e32 v[16:17], v[220:221]
	v_mov_b64_e32 v[18:19], v[238:239]
	v_mov_b64_e32 v[20:21], v[240:241]
	v_mov_b32_e32 v22, v0
	v_pk_add_f32 v[0:1], v[2:3], v[0:1]
	v_mul_f32_e32 v2, v61, v61
	v_mul_f32_e32 v24, v53, v53
	v_pk_fma_f32 v[2:3], v[60:61], v[60:61], v[2:3] op_sel_hi:[1,1,0]
	v_pk_fma_f32 v[24:25], v[52:53], v[52:53], v[24:25] op_sel_hi:[1,1,0]
	v_mov_b32_e32 v26, v2
	v_mov_b32_e32 v74, v24
	v_mov_b32_e32 v23, v85
	v_mov_b32_e32 v27, v75
	v_pk_add_f32 v[2:3], v[24:25], v[2:3]
	v_pk_fma_f32 v[24:25], v[68:69], v[70:71], v[86:87]
	v_pk_mul_f32 v[28:29], v[86:87], v[86:87]
	v_pk_fma_f32 v[30:31], v[62:63], v[72:73], v[88:89]
	v_pk_mul_f32 v[22:23], v[84:85], v[22:23]
	v_pk_mul_f32 v[26:27], v[74:75], v[26:27]
	v_mov_b32_e32 v25, v29
	v_mov_b32_e32 v31, v49
	v_mov_b32_e32 v1, v23
	v_mov_b32_e32 v3, v27
	v_pk_add_f32 v[22:23], v[24:25], v[30:31]
	v_pk_add_f32 v[0:1], v[0:1], v[2:3]
	v_sub_f32_e32 v2, v98, v12
	v_pk_add_f32 v[88:89], v[0:1], v[22:23]
	v_pk_mul_f32 v[0:1], v[92:93], v[92:93]
	ds_write_b16 v155, v54 offset:54128
	v_pk_fma_f32 v[0:1], v[90:91], v[90:91], v[0:1]
	v_sub_f32_e32 v3, v100, v12
	v_pk_add_f32 v[86:87], v[0:1], v[0:1] op_sel:[0,1] op_sel_hi:[1,0]
	v_mul_f32_e32 v0, v95, v95
	v_pk_fma_f32 v[84:85], v[94:95], v[94:95], v[0:1] op_sel_hi:[1,1,0]
	v_sub_f32_e32 v0, v56, v12
	v_mul_f32_e32 v0, v13, v0
	v_sub_f32_e32 v1, v96, v12
	v_mul_f32_e32 v1, v13, v1
	v_mul_f32_e32 v2, v13, v2
	v_sub_f32_e32 v22, v101, v12
	v_mul_f32_e32 v3, v13, v3
	v_sub_f32_e32 v23, v102, v12
	v_mul_f32_e32 v22, v13, v22
	v_sub_f32_e32 v24, v103, v12
	v_mul_f32_e32 v23, v13, v23
	v_sub_f32_e32 v12, v104, v12
	v_mul_f32_e32 v24, v13, v24
	v_mul_f32_e32 v12, v13, v12
	s_waitcnt vmcnt(2)
	v_fma_f32 v0, v0, v4, v8
	v_cvt_pk_bf16_f32 v0, v0, v33
	v_fma_f32 v1, v1, v5, v9
	ds_write_b16 v155, v0 offset:60928
	v_cvt_pk_bf16_f32 v0, v1, v33
	v_fma_f32 v2, v2, v6, v10
	ds_write_b16 v155, v0 offset:61200
	v_cvt_pk_bf16_f32 v0, v2, v33
	v_fmac_f32_e32 v11, v3, v7
	ds_write_b16 v155, v0 offset:61472
	v_cvt_pk_bf16_f32 v0, v11, v33
	s_waitcnt vmcnt(0)
	v_fma_f32 v3, v22, v14, v18
	ds_write_b16 v155, v0 offset:61744
	v_cvt_pk_bf16_f32 v0, v3, v33
	v_fma_f32 v4, v23, v15, v19
	ds_write_b16 v155, v0 offset:62016
	v_cvt_pk_bf16_f32 v0, v4, v33
	v_fma_f32 v5, v24, v16, v20
	ds_write_b16 v155, v0 offset:62288
	v_cvt_pk_bf16_f32 v0, v5, v33
	v_fmac_f32_e32 v21, v12, v17
	ds_write_b16 v155, v0 offset:62560
	v_cvt_pk_bf16_f32 v0, v21, v33
	ds_write_b16 v155, v0 offset:62832
	s_waitcnt lgkmcnt(0)
	s_barrier
	v_pk_fma_f32 v[66:67], v[66:67], v[76:77], v[80:81]
	s_nop 0
	v_mov_b64_e32 v[20:21], v[222:223]
	v_mov_b64_e32 v[22:23], v[224:225]
	v_mov_b64_e32 v[24:25], v[226:227]
	v_mov_b64_e32 v[26:27], v[228:229]
	v_mov_b64_e32 v[28:29], v[230:231]
	v_mov_b64_e32 v[30:31], v[232:233]
	v_mov_b64_e32 v[16:17], v[234:235]
	v_mov_b64_e32 v[18:19], v[236:237]
	global_load_dwordx2 v[224:225], v[40:41], off offset:1312
	global_load_dwordx2 v[226:227], v[40:41], off offset:1344
	global_load_dwordx2 v[228:229], v[40:41], off offset:1376
	global_load_dwordx2 v[230:231], v[40:41], off offset:1408
	global_load_dwordx2 v[232:233], v[40:41], off offset:1440
	global_load_dwordx2 v[234:235], v[40:41], off offset:1472
	global_load_dwordx2 v[236:237], v[40:41], off offset:1504
	global_load_dwordx2 v[72:73], v[40:41], off offset:1280
	global_load_dword v48, v[44:45], off offset:512
	ds_read_b128 v[0:3], v152 offset:34816
	ds_read_b128 v[4:7], v152 offset:34880
	ds_read_b128 v[50:53], v152 offset:34944
	global_load_dwordx4 v[12:15], v[46:47], off offset:2560
	global_load_dwordx4 v[8:11], v[46:47], off offset:2624
	ds_read_b128 v[60:63], v152 offset:35008
	v_pk_mul_f32 v[76:77], v[80:81], v[80:81]
	v_pk_fma_f32 v[64:65], v[64:65], v[78:79], v[82:83]
	v_pk_mul_f32 v[78:79], v[82:83], v[82:83]
	v_mov_b32_e32 v67, v77
	v_mov_b32_e32 v65, v79
	s_waitcnt vmcnt(3) lgkmcnt(3)
	v_mfma_f32_16x16x32_bf16 v[0:3], v[0:3], v[20:23], 0
	s_waitcnt vmcnt(1)
	v_lshlrev_b32_e32 v75, 16, v73
	v_lshlrev_b32_e32 v74, 16, v72
	s_waitcnt lgkmcnt(2)
	v_mfma_f32_16x16x32_bf16 v[68:71], v[4:7], v[24:27], v[0:3]
	global_load_dwordx4 v[4:7], v[46:47], off offset:2688
	s_nop 1
	global_load_dwordx4 v[0:3], v[46:47], off offset:2752
	s_waitcnt vmcnt(0)
	v_and_b32_e32 v76, 0xffff0000, v1
	s_waitcnt lgkmcnt(1)
	v_mfma_f32_16x16x32_bf16 v[50:53], v[50:53], v[28:31], v[68:71]
	v_lshlrev_b32_e32 v77, 16, v2
	v_and_b32_e32 v78, 0xffff0000, v2
	v_lshlrev_b32_e32 v79, 16, v3
	s_waitcnt lgkmcnt(0)
	v_mfma_f32_16x16x32_bf16 v[50:53], v[60:63], v[16:19], v[50:53]
	v_and_b32_e32 v69, 0xffff0000, v73
	v_and_b32_e32 v68, 0xffff0000, v72
	v_and_b32_e32 v80, 0xffff0000, v3
	s_nop 4
	v_mov_b32_e32 v60, v50
	v_mov_b32_e32 v61, v52
	v_mov_b32_e32 v52, v51
	v_pk_add_f32 v[50:51], v[48:49], v[60:61] op_sel_hi:[0,1]
	v_pk_add_f32 v[52:53], v[48:49], v[52:53] op_sel_hi:[0,1]
	v_pk_mul_f32 v[90:91], v[50:51], v[74:75]
	v_pk_mul_f32 v[92:93], v[52:53], v[68:69]
	s_nop 0
	v_cvt_pk_bf16_f32 v156, v90, v92
	v_cvt_pk_bf16_f32 v154, v91, v93
	ds_read_b128 v[50:53], v152 offset:39168
	ds_read_b128 v[60:63], v152 offset:39232
	s_waitcnt lgkmcnt(1)
	v_mfma_f32_16x16x32_bf16 v[50:53], v[50:53], v[20:23], 0
	s_waitcnt lgkmcnt(0)
	v_mfma_f32_16x16x32_bf16 v[50:53], v[60:63], v[24:27], v[50:53]
	ds_read_b128 v[60:63], v152 offset:39296
	ds_read_b128 v[68:71], v152 offset:39360
	s_waitcnt lgkmcnt(1)
	v_mfma_f32_16x16x32_bf16 v[50:53], v[60:63], v[28:31], v[50:53]
	v_mov_b64_e32 v[60:61], v[224:225]
	s_waitcnt vmcnt(0)
	v_lshlrev_b32_e32 v62, 16, v60
	s_waitcnt lgkmcnt(0)
	v_mfma_f32_16x16x32_bf16 v[50:53], v[68:71], v[16:19], v[50:53]
	v_and_b32_e32 v63, 0xffff0000, v60
	v_lshlrev_b32_e32 v60, 16, v61
	v_and_b32_e32 v61, 0xffff0000, v61
	s_nop 4
	v_pk_add_f32 v[50:51], v[48:49], v[50:51] op_sel_hi:[0,1]
	v_pk_add_f32 v[52:53], v[48:49], v[52:53] op_sel_hi:[0,1]
	v_pk_mul_f32 v[94:95], v[50:51], v[62:63]
	v_pk_mul_f32 v[96:97], v[52:53], v[60:61]
	v_cvt_pk_bf16_f32 v153, v94, v95
	s_nop 0
	v_cvt_pk_bf16_f32 v151, v96, v97
	ds_read_b128 v[50:53], v152 offset:43520
	ds_read_b128 v[60:63], v152 offset:43584
	s_waitcnt lgkmcnt(1)
	v_mfma_f32_16x16x32_bf16 v[50:53], v[50:53], v[20:23], 0
	s_waitcnt lgkmcnt(0)
	v_mfma_f32_16x16x32_bf16 v[50:53], v[60:63], v[24:27], v[50:53]
	ds_read_b128 v[60:63], v152 offset:43648
	ds_read_b128 v[68:71], v152 offset:43712
	s_waitcnt lgkmcnt(1)
	v_mfma_f32_16x16x32_bf16 v[50:53], v[60:63], v[28:31], v[50:53]
	v_mov_b64_e32 v[60:61], v[226:227]
	s_waitcnt vmcnt(0)
	v_and_b32_e32 v54, 0xffff0000, v60
	s_waitcnt lgkmcnt(0)
	v_mfma_f32_16x16x32_bf16 v[50:53], v[68:71], v[16:19], v[50:53]
	v_lshlrev_b32_e32 v56, 16, v61
	v_and_b32_e32 v61, 0xffff0000, v61
	s_nop 5
	v_add_f32_e32 v49, v48, v50
	v_add_f32_e32 v50, v48, v51
	v_add_f32_e32 v51, v48, v52
	v_add_f32_e32 v52, v48, v53
	v_lshlrev_b32_e32 v53, 16, v60
	v_mul_f32_e32 v60, v49, v53
	v_mul_f32_e32 v100, v50, v54
	v_mul_f32_e32 v62, v51, v56
	v_mul_f32_e32 v98, v52, v61
	v_cvt_pk_bf16_f32 v149, v60, v100
	v_cvt_pk_bf16_f32 v147, v62, v98
	ds_read_b128 v[50:53], v152 offset:47872
	ds_read_b128 v[68:71], v152 offset:47936
	s_waitcnt lgkmcnt(1)
	v_mfma_f32_16x16x32_bf16 v[50:53], v[50:53], v[20:23], 0
	v_mov_b32_e32 v102, v60
	v_mov_b32_e32 v104, v62
	s_waitcnt lgkmcnt(0)
	v_mfma_f32_16x16x32_bf16 v[50:53], v[68:71], v[24:27], v[50:53]
	ds_read_b128 v[68:71], v152 offset:48000
	ds_read_b128 v[72:75], v152 offset:48064
	s_waitcnt lgkmcnt(1)
	v_mfma_f32_16x16x32_bf16 v[50:53], v[68:71], v[28:31], v[50:53]
	v_mov_b64_e32 v[68:69], v[228:229]
	s_waitcnt vmcnt(0)
	v_lshlrev_b32_e32 v103, 16, v69
	s_waitcnt lgkmcnt(0)
	v_mfma_f32_16x16x32_bf16 v[50:53], v[72:75], v[16:19], v[50:53]
	v_and_b32_e32 v105, 0xffff0000, v69
	s_nop 6
	v_add_f32_e32 v49, v48, v50
	v_add_f32_e32 v50, v48, v51
	v_add_f32_e32 v61, v48, v52
	v_add_f32_e32 v63, v48, v53
	v_lshlrev_b32_e32 v51, 16, v68
	v_and_b32_e32 v52, 0xffff0000, v68
	v_mul_f32_e32 v109, v49, v51
	v_mul_f32_e32 v107, v50, v52
	v_pk_mul_f32 v[110:111], v[60:61], v[102:103]
	v_pk_mul_f32 v[112:113], v[62:63], v[104:105]
	v_cvt_pk_bf16_f32 v146, v109, v107
	v_mov_b32_e32 v101, v61
	v_cvt_pk_bf16_f32 v143, v111, v113
	ds_read_b128 v[50:53], v152 offset:52224
	ds_read_b128 v[68:71], v152 offset:52288
	s_waitcnt lgkmcnt(1)
	v_mfma_f32_16x16x32_bf16 v[50:53], v[50:53], v[20:23], 0
	v_mov_b32_e32 v99, v63
	v_mov_b32_e32 v102, v100
	v_mov_b32_e32 v104, v98
	s_waitcnt lgkmcnt(0)
	v_mfma_f32_16x16x32_bf16 v[50:53], v[68:71], v[24:27], v[50:53]
	ds_read_b128 v[68:71], v152 offset:52352
	ds_read_b128 v[72:75], v152 offset:52416
	v_mov_b32_e32 v3, v109
	s_waitcnt lgkmcnt(1)
	v_mfma_f32_16x16x32_bf16 v[50:53], v[68:71], v[28:31], v[50:53]
	v_mov_b64_e32 v[68:69], v[230:231]
	s_waitcnt lgkmcnt(0)
	v_mfma_f32_16x16x32_bf16 v[50:53], v[72:75], v[16:19], v[50:53]
	s_nop 7
	v_mov_b32_e32 v70, v50
	v_mov_b32_e32 v71, v52
	v_mov_b32_e32 v52, v51
	v_pk_add_f32 v[50:51], v[48:49], v[70:71] op_sel_hi:[0,1]
	v_pk_add_f32 v[52:53], v[48:49], v[52:53] op_sel_hi:[0,1]
	s_waitcnt vmcnt(0)
	v_lshlrev_b32_e32 v71, 16, v69
	v_lshlrev_b32_e32 v70, 16, v68
	v_and_b32_e32 v69, 0xffff0000, v69
	v_and_b32_e32 v68, 0xffff0000, v68
	v_pk_mul_f32 v[114:115], v[50:51], v[70:71]
	v_pk_mul_f32 v[116:117], v[52:53], v[68:69]
	s_nop 0
	v_cvt_pk_bf16_f32 v144, v114, v116
	v_cvt_pk_bf16_f32 v141, v115, v117
	ds_read_b128 v[50:53], v152 offset:56576
	ds_read_b128 v[68:71], v152 offset:56640
	s_waitcnt lgkmcnt(1)
	v_mfma_f32_16x16x32_bf16 v[50:53], v[50:53], v[20:23], 0
	s_waitcnt lgkmcnt(0)
	v_mfma_f32_16x16x32_bf16 v[50:53], v[68:71], v[24:27], v[50:53]
	ds_read_b128 v[68:71], v152 offset:56704
	ds_read_b128 v[72:75], v152 offset:56768
	s_waitcnt lgkmcnt(1)
	v_mfma_f32_16x16x32_bf16 v[50:53], v[68:71], v[28:31], v[50:53]
	v_mov_b64_e32 v[68:69], v[232:233]
	s_waitcnt lgkmcnt(0)
	v_mfma_f32_16x16x32_bf16 v[50:53], v[72:75], v[16:19], v[50:53]
	s_nop 7
	v_pk_add_f32 v[50:51], v[48:49], v[50:51] op_sel_hi:[0,1]
	v_pk_add_f32 v[70:71], v[48:49], v[52:53] op_sel_hi:[0,1]
	s_waitcnt vmcnt(0)
	v_lshlrev_b32_e32 v52, 16, v68
	v_and_b32_e32 v53, 0xffff0000, v68
	v_lshlrev_b32_e32 v68, 16, v69
	v_and_b32_e32 v69, 0xffff0000, v69
	v_pk_mul_f32 v[52:53], v[50:51], v[52:53]
	v_pk_mul_f32 v[118:119], v[70:71], v[68:69]
	v_cvt_pk_bf16_f32 v140, v52, v53
	s_nop 0
	v_cvt_pk_bf16_f32 v138, v118, v119
	ds_read_b128 v[68:71], v152 offset:60928
	ds_read_b128 v[72:75], v152 offset:60992
	s_waitcnt lgkmcnt(1)
	v_mfma_f32_16x16x32_bf16 v[68:71], v[68:71], v[20:23], 0
	s_waitcnt lgkmcnt(0)
	v_mfma_f32_16x16x32_bf16 v[68:71], v[72:75], v[24:27], v[68:71]
	ds_read_b128 v[72:75], v152 offset:61056
	ds_read_b128 v[120:123], v152 offset:61120
	v_mov_b64_e32 v[50:51], v[234:235]
	s_waitcnt vmcnt(0)
	v_lshlrev_b32_e32 v62, 16, v50
	s_waitcnt lgkmcnt(1)
	v_mfma_f32_16x16x32_bf16 v[68:71], v[72:75], v[28:31], v[68:71]
	v_and_b32_e32 v50, 0xffff0000, v50
	s_waitcnt lgkmcnt(0)
	v_mfma_f32_16x16x32_bf16 v[68:71], v[120:123], v[16:19], v[68:71]
	s_nop 7
	v_add_f32_e32 v49, v48, v68
	v_add_f32_e32 v54, v48, v69
	v_add_f32_e32 v56, v48, v70
	v_add_f32_e32 v60, v48, v71
	v_lshlrev_b32_e32 v68, 16, v51
	v_and_b32_e32 v51, 0xffff0000, v51
	v_mul_f32_e32 v120, v49, v62
	v_mul_f32_e32 v62, v54, v50
	v_mul_f32_e32 v122, v56, v68
	v_mul_f32_e32 v60, v60, v51
	v_cvt_pk_bf16_f32 v135, v120, v62
	v_cvt_pk_bf16_f32 v131, v122, v60
	ds_read_b128 v[68:71], v152 offset:65280
	ds_read_b128 v[72:75], v152 offset:65344
	s_waitcnt lgkmcnt(1)
	v_mfma_f32_16x16x32_bf16 v[20:23], v[68:71], v[20:23], 0
	v_mov_b32_e32 v68, v120
	v_mov_b32_e32 v70, v122
	v_and_b32_e32 v50, 0xffff0000, v12
	s_waitcnt lgkmcnt(0)
	v_mfma_f32_16x16x32_bf16 v[20:23], v[72:75], v[24:27], v[20:23]
	ds_read_b128 v[24:27], v152 offset:65408
	ds_read_b128 v[72:75], v152 offset:65472
	v_lshlrev_b32_e32 v54, 16, v13
	v_and_b32_e32 v56, 0xffff0000, v13
	s_waitcnt lgkmcnt(1)
	v_mfma_f32_16x16x32_bf16 v[20:23], v[24:27], v[28:31], v[20:23]
	v_mov_b64_e32 v[24:25], v[236:237]
	s_waitcnt vmcnt(0)
	v_lshlrev_b32_e32 v69, 16, v25
	s_waitcnt lgkmcnt(0)
	v_mfma_f32_16x16x32_bf16 v[16:19], v[72:75], v[16:19], v[20:23]
	v_and_b32_e32 v71, 0xffff0000, v25
	s_nop 6
	v_add_f32_e32 v16, v48, v16
	v_add_f32_e32 v17, v48, v17
	v_add_f32_e32 v121, v48, v18
	v_add_f32_e32 v123, v48, v19
	v_lshlrev_b32_e32 v18, 16, v24
	v_and_b32_e32 v19, 0xffff0000, v24
	v_mul_f32_e32 v51, v16, v18
	v_mul_f32_e32 v49, v17, v19
	v_pk_mul_f32 v[72:73], v[120:121], v[68:69]
	v_pk_mul_f32 v[74:75], v[122:123], v[70:71]
	v_cvt_pk_bf16_f32 v122, v51, v49
	v_lshlrev_b32_e32 v48, 16, v12
	v_cvt_pk_bf16_f32 v120, v73, v75
	v_add_co_u32_e32 v242, vcc, s27, v42
	s_nop 1
	v_addc_co_u32_e32 v243, vcc, 0, v43, vcc
	global_load_dwordx4 v[222:225], v[242:243], off
	global_load_dwordx4 v[226:229], v[242:243], off offset:64
	global_load_dwordx4 v[230:233], v[242:243], off offset:128
	global_load_dwordx4 v[234:237], v[242:243], off offset:192
	global_load_dwordx4 v[16:19], v157, s[48:49] offset:1024
	global_load_dwordx4 v[20:23], v157, s[50:51] offset:1024
	global_load_dwordx4 v[24:27], v157, s[48:49] offset:1040
	global_load_dwordx4 v[28:31], v157, s[50:51] offset:1040
	global_load_dwordx4 v[178:181], v157, s[48:49] offset:1152
	global_load_dwordx4 v[182:185], v157, s[50:51] offset:1152
	global_load_dwordx4 v[186:189], v157, s[48:49] offset:1168
	global_load_dwordx4 v[190:193], v157, s[50:51] offset:1168
	global_load_dwordx4 v[194:197], v157, s[48:49] offset:1280
	global_load_dwordx4 v[198:201], v157, s[50:51] offset:1280
	global_load_dwordx4 v[202:205], v157, s[48:49] offset:1296
	global_load_dwordx4 v[206:209], v157, s[50:51] offset:1296
	global_load_dwordx4 v[210:213], v157, s[48:49] offset:1408
	global_load_dwordx4 v[214:217], v157, s[50:51] offset:1408
	global_load_dwordx4 v[218:221], v157, s[48:49] offset:1424
	global_load_dwordx4 v[238:241], v157, s[50:51] offset:1424
	ds_read_b64 v[12:13], v160
	v_lshlrev_b32_e32 v70, 16, v15
	v_and_b32_e32 v15, 0xffff0000, v15
	v_lshlrev_b32_e32 v68, 16, v14
	v_and_b32_e32 v14, 0xffff0000, v14
	s_waitcnt lgkmcnt(0)
	v_sub_f32_e32 v48, v48, v12
	v_sub_f32_e32 v15, v15, v12
	v_sub_f32_e32 v50, v50, v12
	v_mul_f32_e32 v48, v13, v48
	v_mul_f32_e32 v15, v13, v15
	v_sub_f32_e32 v54, v54, v12
	v_mul_f32_e32 v50, v13, v50
	v_sub_f32_e32 v56, v56, v12
	v_sub_f32_e32 v14, v14, v12
	v_mul_f32_e32 v54, v13, v54
	v_sub_f32_e32 v68, v68, v12
	v_mul_f32_e32 v56, v13, v56
	v_mul_f32_e32 v14, v13, v14
	v_sub_f32_e32 v70, v70, v12
	v_mul_f32_e32 v68, v13, v68
	v_mul_f32_e32 v70, v13, v70
	v_mov_b32_e32 v63, v121
	v_mov_b32_e32 v61, v123
	s_waitcnt vmcnt(2)
	v_fma_f32 v16, v16, v48, v20
	v_fma_f32 v17, v17, v50, v21
	s_waitcnt vmcnt(0)
	v_fmac_f32_e32 v31, v27, v15
	v_cvt_pk_bf16_f32 v15, v16, v33
	ds_write_b16 v155, v15
	v_cvt_pk_bf16_f32 v15, v17, v33
	v_fma_f32 v18, v18, v54, v22
	ds_write_b16 v155, v15 offset:272
	v_cvt_pk_bf16_f32 v15, v18, v33
	v_fmac_f32_e32 v23, v19, v56
	v_fma_f32 v14, v25, v14, v29
	ds_write_b16 v155, v15 offset:544
	v_cvt_pk_bf16_f32 v15, v23, v33
	v_fma_f32 v19, v24, v68, v28
	ds_write_b16 v155, v15 offset:816
	v_cvt_pk_bf16_f32 v15, v19, v33
	ds_write_b16 v155, v15 offset:1088
	v_cvt_pk_bf16_f32 v14, v14, v33
	v_fma_f32 v20, v26, v70, v30
	ds_write_b16 v155, v14 offset:1360
	v_cvt_pk_bf16_f32 v14, v20, v33
	ds_write_b16 v155, v14 offset:1632
	v_cvt_pk_bf16_f32 v30, v31, v33
	v_mov_b64_e32 v[14:15], v[178:179]
	v_mov_b64_e32 v[16:17], v[180:181]
	v_mov_b64_e32 v[18:19], v[182:183]
	v_mov_b64_e32 v[20:21], v[184:185]
	v_mov_b64_e32 v[22:23], v[186:187]
	v_mov_b64_e32 v[24:25], v[188:189]
	v_mov_b64_e32 v[26:27], v[190:191]
	v_mov_b64_e32 v[28:29], v[192:193]
	v_lshlrev_b32_e32 v31, 16, v8
	v_and_b32_e32 v8, 0xffff0000, v8
	v_lshlrev_b32_e32 v54, 16, v11
	v_and_b32_e32 v11, 0xffff0000, v11
	v_sub_f32_e32 v8, v8, v12
	v_lshlrev_b32_e32 v48, 16, v9
	v_sub_f32_e32 v31, v31, v12
	v_sub_f32_e32 v11, v11, v12
	v_mul_f32_e32 v8, v13, v8
	v_and_b32_e32 v9, 0xffff0000, v9
	v_sub_f32_e32 v48, v48, v12
	v_mul_f32_e32 v31, v13, v31
	v_mul_f32_e32 v11, v13, v11
	v_lshlrev_b32_e32 v50, 16, v10
	v_sub_f32_e32 v9, v9, v12
	v_mul_f32_e32 v48, v13, v48
	ds_write_b16 v155, v30 offset:1904
	v_and_b32_e32 v10, 0xffff0000, v10
	v_sub_f32_e32 v50, v50, v12
	v_mul_f32_e32 v9, v13, v9
	v_sub_f32_e32 v10, v10, v12
	v_mul_f32_e32 v50, v13, v50
	v_sub_f32_e32 v54, v54, v12
	v_mul_f32_e32 v10, v13, v10
	v_mul_f32_e32 v54, v13, v54
	v_mul_f32_e32 v30, v59, v59
	v_mov_b32_e32 v68, v62
	v_mov_b32_e32 v70, v60
	s_waitcnt vmcnt(2)
	v_fma_f32 v8, v8, v15, v19
	v_fma_f32 v14, v31, v14, v18
	s_waitcnt vmcnt(0)
	v_fmac_f32_e32 v29, v11, v25
	v_cvt_pk_bf16_f32 v11, v14, v33
	ds_write_b16 v155, v11 offset:8704
	v_cvt_pk_bf16_f32 v8, v8, v33
	v_fma_f32 v15, v48, v16, v20
	ds_write_b16 v155, v8 offset:8976
	v_cvt_pk_bf16_f32 v8, v15, v33
	v_fmac_f32_e32 v21, v9, v17
	ds_write_b16 v155, v8 offset:9248
	v_cvt_pk_bf16_f32 v8, v21, v33
	v_fma_f32 v9, v50, v22, v26
	ds_write_b16 v155, v8 offset:9520
	v_cvt_pk_bf16_f32 v8, v9, v33
	v_fma_f32 v10, v10, v23, v27
	ds_write_b16 v155, v8 offset:9792
	v_cvt_pk_bf16_f32 v8, v10, v33
	v_fma_f32 v16, v54, v24, v28
	ds_write_b16 v155, v8 offset:10064
	v_cvt_pk_bf16_f32 v8, v16, v33
	ds_write_b16 v155, v8 offset:10336
	v_cvt_pk_bf16_f32 v48, v29, v33
	v_mov_b64_e32 v[8:9], v[194:195]
	v_mov_b64_e32 v[10:11], v[196:197]
	v_mov_b64_e32 v[14:15], v[198:199]
	v_mov_b64_e32 v[16:17], v[200:201]
	v_mov_b64_e32 v[18:19], v[202:203]
	v_mov_b64_e32 v[20:21], v[204:205]
	v_mov_b64_e32 v[22:23], v[206:207]
	v_mov_b64_e32 v[24:25], v[208:209]
	v_pk_add_f32 v[26:27], v[88:89], v[88:89] op_sel:[0,1] op_sel_hi:[1,0]
	v_pk_fma_f32 v[30:31], v[58:59], v[58:59], v[30:31] op_sel_hi:[1,1,0]
	v_mov_b32_e32 v56, v26
	v_pk_add_f32 v[26:27], v[26:27], v[86:87]
	v_lshlrev_b32_e32 v58, 16, v7
	v_lshlrev_b32_e32 v27, 16, v4
	v_and_b32_e32 v4, 0xffff0000, v4
	v_and_b32_e32 v7, 0xffff0000, v7
	v_sub_f32_e32 v4, v4, v12
	v_lshlrev_b32_e32 v50, 16, v5
	v_sub_f32_e32 v27, v27, v12
	v_sub_f32_e32 v7, v7, v12
	v_mul_f32_e32 v4, v13, v4
	v_and_b32_e32 v5, 0xffff0000, v5
	v_sub_f32_e32 v50, v50, v12
	v_mul_f32_e32 v27, v13, v27
	v_mul_f32_e32 v7, v13, v7
	v_lshlrev_b32_e32 v54, 16, v6
	v_sub_f32_e32 v5, v5, v12
	v_mul_f32_e32 v50, v13, v50
	ds_write_b16 v155, v48 offset:10608
	v_and_b32_e32 v6, 0xffff0000, v6
	v_sub_f32_e32 v54, v54, v12
	v_mul_f32_e32 v5, v13, v5
	v_sub_f32_e32 v6, v6, v12
	v_mul_f32_e32 v54, v13, v54
	v_sub_f32_e32 v58, v58, v12
	v_mul_f32_e32 v6, v13, v6
	v_mul_f32_e32 v58, v13, v58
	v_mov_b32_e32 v28, v86
	v_mov_b32_e32 v29, v57
	v_mov_b32_e32 v88, v84
	v_mov_b32_e32 v89, v55
	s_waitcnt vmcnt(2)
	v_fma_f32 v4, v4, v9, v15
	v_fma_f32 v8, v27, v8, v14
	s_waitcnt vmcnt(0)
	v_fmac_f32_e32 v25, v7, v21
	v_cvt_pk_bf16_f32 v7, v8, v33
	ds_write_b16 v155, v7 offset:17408
	v_cvt_pk_bf16_f32 v4, v4, v33
	v_fma_f32 v9, v50, v10, v16
	ds_write_b16 v155, v4 offset:17680
	v_cvt_pk_bf16_f32 v4, v9, v33
	v_fmac_f32_e32 v17, v5, v11
	ds_write_b16 v155, v4 offset:17952
	v_cvt_pk_bf16_f32 v4, v17, v33
	v_fma_f32 v5, v54, v18, v22
	ds_write_b16 v155, v4 offset:18224
	v_cvt_pk_bf16_f32 v4, v5, v33
	v_fma_f32 v6, v6, v19, v23
	ds_write_b16 v155, v4 offset:18496
	v_cvt_pk_bf16_f32 v4, v6, v33
	v_fma_f32 v10, v58, v20, v24
	ds_write_b16 v155, v4 offset:18768
	v_cvt_pk_bf16_f32 v4, v10, v33
	ds_write_b16 v155, v4 offset:19040
	v_cvt_pk_bf16_f32 v48, v25, v33
	v_mov_b64_e32 v[4:5], v[210:211]
	v_mov_b64_e32 v[6:7], v[212:213]
	v_mov_b64_e32 v[8:9], v[214:215]
	v_mov_b64_e32 v[10:11], v[216:217]
	v_mov_b64_e32 v[14:15], v[218:219]
	v_mov_b64_e32 v[16:17], v[220:221]
	v_mov_b64_e32 v[18:19], v[238:239]
	v_mov_b64_e32 v[20:21], v[240:241]
	v_pk_mul_f32 v[22:23], v[56:57], v[28:29]
	v_mov_b32_e32 v54, v30
	v_pk_add_f32 v[24:25], v[30:31], v[84:85]
	v_mov_b32_e32 v27, v23
	v_pk_mul_f32 v[22:23], v[54:55], v[88:89]
	v_pk_add_f32 v[28:29], v[66:67], v[64:65]
	v_mov_b32_e32 v25, v23
	v_pk_add_f32 v[22:23], v[26:27], v[24:25]
	v_lshlrev_b32_e32 v50, 16, v0
	v_and_b32_e32 v56, 0xffff0000, v0
	v_lshlrev_b32_e32 v57, 16, v1
	v_pk_mul_f32 v[0:1], v[92:93], v[92:93]
	v_pk_add_f32 v[22:23], v[22:23], v[28:29]
	v_pk_fma_f32 v[0:1], v[90:91], v[90:91], v[0:1]
	v_pk_add_f32 v[22:23], v[22:23], v[22:23] op_sel:[0,1] op_sel_hi:[1,0]
	v_pk_add_f32 v[0:1], v[0:1], v[0:1] op_sel:[0,1] op_sel_hi:[1,0]
	v_mov_b32_e32 v108, v22
	v_mov_b32_e32 v2, v0
	v_pk_add_f32 v[0:1], v[22:23], v[0:1]
	v_mul_f32_e32 v22, v97, v97
	v_mul_f32_e32 v24, v95, v95
	v_pk_fma_f32 v[22:23], v[96:97], v[96:97], v[22:23] op_sel_hi:[1,1,0]
	v_pk_fma_f32 v[24:25], v[94:95], v[94:95], v[24:25] op_sel_hi:[1,1,0]
	v_mov_b32_e32 v26, v22
	v_mov_b32_e32 v106, v24
	v_mov_b32_e32 v27, v107
	v_pk_add_f32 v[22:23], v[24:25], v[22:23]
	v_pk_fma_f32 v[24:25], v[100:101], v[102:103], v[110:111]
	v_pk_mul_f32 v[28:29], v[110:111], v[110:111]
	v_pk_fma_f32 v[30:31], v[98:99], v[104:105], v[112:113]
	v_pk_mul_f32 v[54:55], v[112:113], v[112:113]
	v_pk_mul_f32 v[2:3], v[108:109], v[2:3]
	v_pk_mul_f32 v[26:27], v[106:107], v[26:27]
	v_mov_b32_e32 v25, v29
	v_mov_b32_e32 v31, v55
	v_mov_b32_e32 v1, v3
	v_mov_b32_e32 v23, v27
	v_pk_add_f32 v[2:3], v[24:25], v[30:31]
	v_pk_add_f32 v[0:1], v[0:1], v[22:23]
	ds_write_b16 v155, v48 offset:19312
	v_pk_add_f32 v[66:67], v[0:1], v[2:3]
	v_pk_mul_f32 v[0:1], v[116:117], v[116:117]
	v_sub_f32_e32 v2, v57, v12
	v_pk_fma_f32 v[0:1], v[114:115], v[114:115], v[0:1]
	v_sub_f32_e32 v3, v76, v12
	v_pk_add_f32 v[64:65], v[0:1], v[0:1] op_sel:[0,1] op_sel_hi:[1,0]
	v_mul_f32_e32 v0, v119, v119
	v_pk_fma_f32 v[58:59], v[118:119], v[118:119], v[0:1] op_sel_hi:[1,1,0]
	v_sub_f32_e32 v0, v50, v12
	v_mul_f32_e32 v0, v13, v0
	v_sub_f32_e32 v1, v56, v12
	v_mul_f32_e32 v1, v13, v1
	v_mul_f32_e32 v2, v13, v2
	v_sub_f32_e32 v22, v77, v12
	v_mul_f32_e32 v3, v13, v3
	v_sub_f32_e32 v23, v78, v12
	v_mul_f32_e32 v22, v13, v22
	v_sub_f32_e32 v24, v79, v12
	v_mul_f32_e32 v23, v13, v23
	v_sub_f32_e32 v12, v80, v12
	v_mul_f32_e32 v24, v13, v24
	v_mul_f32_e32 v12, v13, v12
	s_waitcnt vmcnt(2)
	v_fma_f32 v0, v0, v4, v8
	v_cvt_pk_bf16_f32 v0, v0, v33
	v_fma_f32 v1, v1, v5, v9
	ds_write_b16 v155, v0 offset:26112
	v_cvt_pk_bf16_f32 v0, v1, v33
	v_fma_f32 v2, v2, v6, v10
	ds_write_b16 v155, v0 offset:26384
	v_cvt_pk_bf16_f32 v0, v2, v33
	v_fmac_f32_e32 v11, v3, v7
	ds_write_b16 v155, v0 offset:26656
	v_cvt_pk_bf16_f32 v0, v11, v33
	s_waitcnt vmcnt(0)
	v_fma_f32 v3, v22, v14, v18
	ds_write_b16 v155, v0 offset:26928
	v_cvt_pk_bf16_f32 v0, v3, v33
	v_fma_f32 v4, v23, v15, v19
	ds_write_b16 v155, v0 offset:27200
	v_cvt_pk_bf16_f32 v0, v4, v33
	v_fma_f32 v5, v24, v16, v20
	ds_write_b16 v155, v0 offset:27472
	v_cvt_pk_bf16_f32 v0, v5, v33
	v_fmac_f32_e32 v21, v12, v17
	ds_write_b16 v155, v0 offset:27744
	v_cvt_pk_bf16_f32 v0, v21, v33
	ds_write_b16 v155, v0 offset:28016
	s_waitcnt lgkmcnt(0)
	s_barrier
	v_pk_fma_f32 v[68:69], v[62:63], v[68:69], v[72:73]
	s_nop 0
	v_mov_b64_e32 v[20:21], v[222:223]
	v_mov_b64_e32 v[22:23], v[224:225]
	v_mov_b64_e32 v[24:25], v[226:227]
	v_mov_b64_e32 v[26:27], v[228:229]
	v_mov_b64_e32 v[28:29], v[230:231]
	v_mov_b64_e32 v[30:31], v[232:233]
	v_mov_b64_e32 v[16:17], v[234:235]
	v_mov_b64_e32 v[18:19], v[236:237]
	global_load_dwordx2 v[224:225], v[40:41], off offset:1568
	global_load_dwordx2 v[226:227], v[40:41], off offset:1600
	global_load_dwordx2 v[228:229], v[40:41], off offset:1632
	global_load_dwordx2 v[230:231], v[40:41], off offset:1664
	global_load_dwordx2 v[232:233], v[40:41], off offset:1696
	global_load_dwordx2 v[234:235], v[40:41], off offset:1728
	global_load_dwordx2 v[236:237], v[40:41], off offset:1760
	global_load_dwordx2 v[84:85], v[40:41], off offset:1536
	global_load_dword v48, v[44:45], off offset:1024
	ds_read_b128 v[0:3], v152
	ds_read_b128 v[4:7], v152 offset:64
	ds_read_b128 v[54:57], v152 offset:128
	global_load_dwordx4 v[12:15], v[46:47], off offset:2816
	global_load_dwordx4 v[8:11], v[46:47], off offset:2880
	ds_read_b128 v[76:79], v152 offset:192
	v_pk_mul_f32 v[62:63], v[72:73], v[72:73]
	v_pk_fma_f32 v[70:71], v[60:61], v[70:71], v[74:75]
	v_pk_mul_f32 v[60:61], v[74:75], v[74:75]
	v_mov_b32_e32 v69, v63
	v_mov_b32_e32 v71, v61
	s_waitcnt vmcnt(3) lgkmcnt(3)
	v_mfma_f32_16x16x32_bf16 v[0:3], v[0:3], v[20:23], 0
	s_waitcnt vmcnt(2) lgkmcnt(2)
	v_mfma_f32_16x16x32_bf16 v[80:83], v[4:7], v[24:27], v[0:3]
	global_load_dwordx4 v[4:7], v[46:47], off offset:2944
	s_nop 4
	global_load_dwordx4 v[0:3], v[46:47], off offset:3008
	s_waitcnt vmcnt(3)
	v_lshlrev_b32_e32 v47, 16, v85
	v_lshlrev_b32_e32 v46, 16, v84
	s_waitcnt vmcnt(2) lgkmcnt(1)
	v_mfma_f32_16x16x32_bf16 v[54:57], v[54:57], v[28:31], v[80:83]
	s_waitcnt vmcnt(0)
	v_and_b32_e32 v72, 0xffff0000, v2
	s_waitcnt lgkmcnt(0)
	v_mfma_f32_16x16x32_bf16 v[54:57], v[76:79], v[16:19], v[54:57]
	v_and_b32_e32 v81, 0xffff0000, v85
	v_and_b32_e32 v80, 0xffff0000, v84
	v_lshlrev_b32_e32 v73, 16, v3
	v_and_b32_e32 v74, 0xffff0000, v3
	s_nop 3
	v_mov_b32_e32 v76, v54
	v_mov_b32_e32 v77, v56
	v_mov_b32_e32 v56, v55
	v_pk_add_f32 v[54:55], v[48:49], v[76:77] op_sel_hi:[0,1]
	v_pk_add_f32 v[56:57], v[48:49], v[56:57] op_sel_hi:[0,1]
	v_pk_mul_f32 v[76:77], v[54:55], v[46:47]
	v_pk_mul_f32 v[78:79], v[56:57], v[80:81]
	s_nop 0
	v_cvt_pk_bf16_f32 v159, v76, v78
	v_cvt_pk_bf16_f32 v158, v77, v79
	ds_read_b128 v[54:57], v152 offset:4352
	ds_read_b128 v[80:83], v152 offset:4416
	s_waitcnt lgkmcnt(1)
	v_mfma_f32_16x16x32_bf16 v[54:57], v[54:57], v[20:23], 0
	s_waitcnt lgkmcnt(0)
	v_mfma_f32_16x16x32_bf16 v[54:57], v[80:83], v[24:27], v[54:57]
	ds_read_b128 v[80:83], v152 offset:4480
	ds_read_b128 v[84:87], v152 offset:4544
	v_mov_b64_e32 v[46:47], v[224:225]
	s_waitcnt lgkmcnt(1)
	v_mfma_f32_16x16x32_bf16 v[54:57], v[80:83], v[28:31], v[54:57]
	s_waitcnt vmcnt(0)
	v_lshlrev_b32_e32 v80, 16, v46
	s_waitcnt lgkmcnt(0)
	v_mfma_f32_16x16x32_bf16 v[54:57], v[84:87], v[16:19], v[54:57]
	v_and_b32_e32 v81, 0xffff0000, v46
	v_lshlrev_b32_e32 v46, 16, v47
	v_and_b32_e32 v47, 0xffff0000, v47
	s_nop 4
	v_pk_add_f32 v[54:55], v[48:49], v[54:55] op_sel_hi:[0,1]
	v_pk_add_f32 v[56:57], v[48:49], v[56:57] op_sel_hi:[0,1]
	v_pk_mul_f32 v[80:81], v[54:55], v[80:81]
	v_pk_mul_f32 v[82:83], v[56:57], v[46:47]
	v_cvt_pk_bf16_f32 v123, v80, v81
	s_nop 0
	v_cvt_pk_bf16_f32 v121, v82, v83
	ds_read_b128 v[54:57], v152 offset:8704
	ds_read_b128 v[84:87], v152 offset:8768
	s_waitcnt lgkmcnt(1)
	v_mfma_f32_16x16x32_bf16 v[54:57], v[54:57], v[20:23], 0
	s_waitcnt lgkmcnt(0)
	v_mfma_f32_16x16x32_bf16 v[54:57], v[84:87], v[24:27], v[54:57]
	ds_read_b128 v[84:87], v152 offset:8832
	ds_read_b128 v[88:91], v152 offset:8896
	v_mov_b64_e32 v[46:47], v[226:227]
	s_waitcnt lgkmcnt(1)
	v_mfma_f32_16x16x32_bf16 v[54:57], v[84:87], v[28:31], v[54:57]
	s_waitcnt vmcnt(0)
	v_lshlrev_b32_e32 v84, 16, v47
	s_waitcnt lgkmcnt(0)
	v_mfma_f32_16x16x32_bf16 v[54:57], v[88:91], v[16:19], v[54:57]
	v_and_b32_e32 v47, 0xffff0000, v47
	s_nop 6
	v_add_f32_e32 v50, v48, v54
	v_add_f32_e32 v55, v48, v55
	v_add_f32_e32 v56, v48, v56
	v_add_f32_e32 v57, v48, v57
	v_lshlrev_b32_e32 v54, 16, v46
	v_and_b32_e32 v46, 0xffff0000, v46
	v_mul_f32_e32 v54, v50, v54
	v_mul_f32_e32 v86, v55, v46
	v_mul_f32_e32 v56, v56, v84
	v_mul_f32_e32 v84, v57, v47
	v_cvt_pk_bf16_f32 v119, v54, v86
	v_cvt_pk_bf16_f32 v118, v56, v84
	ds_read_b128 v[88:91], v152 offset:13056
	ds_read_b128 v[92:95], v152 offset:13120
	s_waitcnt lgkmcnt(1)
	v_mfma_f32_16x16x32_bf16 v[88:91], v[88:91], v[20:23], 0
	s_waitcnt lgkmcnt(0)
	v_mfma_f32_16x16x32_bf16 v[88:91], v[92:95], v[24:27], v[88:91]
	ds_read_b128 v[92:95], v152 offset:13184
	ds_read_b128 v[96:99], v152 offset:13248
	v_mov_b64_e32 v[46:47], v[228:229]
	s_waitcnt vmcnt(0)
	v_lshlrev_b32_e32 v87, 16, v46
	s_waitcnt lgkmcnt(1)
	v_mfma_f32_16x16x32_bf16 v[92:95], v[92:95], v[28:31], v[88:91]
	v_and_b32_e32 v46, 0xffff0000, v46
	s_waitcnt lgkmcnt(0)
	v_mfma_f32_16x16x32_bf16 v[92:95], v[96:99], v[16:19], v[92:95]
	v_mov_b32_e32 v88, v54
	v_mov_b32_e32 v90, v56
	v_lshlrev_b32_e32 v89, 16, v47
	v_and_b32_e32 v91, 0xffff0000, v47
	s_nop 3
	v_add_f32_e32 v50, v48, v92
	v_add_f32_e32 v85, v48, v93
	v_add_f32_e32 v55, v48, v94
	v_add_f32_e32 v57, v48, v95
	v_mul_f32_e32 v95, v50, v87
	v_mul_f32_e32 v93, v85, v46
	v_pk_mul_f32 v[96:97], v[54:55], v[88:89]
	v_pk_mul_f32 v[98:99], v[56:57], v[90:91]
	v_cvt_pk_bf16_f32 v117, v95, v93
	v_mov_b32_e32 v3, v95
	v_cvt_pk_bf16_f32 v115, v97, v99
	ds_read_b128 v[100:103], v152 offset:17408
	ds_read_b128 v[104:107], v152 offset:17472
	s_waitcnt lgkmcnt(1)
	v_mfma_f32_16x16x32_bf16 v[100:103], v[100:103], v[20:23], 0
	s_waitcnt lgkmcnt(0)
	v_mfma_f32_16x16x32_bf16 v[100:103], v[104:107], v[24:27], v[100:103]
	ds_read_b128 v[104:107], v152 offset:17536
	ds_read_b128 v[108:111], v152 offset:17600
	v_mov_b64_e32 v[46:47], v[230:231]
	s_waitcnt lgkmcnt(1)
	v_mfma_f32_16x16x32_bf16 v[100:103], v[104:107], v[28:31], v[100:103]
	s_waitcnt lgkmcnt(0)
	v_mfma_f32_16x16x32_bf16 v[100:103], v[108:111], v[16:19], v[100:103]
	s_nop 7
	v_mov_b32_e32 v104, v100
	v_mov_b32_e32 v105, v102
	v_mov_b32_e32 v102, v101
	v_pk_add_f32 v[100:101], v[48:49], v[104:105] op_sel_hi:[0,1]
	v_pk_add_f32 v[102:103], v[48:49], v[102:103] op_sel_hi:[0,1]
	s_waitcnt vmcnt(0)
	v_lshlrev_b32_e32 v105, 16, v47
	v_lshlrev_b32_e32 v104, 16, v46
	v_and_b32_e32 v47, 0xffff0000, v47
	v_and_b32_e32 v46, 0xffff0000, v46
	v_pk_mul_f32 v[100:101], v[100:101], v[104:105]
	v_pk_mul_f32 v[102:103], v[102:103], v[46:47]
	s_nop 0
	v_cvt_pk_bf16_f32 v116, v100, v102
	v_cvt_pk_bf16_f32 v114, v101, v103
	ds_read_b128 v[104:107], v152 offset:21760
	ds_read_b128 v[108:111], v152 offset:21824
	s_waitcnt lgkmcnt(1)
	v_mfma_f32_16x16x32_bf16 v[104:107], v[104:107], v[20:23], 0
	s_waitcnt lgkmcnt(0)
	v_mfma_f32_16x16x32_bf16 v[104:107], v[108:111], v[24:27], v[104:107]
	ds_read_b128 v[108:111], v152 offset:21888
	ds_read_b128 v[162:165], v152 offset:21952
	v_mov_b64_e32 v[46:47], v[232:233]
	s_waitcnt lgkmcnt(1)
	v_mfma_f32_16x16x32_bf16 v[104:107], v[108:111], v[28:31], v[104:107]
	s_waitcnt vmcnt(0)
	v_lshlrev_b32_e32 v108, 16, v46
	s_waitcnt lgkmcnt(0)
	v_mfma_f32_16x16x32_bf16 v[104:107], v[162:165], v[16:19], v[104:107]
	v_and_b32_e32 v109, 0xffff0000, v46
	v_lshlrev_b32_e32 v110, 16, v47
	v_and_b32_e32 v111, 0xffff0000, v47
	s_nop 4
	v_pk_add_f32 v[104:105], v[48:49], v[104:105] op_sel_hi:[0,1]
	v_pk_add_f32 v[106:107], v[48:49], v[106:107] op_sel_hi:[0,1]
	v_pk_mul_f32 v[46:47], v[104:105], v[108:109]
	v_pk_mul_f32 v[104:105], v[106:107], v[110:111]
	v_cvt_pk_bf16_f32 v113, v46, v47
	s_nop 0
	v_cvt_pk_bf16_f32 v112, v104, v105
	ds_read_b128 v[106:109], v152 offset:26112
	ds_read_b128 v[162:165], v152 offset:26176
	s_waitcnt lgkmcnt(1)
	v_mfma_f32_16x16x32_bf16 v[106:109], v[106:109], v[20:23], 0
	s_waitcnt lgkmcnt(0)
	v_mfma_f32_16x16x32_bf16 v[106:109], v[162:165], v[24:27], v[106:109]
	ds_read_b128 v[162:165], v152 offset:26240
	ds_read_b128 v[166:169], v152 offset:26304
	v_mov_b64_e32 v[110:111], v[234:235]
	s_waitcnt vmcnt(0)
	v_lshlrev_b32_e32 v56, 16, v110
	s_waitcnt lgkmcnt(1)
	v_mfma_f32_16x16x32_bf16 v[106:109], v[162:165], v[28:31], v[106:109]
	v_and_b32_e32 v88, 0xffff0000, v110
	v_lshlrev_b32_e32 v90, 16, v111
	v_and_b32_e32 v92, 0xffff0000, v111
	s_waitcnt lgkmcnt(0)
	v_mfma_f32_16x16x32_bf16 v[106:109], v[166:169], v[16:19], v[106:109]
	s_nop 7
	v_add_f32_e32 v50, v48, v106
	v_add_f32_e32 v54, v48, v107
	v_add_f32_e32 v85, v48, v108
	v_add_f32_e32 v87, v48, v109
	v_mul_f32_e32 v106, v50, v56
	v_mul_f32_e32 v56, v54, v88
	v_mul_f32_e32 v108, v85, v90
	v_mul_f32_e32 v54, v87, v92
	v_cvt_pk_bf16_f32 v111, v106, v56
	v_cvt_pk_bf16_f32 v110, v108, v54
	ds_read_b128 v[162:165], v152 offset:30464
	ds_read_b128 v[166:169], v152 offset:30528
	s_waitcnt lgkmcnt(1)
	v_mfma_f32_16x16x32_bf16 v[20:23], v[162:165], v[20:23], 0
	v_mov_b32_e32 v87, v55
	v_mov_b32_e32 v85, v57
	v_mov_b32_e32 v88, v86
	s_waitcnt lgkmcnt(0)
	v_mfma_f32_16x16x32_bf16 v[20:23], v[166:169], v[24:27], v[20:23]
	ds_read_b128 v[24:27], v152 offset:30592
	ds_read_b128 v[162:165], v152 offset:30656
	v_mov_b32_e32 v90, v84
	s_waitcnt lgkmcnt(1)
	v_mfma_f32_16x16x32_bf16 v[24:27], v[24:27], v[28:31], v[20:23]
	v_mov_b64_e32 v[28:29], v[236:237]
	v_lshlrev_b32_e32 v30, 16, v15
	s_nop 0
	v_mov_b32_e32 v20, v106
	s_waitcnt lgkmcnt(0)
	v_mfma_f32_16x16x32_bf16 v[16:19], v[162:165], v[16:19], v[24:27]
	v_mov_b32_e32 v22, v108
	v_and_b32_e32 v15, 0xffff0000, v15
	v_mov_b32_e32 v31, v51
	s_waitcnt vmcnt(0)
	v_and_b32_e32 v24, 0xffff0000, v28
	s_nop 2
	v_add_f32_e32 v16, v48, v16
	v_add_f32_e32 v17, v48, v17
	v_add_f32_e32 v107, v48, v18
	v_add_f32_e32 v109, v48, v19
	v_lshlrev_b32_e32 v18, 16, v28
	v_lshlrev_b32_e32 v21, 16, v29
	v_and_b32_e32 v23, 0xffff0000, v29
	v_mul_f32_e32 v19, v16, v18
	v_mul_f32_e32 v17, v17, v24
	v_pk_mul_f32 v[26:27], v[106:107], v[20:21]
	v_pk_mul_f32 v[24:25], v[108:109], v[22:23]
	v_cvt_pk_bf16_f32 v106, v19, v17
	v_lshlrev_b32_e32 v16, 16, v12
	v_cvt_pk_bf16_f32 v29, v27, v25
	v_add_co_u32_e32 v242, vcc, s28, v42
	s_nop 1
	v_addc_co_u32_e32 v243, vcc, 0, v43, vcc
	global_load_dwordx4 v[222:225], v[242:243], off
	global_load_dwordx4 v[226:229], v[242:243], off offset:64
	global_load_dwordx4 v[230:233], v[242:243], off offset:128
	global_load_dwordx4 v[234:237], v[242:243], off offset:192
	global_load_dwordx4 v[162:165], v157, s[48:49] offset:1536
	global_load_dwordx4 v[166:169], v157, s[50:51] offset:1536
	global_load_dwordx4 v[170:173], v157, s[48:49] offset:1552
	global_load_dwordx4 v[174:177], v157, s[50:51] offset:1552
	global_load_dwordx4 v[178:181], v157, s[48:49] offset:1664
	global_load_dwordx4 v[182:185], v157, s[50:51] offset:1664
	global_load_dwordx4 v[186:189], v157, s[48:49] offset:1680
	global_load_dwordx4 v[190:193], v157, s[50:51] offset:1680
	global_load_dwordx4 v[194:197], v157, s[48:49] offset:1792
	global_load_dwordx4 v[198:201], v157, s[50:51] offset:1792
	global_load_dwordx4 v[202:205], v157, s[48:49] offset:1808
	global_load_dwordx4 v[206:209], v157, s[50:51] offset:1808
	global_load_dwordx4 v[210:213], v157, s[48:49] offset:1920
	global_load_dwordx4 v[214:217], v157, s[50:51] offset:1920
	global_load_dwordx4 v[218:221], v157, s[48:49] offset:1936
	global_load_dwordx4 v[238:241], v157, s[50:51] offset:1936
	v_and_b32_e32 v18, 0xffff0000, v12
	v_lshlrev_b32_e32 v20, 16, v13
	v_and_b32_e32 v22, 0xffff0000, v13
	ds_read_b64 v[12:13], v160
	v_lshlrev_b32_e32 v28, 16, v14
	v_and_b32_e32 v14, 0xffff0000, v14
	v_mov_b32_e32 v57, v107
	v_mov_b32_e32 v55, v109
	s_waitcnt lgkmcnt(0)
	v_sub_f32_e32 v16, v16, v12
	v_sub_f32_e32 v15, v15, v12
	v_sub_f32_e32 v18, v18, v12
	v_mul_f32_e32 v16, v13, v16
	v_mul_f32_e32 v15, v13, v15
	v_sub_f32_e32 v20, v20, v12
	v_mul_f32_e32 v18, v13, v18
	v_sub_f32_e32 v22, v22, v12
	v_sub_f32_e32 v14, v14, v12
	v_mul_f32_e32 v20, v13, v20
	v_sub_f32_e32 v28, v28, v12
	v_mul_f32_e32 v22, v13, v22
	v_mul_f32_e32 v14, v13, v14
	v_sub_f32_e32 v30, v30, v12
	v_mul_f32_e32 v28, v13, v28
	v_mul_f32_e32 v30, v13, v30
	s_waitcnt vmcnt(2)
	v_fma_f32 v16, v162, v16, v166
	v_fma_f32 v18, v163, v18, v167
	s_waitcnt vmcnt(0)
	v_fmac_f32_e32 v177, v173, v15
	v_cvt_pk_bf16_f32 v15, v16, v33
	ds_write_b16 v155, v15 offset:34816
	v_cvt_pk_bf16_f32 v15, v18, v33
	v_fma_f32 v20, v164, v20, v168
	ds_write_b16 v155, v15 offset:35088
	v_cvt_pk_bf16_f32 v15, v20, v33
	v_fmac_f32_e32 v169, v165, v22
	v_fma_f32 v14, v171, v14, v175
	ds_write_b16 v155, v15 offset:35360
	v_cvt_pk_bf16_f32 v15, v169, v33
	v_fma_f32 v22, v170, v28, v174
	ds_write_b16 v155, v15 offset:35632
	v_cvt_pk_bf16_f32 v15, v22, v33
	ds_write_b16 v155, v15 offset:35904
	v_cvt_pk_bf16_f32 v14, v14, v33
	v_fma_f32 v28, v172, v30, v176
	ds_write_b16 v155, v14 offset:36176
	v_cvt_pk_bf16_f32 v14, v28, v33
	ds_write_b16 v155, v14 offset:36448
	v_cvt_pk_bf16_f32 v14, v177, v33
	v_mov_b64_e32 v[160:161], v[178:179]
	v_mov_b64_e32 v[162:163], v[180:181]
	v_mov_b64_e32 v[164:165], v[182:183]
	v_mov_b64_e32 v[166:167], v[184:185]
	v_mov_b64_e32 v[168:169], v[186:187]
	v_mov_b64_e32 v[170:171], v[188:189]
	v_mov_b64_e32 v[172:173], v[190:191]
	v_mov_b64_e32 v[174:175], v[192:193]
	v_lshlrev_b32_e32 v15, 16, v8
	v_and_b32_e32 v8, 0xffff0000, v8
	v_lshlrev_b32_e32 v20, 16, v11
	v_and_b32_e32 v11, 0xffff0000, v11
	v_sub_f32_e32 v8, v8, v12
	v_lshlrev_b32_e32 v16, 16, v9
	v_sub_f32_e32 v15, v15, v12
	v_sub_f32_e32 v11, v11, v12
	v_mul_f32_e32 v8, v13, v8
	v_and_b32_e32 v9, 0xffff0000, v9
	v_sub_f32_e32 v16, v16, v12
	v_mul_f32_e32 v15, v13, v15
	v_mul_f32_e32 v11, v13, v11
	v_lshlrev_b32_e32 v18, 16, v10
	v_sub_f32_e32 v9, v9, v12
	v_mul_f32_e32 v16, v13, v16
	ds_write_b16 v155, v14 offset:36720
	v_and_b32_e32 v10, 0xffff0000, v10
	v_sub_f32_e32 v18, v18, v12
	v_mul_f32_e32 v9, v13, v9
	v_sub_f32_e32 v10, v10, v12
	v_mul_f32_e32 v18, v13, v18
	v_sub_f32_e32 v20, v20, v12
	v_mul_f32_e32 v10, v13, v10
	v_mul_f32_e32 v20, v13, v20
	v_lshlrev_b32_e32 v22, 16, v7
	v_and_b32_e32 v7, 0xffff0000, v7
	v_sub_f32_e32 v7, v7, v12
	v_mul_f32_e32 v7, v13, v7
	v_sub_f32_e32 v22, v22, v12
	v_mul_f32_e32 v22, v13, v22
	v_mov_b32_e32 v30, v64
	v_lshlrev_b32_e32 v28, 16, v0
	s_waitcnt vmcnt(2)
	v_fma_f32 v8, v8, v161, v165
	v_fma_f32 v14, v15, v160, v164
	s_waitcnt vmcnt(0)
	v_fmac_f32_e32 v175, v11, v171
	v_cvt_pk_bf16_f32 v11, v14, v33
	ds_write_b16 v155, v11 offset:43520
	v_cvt_pk_bf16_f32 v8, v8, v33
	v_fma_f32 v15, v16, v162, v166
	ds_write_b16 v155, v8 offset:43792
	v_cvt_pk_bf16_f32 v8, v15, v33
	v_fmac_f32_e32 v167, v9, v163
	ds_write_b16 v155, v8 offset:44064
	v_cvt_pk_bf16_f32 v8, v167, v33
	v_fma_f32 v9, v18, v168, v172
	ds_write_b16 v155, v8 offset:44336
	v_cvt_pk_bf16_f32 v8, v9, v33
	v_fma_f32 v10, v10, v169, v173
	ds_write_b16 v155, v8 offset:44608
	v_cvt_pk_bf16_f32 v8, v10, v33
	v_fma_f32 v16, v20, v170, v174
	ds_write_b16 v155, v8 offset:44880
	v_cvt_pk_bf16_f32 v8, v16, v33
	ds_write_b16 v155, v8 offset:45152
	v_cvt_pk_bf16_f32 v18, v175, v33
	v_mov_b64_e32 v[8:9], v[194:195]
	v_mov_b64_e32 v[10:11], v[196:197]
	v_mov_b64_e32 v[160:161], v[198:199]
	v_mov_b64_e32 v[162:163], v[200:201]
	v_mov_b64_e32 v[164:165], v[202:203]
	v_mov_b64_e32 v[166:167], v[204:205]
	v_mov_b64_e32 v[168:169], v[206:207]
	v_mov_b64_e32 v[170:171], v[208:209]
	v_pk_add_f32 v[14:15], v[66:67], v[66:67] op_sel:[0,1] op_sel_hi:[1,0]
	v_mul_f32_e32 v16, v53, v53
	v_mov_b32_e32 v50, v14
	v_pk_add_f32 v[14:15], v[14:15], v[64:65]
	v_pk_fma_f32 v[52:53], v[52:53], v[52:53], v[16:17] op_sel_hi:[1,1,0]
	v_lshlrev_b32_e32 v15, 16, v4
	v_and_b32_e32 v4, 0xffff0000, v4
	v_sub_f32_e32 v4, v4, v12
	v_lshlrev_b32_e32 v16, 16, v5
	v_sub_f32_e32 v15, v15, v12
	v_mul_f32_e32 v4, v13, v4
	v_and_b32_e32 v5, 0xffff0000, v5
	v_sub_f32_e32 v16, v16, v12
	v_mul_f32_e32 v15, v13, v15
	v_lshlrev_b32_e32 v20, 16, v6
	v_sub_f32_e32 v5, v5, v12
	v_mul_f32_e32 v16, v13, v16
	ds_write_b16 v155, v18 offset:45424
	v_and_b32_e32 v6, 0xffff0000, v6
	v_sub_f32_e32 v20, v20, v12
	v_mul_f32_e32 v5, v13, v5
	v_sub_f32_e32 v6, v6, v12
	v_mul_f32_e32 v20, v13, v20
	v_mul_f32_e32 v6, v13, v6
	v_mov_b32_e32 v172, v58
	v_mov_b32_e32 v173, v49
	v_pk_mul_f32 v[30:31], v[50:51], v[30:31]
	v_mov_b32_e32 v48, v52
	v_pk_add_f32 v[50:51], v[52:53], v[58:59]
	v_pk_add_f32 v[52:53], v[68:69], v[70:71]
	v_and_b32_e32 v68, 0xffff0000, v0
	v_lshlrev_b32_e32 v69, 16, v1
	v_and_b32_e32 v70, 0xffff0000, v1
	v_pk_mul_f32 v[0:1], v[78:79], v[78:79]
	v_lshlrev_b32_e32 v71, 16, v2
	v_pk_fma_f32 v[0:1], v[76:77], v[76:77], v[0:1]
	v_pk_mul_f32 v[58:59], v[98:99], v[98:99]
	v_pk_add_f32 v[0:1], v[0:1], v[0:1] op_sel:[0,1] op_sel_hi:[1,0]
	s_waitcnt vmcnt(2)
	v_fma_f32 v4, v4, v9, v161
	v_fma_f32 v8, v15, v8, v160
	s_waitcnt vmcnt(0)
	v_fmac_f32_e32 v171, v7, v167
	v_cvt_pk_bf16_f32 v7, v8, v33
	ds_write_b16 v155, v7 offset:52224
	v_cvt_pk_bf16_f32 v4, v4, v33
	v_fma_f32 v9, v16, v10, v162
	ds_write_b16 v155, v4 offset:52496
	v_cvt_pk_bf16_f32 v4, v9, v33
	v_fmac_f32_e32 v163, v5, v11
	ds_write_b16 v155, v4 offset:52768
	v_cvt_pk_bf16_f32 v4, v163, v33
	v_fma_f32 v5, v20, v164, v168
	ds_write_b16 v155, v4 offset:53040
	v_cvt_pk_bf16_f32 v4, v5, v33
	v_fma_f32 v6, v6, v165, v169
	ds_write_b16 v155, v4 offset:53312
	v_cvt_pk_bf16_f32 v4, v6, v33
	v_fma_f32 v10, v22, v166, v170
	ds_write_b16 v155, v4 offset:53584
	v_cvt_pk_bf16_f32 v4, v10, v33
	ds_write_b16 v155, v4 offset:53856
	v_cvt_pk_bf16_f32 v18, v171, v33
	v_mov_b64_e32 v[4:5], v[210:211]
	v_mov_b64_e32 v[6:7], v[212:213]
	v_mov_b64_e32 v[8:9], v[214:215]
	v_mov_b64_e32 v[10:11], v[216:217]
	v_mov_b64_e32 v[60:61], v[218:219]
	v_mov_b64_e32 v[62:63], v[220:221]
	v_mov_b64_e32 v[64:65], v[238:239]
	v_mov_b64_e32 v[66:67], v[240:241]
	v_mov_b32_e32 v15, v31
	v_pk_mul_f32 v[30:31], v[48:49], v[172:173]
	v_mov_b32_e32 v2, v0
	v_mov_b32_e32 v51, v31
	v_pk_add_f32 v[14:15], v[14:15], v[50:51]
	v_mul_f32_e32 v16, v81, v81
	v_pk_add_f32 v[14:15], v[14:15], v[52:53]
	v_pk_fma_f32 v[30:31], v[80:81], v[80:81], v[16:17] op_sel_hi:[1,1,0]
	v_pk_add_f32 v[14:15], v[14:15], v[14:15] op_sel:[0,1] op_sel_hi:[1,0]
	v_mov_b32_e32 v92, v30
	v_mov_b32_e32 v94, v14
	v_pk_add_f32 v[0:1], v[14:15], v[0:1]
	v_mul_f32_e32 v14, v83, v83
	v_pk_fma_f32 v[14:15], v[82:83], v[82:83], v[14:15] op_sel_hi:[1,1,0]
	v_mov_b32_e32 v49, v93
	v_mov_b32_e32 v48, v14
	v_pk_add_f32 v[14:15], v[30:31], v[14:15]
	v_pk_fma_f32 v[30:31], v[86:87], v[88:89], v[96:97]
	v_pk_mul_f32 v[50:51], v[96:97], v[96:97]
	v_pk_fma_f32 v[52:53], v[84:85], v[90:91], v[98:99]
	v_pk_mul_f32 v[2:3], v[94:95], v[2:3]
	v_pk_mul_f32 v[48:49], v[92:93], v[48:49]
	v_mov_b32_e32 v31, v51
	v_mov_b32_e32 v53, v59
	v_mov_b32_e32 v1, v3
	v_mov_b32_e32 v15, v49
	v_pk_add_f32 v[2:3], v[30:31], v[52:53]
	v_pk_add_f32 v[0:1], v[0:1], v[14:15]
	ds_write_b16 v155, v18 offset:54128
	v_pk_add_f32 v[50:51], v[0:1], v[2:3]
	v_pk_mul_f32 v[0:1], v[102:103], v[102:103]
	v_sub_f32_e32 v2, v69, v12
	v_pk_fma_f32 v[0:1], v[100:101], v[100:101], v[0:1]
	v_sub_f32_e32 v3, v70, v12
	v_pk_add_f32 v[48:49], v[0:1], v[0:1] op_sel:[0,1] op_sel_hi:[1,0]
	v_mul_f32_e32 v0, v105, v105
	v_pk_fma_f32 v[30:31], v[104:105], v[104:105], v[0:1] op_sel_hi:[1,1,0]
	v_sub_f32_e32 v0, v28, v12
	v_mul_f32_e32 v0, v13, v0
	v_sub_f32_e32 v1, v68, v12
	v_mul_f32_e32 v1, v13, v1
	v_mul_f32_e32 v2, v13, v2
	v_sub_f32_e32 v14, v71, v12
	v_mul_f32_e32 v3, v13, v3
	v_sub_f32_e32 v15, v72, v12
	v_mul_f32_e32 v14, v13, v14
	v_sub_f32_e32 v16, v73, v12
	v_mul_f32_e32 v15, v13, v15
	v_sub_f32_e32 v12, v74, v12
	v_mul_f32_e32 v16, v13, v16
	v_mul_f32_e32 v12, v13, v12
	v_mov_b32_e32 v20, v56
	v_mov_b32_e32 v22, v54
	s_waitcnt vmcnt(2)
	v_fma_f32 v0, v0, v4, v8
	v_cvt_pk_bf16_f32 v0, v0, v33
	v_fma_f32 v1, v1, v5, v9
	ds_write_b16 v155, v0 offset:60928
	v_cvt_pk_bf16_f32 v0, v1, v33
	v_fma_f32 v2, v2, v6, v10
	ds_write_b16 v155, v0 offset:61200
	v_cvt_pk_bf16_f32 v0, v2, v33
	v_fmac_f32_e32 v11, v3, v7
	ds_write_b16 v155, v0 offset:61472
	v_cvt_pk_bf16_f32 v0, v11, v33
	s_waitcnt vmcnt(0)
	v_fma_f32 v3, v14, v60, v64
	ds_write_b16 v155, v0 offset:61744
	v_cvt_pk_bf16_f32 v0, v3, v33
	v_fma_f32 v4, v15, v61, v65
	ds_write_b16 v155, v0 offset:62016
	v_cvt_pk_bf16_f32 v0, v4, v33
	v_fma_f32 v5, v16, v62, v66
	ds_write_b16 v155, v0 offset:62288
	v_cvt_pk_bf16_f32 v0, v5, v33
	v_fmac_f32_e32 v67, v12, v63
	ds_write_b16 v155, v0 offset:62560
	v_cvt_pk_bf16_f32 v0, v67, v33
	ds_write_b16 v155, v0 offset:62832
	s_waitcnt lgkmcnt(0)
	s_barrier
	v_pk_fma_f32 v[56:57], v[56:57], v[20:21], v[26:27]
	s_nop 0
	v_mov_b64_e32 v[8:9], v[222:223]
	v_mov_b64_e32 v[10:11], v[224:225]
	v_mov_b64_e32 v[0:1], v[226:227]
	v_mov_b64_e32 v[2:3], v[228:229]
	v_mov_b64_e32 v[12:13], v[230:231]
	v_mov_b64_e32 v[14:15], v[232:233]
	v_mov_b64_e32 v[4:5], v[234:235]
	v_mov_b64_e32 v[6:7], v[236:237]
	global_load_dwordx2 v[224:225], v[40:41], off offset:1824
	global_load_dwordx2 v[226:227], v[40:41], off offset:1856
	global_load_dwordx2 v[228:229], v[40:41], off offset:1888
	global_load_dwordx2 v[230:231], v[40:41], off offset:1920
	global_load_dwordx2 v[232:233], v[40:41], off offset:1952
	global_load_dwordx2 v[234:235], v[40:41], off offset:1984
	global_load_dwordx2 v[236:237], v[40:41], off offset:2016
	global_load_dwordx2 v[52:53], v[40:41], off offset:1792
	s_nop 0
	s_nop 0
	global_load_dword v28, v[44:45], off offset:1536
	ds_read_b128 v[42:45], v152 offset:34816
	ds_read_b128 v[58:61], v152 offset:34880
	ds_read_b128 v[62:65], v152 offset:34944
	v_pk_fma_f32 v[54:55], v[54:55], v[22:23], v[24:25]
	v_pk_mul_f32 v[24:25], v[24:25], v[24:25]
	v_pk_mul_f32 v[26:27], v[26:27], v[26:27]
	v_pk_add_f32 v[50:51], v[50:51], v[50:51] op_sel:[0,1] op_sel_hi:[1,0]
	v_mov_b32_e32 v168, v48
	v_mov_b32_e32 v169, v19
	v_mov_b32_e32 v170, v30
	v_mov_b32_e32 v171, v17
	s_waitcnt vmcnt(1) lgkmcnt(2)
	v_mfma_f32_16x16x32_bf16 v[42:45], v[42:45], v[8:11], 0
	s_waitcnt vmcnt(0)
	v_lshlrev_b32_e32 v67, 16, v53
	v_lshlrev_b32_e32 v66, 16, v52
	s_waitcnt lgkmcnt(1)
	v_mfma_f32_16x16x32_bf16 v[42:45], v[58:61], v[0:3], v[42:45]
	ds_read_b128 v[58:61], v152 offset:35008
	v_and_b32_e32 v53, 0xffff0000, v53
	v_and_b32_e32 v52, 0xffff0000, v52
	s_waitcnt vmcnt(0) lgkmcnt(1)
	v_mfma_f32_16x16x32_bf16 v[42:45], v[62:65], v[12:15], v[42:45]
	s_waitcnt vmcnt(0) lgkmcnt(0)
	v_mfma_f32_16x16x32_bf16 v[42:45], v[58:61], v[4:7], v[42:45]
	s_nop 7
	v_mov_b32_e32 v58, v42
	v_mov_b32_e32 v59, v44
	v_mov_b32_e32 v44, v43
	s_waitcnt vmcnt(0)
	v_pk_add_f32 v[42:43], v[28:29], v[58:59] op_sel_hi:[0,1]
	v_pk_add_f32 v[44:45], v[28:29], v[44:45] op_sel_hi:[0,1]
	v_pk_mul_f32 v[42:43], v[42:43], v[66:67]
	v_pk_mul_f32 v[44:45], v[44:45], v[52:53]
	s_nop 0
	v_cvt_pk_bf16_f32 v77, v42, v44
	v_cvt_pk_bf16_f32 v76, v43, v45
	ds_read_b128 v[58:61], v152 offset:39168
	ds_read_b128 v[62:65], v152 offset:39232
	s_waitcnt lgkmcnt(1)
	v_mfma_f32_16x16x32_bf16 v[58:61], v[58:61], v[8:11], 0
	s_waitcnt lgkmcnt(0)
	v_mfma_f32_16x16x32_bf16 v[58:61], v[62:65], v[0:3], v[58:61]
	ds_read_b128 v[62:65], v152 offset:39296
	ds_read_b128 v[66:69], v152 offset:39360
	v_mov_b64_e32 v[52:53], v[224:225]
	s_waitcnt lgkmcnt(1)
	v_mfma_f32_16x16x32_bf16 v[58:61], v[62:65], v[12:15], v[58:61]
	s_waitcnt vmcnt(0)
	v_lshlrev_b32_e32 v62, 16, v52
	s_waitcnt lgkmcnt(0)
	v_mfma_f32_16x16x32_bf16 v[58:61], v[66:69], v[4:7], v[58:61]
	v_and_b32_e32 v63, 0xffff0000, v52
	v_lshlrev_b32_e32 v64, 16, v53
	v_and_b32_e32 v65, 0xffff0000, v53
	s_nop 4
	v_pk_add_f32 v[58:59], v[28:29], v[58:59] op_sel_hi:[0,1]
	v_pk_add_f32 v[60:61], v[28:29], v[60:61] op_sel_hi:[0,1]
	v_pk_mul_f32 v[52:53], v[58:59], v[62:63]
	v_pk_mul_f32 v[58:59], v[60:61], v[64:65]
	v_cvt_pk_bf16_f32 v75, v52, v53
	s_nop 0
	v_cvt_pk_bf16_f32 v74, v58, v59
	ds_read_b128 v[60:63], v152 offset:43520
	ds_read_b128 v[64:67], v152 offset:43584
	s_waitcnt lgkmcnt(1)
	v_mfma_f32_16x16x32_bf16 v[60:63], v[60:63], v[8:11], 0
	s_waitcnt lgkmcnt(0)
	v_mfma_f32_16x16x32_bf16 v[60:63], v[64:67], v[0:3], v[60:63]
	ds_read_b128 v[64:67], v152 offset:43648
	ds_read_b128 v[68:71], v152 offset:43712
	s_waitcnt lgkmcnt(1)
	v_mfma_f32_16x16x32_bf16 v[60:63], v[64:67], v[12:15], v[60:63]
	v_mov_b64_e32 v[64:65], v[226:227]
	s_waitcnt vmcnt(0)
	v_lshlrev_b32_e32 v66, 16, v65
	s_waitcnt lgkmcnt(0)
	v_mfma_f32_16x16x32_bf16 v[60:63], v[68:71], v[4:7], v[60:63]
	v_and_b32_e32 v65, 0xffff0000, v65
	s_nop 6
	v_add_f32_e32 v16, v28, v60
	v_add_f32_e32 v18, v28, v61
	v_add_f32_e32 v60, v28, v62
	v_add_f32_e32 v61, v28, v63
	v_lshlrev_b32_e32 v62, 16, v64
	v_and_b32_e32 v63, 0xffff0000, v64
	v_mul_f32_e32 v64, v16, v62
	v_mul_f32_e32 v62, v18, v63
	v_mul_f32_e32 v66, v60, v66
	v_mul_f32_e32 v60, v61, v65
	v_cvt_pk_bf16_f32 v73, v64, v62
	v_cvt_pk_bf16_f32 v72, v66, v60
	ds_read_b128 v[68:71], v152 offset:47872
	ds_read_b128 v[78:81], v152 offset:47936
	s_waitcnt lgkmcnt(1)
	v_mfma_f32_16x16x32_bf16 v[68:71], v[68:71], v[8:11], 0
	v_mov_b32_e32 v94, v64
	v_mov_b32_e32 v96, v66
	s_waitcnt lgkmcnt(0)
	v_mfma_f32_16x16x32_bf16 v[68:71], v[78:81], v[0:3], v[68:71]
	ds_read_b128 v[78:81], v152 offset:48000
	ds_read_b128 v[82:85], v152 offset:48064
	s_waitcnt lgkmcnt(1)
	v_mfma_f32_16x16x32_bf16 v[68:71], v[78:81], v[12:15], v[68:71]
	v_mov_b64_e32 v[78:79], v[228:229]
	s_waitcnt vmcnt(0)
	v_lshlrev_b32_e32 v61, 16, v78
	s_waitcnt lgkmcnt(0)
	v_mfma_f32_16x16x32_bf16 v[68:71], v[82:85], v[4:7], v[68:71]
	v_and_b32_e32 v63, 0xffff0000, v78
	v_lshlrev_b32_e32 v95, 16, v79
	v_and_b32_e32 v97, 0xffff0000, v79
	s_nop 4
	v_add_f32_e32 v16, v28, v68
	v_add_f32_e32 v18, v28, v69
	v_add_f32_e32 v65, v28, v70
	v_add_f32_e32 v67, v28, v71
	v_mul_f32_e32 v99, v16, v61
	v_mul_f32_e32 v101, v18, v63
	v_pk_mul_f32 v[102:103], v[64:65], v[94:95]
	v_pk_mul_f32 v[104:105], v[66:67], v[96:97]
	v_cvt_pk_bf16_f32 v71, v99, v101
	v_mul_f32_e32 v16, v47, v47
	v_cvt_pk_bf16_f32 v69, v103, v105
	ds_read_b128 v[78:81], v152 offset:52224
	ds_read_b128 v[82:85], v152 offset:52288
	s_waitcnt lgkmcnt(1)
	v_mfma_f32_16x16x32_bf16 v[78:81], v[78:81], v[8:11], 0
	v_mov_b32_e32 v18, v50
	v_pk_mul_f32 v[18:19], v[18:19], v[168:169]
	v_mov_b32_e32 v63, v65
	s_waitcnt lgkmcnt(0)
	v_mfma_f32_16x16x32_bf16 v[78:81], v[82:85], v[0:3], v[78:81]
	ds_read_b128 v[82:85], v152 offset:52352
	ds_read_b128 v[86:89], v152 offset:52416
	v_mov_b32_e32 v94, v62
	v_mov_b32_e32 v96, v60
	s_waitcnt lgkmcnt(1)
	v_mfma_f32_16x16x32_bf16 v[78:81], v[82:85], v[12:15], v[78:81]
	v_mov_b64_e32 v[82:83], v[230:231]
	s_waitcnt lgkmcnt(0)
	v_mfma_f32_16x16x32_bf16 v[78:81], v[86:89], v[4:7], v[78:81]
	s_nop 7
	v_mov_b32_e32 v84, v78
	v_mov_b32_e32 v85, v80
	v_mov_b32_e32 v80, v79
	v_pk_add_f32 v[78:79], v[28:29], v[84:85] op_sel_hi:[0,1]
	v_pk_add_f32 v[80:81], v[28:29], v[80:81] op_sel_hi:[0,1]
	s_waitcnt vmcnt(0)
	v_lshlrev_b32_e32 v85, 16, v83
	v_lshlrev_b32_e32 v84, 16, v82
	v_and_b32_e32 v83, 0xffff0000, v83
	v_and_b32_e32 v82, 0xffff0000, v82
	v_pk_mul_f32 v[108:109], v[78:79], v[84:85]
	v_pk_mul_f32 v[160:161], v[80:81], v[82:83]
	s_nop 0
	v_cvt_pk_bf16_f32 v70, v108, v160
	v_cvt_pk_bf16_f32 v68, v109, v161
	ds_read_b128 v[78:81], v152 offset:56576
	ds_read_b128 v[82:85], v152 offset:56640
	s_waitcnt lgkmcnt(1)
	v_mfma_f32_16x16x32_bf16 v[78:81], v[78:81], v[8:11], 0
	s_waitcnt lgkmcnt(0)
	v_mfma_f32_16x16x32_bf16 v[78:81], v[82:85], v[0:3], v[78:81]
	ds_read_b128 v[82:85], v152 offset:56704
	ds_read_b128 v[86:89], v152 offset:56768
	s_waitcnt lgkmcnt(1)
	v_mfma_f32_16x16x32_bf16 v[78:81], v[82:85], v[12:15], v[78:81]
	v_mov_b64_e32 v[82:83], v[232:233]
	s_waitcnt vmcnt(0)
	v_lshlrev_b32_e32 v84, 16, v82
	s_waitcnt lgkmcnt(0)
	v_mfma_f32_16x16x32_bf16 v[78:81], v[86:89], v[4:7], v[78:81]
	v_and_b32_e32 v85, 0xffff0000, v82
	v_lshlrev_b32_e32 v82, 16, v83
	v_and_b32_e32 v83, 0xffff0000, v83
	s_nop 4
	v_pk_add_f32 v[78:79], v[28:29], v[78:79] op_sel_hi:[0,1]
	v_pk_add_f32 v[80:81], v[28:29], v[80:81] op_sel_hi:[0,1]
	v_pk_mul_f32 v[162:163], v[78:79], v[84:85]
	v_pk_mul_f32 v[164:165], v[80:81], v[82:83]
	v_cvt_pk_bf16_f32 v66, v162, v163
	s_nop 0
	v_cvt_pk_bf16_f32 v64, v164, v165
	v_mov_b64_e32 v[166:167], v[234:235]
	ds_read_b128 v[78:81], v152 offset:60928
	ds_read_b128 v[82:85], v152 offset:60992
	ds_read_b128 v[86:89], v152 offset:61056
	ds_read_b128 v[90:93], v152 offset:61120
	s_waitcnt lgkmcnt(3)
	v_mfma_f32_16x16x32_bf16 v[78:81], v[78:81], v[8:11], 0
	s_waitcnt vmcnt(0)
	v_lshlrev_b32_e32 v24, 16, v166
	s_waitcnt lgkmcnt(2)
	v_mfma_f32_16x16x32_bf16 v[78:81], v[82:85], v[0:3], v[78:81]
	v_and_b32_e32 v55, 0xffff0000, v166
	v_lshlrev_b32_e32 v57, 16, v167
	v_and_b32_e32 v61, 0xffff0000, v167
	s_waitcnt lgkmcnt(1)
	v_mfma_f32_16x16x32_bf16 v[78:81], v[86:89], v[12:15], v[78:81]
	s_waitcnt lgkmcnt(0)
	v_mfma_f32_16x16x32_bf16 v[20:23], v[90:93], v[4:7], v[78:81]
	s_nop 7
	v_add_f32_e32 v20, v28, v20
	v_add_f32_e32 v21, v28, v21
	v_add_f32_e32 v22, v28, v22
	v_add_f32_e32 v23, v28, v23
	v_mul_f32_e32 v26, v20, v24
	v_mul_f32_e32 v78, v21, v55
	v_mul_f32_e32 v80, v22, v57
	v_mul_f32_e32 v82, v23, v61
	v_cvt_pk_bf16_f32 v21, v26, v78
	v_cvt_pk_bf16_f32 v20, v80, v82
	v_mov_b64_e32 v[84:85], v[236:237]
	v_pk_fma_f32 v[40:41], v[46:47], v[46:47], v[16:17] op_sel_hi:[1,1,0]
	v_pk_add_f32 v[22:23], v[50:51], v[48:49]
	v_mov_b32_e32 v16, v40
	v_mov_b32_e32 v55, v25
	v_pk_add_f32 v[24:25], v[40:41], v[30:31]
	v_pk_mul_f32 v[16:17], v[16:17], v[170:171]
	v_mov_b32_e32 v57, v27
	v_mov_b32_e32 v23, v19
	v_mov_b32_e32 v25, v17
	v_pk_add_f32 v[30:31], v[56:57], v[54:55]
	v_pk_add_f32 v[16:17], v[22:23], v[24:25]
	v_pk_mul_f32 v[18:19], v[44:45], v[44:45]
	v_pk_add_f32 v[16:17], v[16:17], v[30:31]
	v_pk_fma_f32 v[18:19], v[42:43], v[42:43], v[18:19]
	v_pk_add_f32 v[16:17], v[16:17], v[16:17] op_sel:[0,1] op_sel_hi:[1,0]
	v_pk_add_f32 v[18:19], v[18:19], v[18:19] op_sel:[0,1] op_sel_hi:[1,0]
	v_mov_b32_e32 v98, v16
	v_mov_b32_e32 v22, v18
	v_pk_add_f32 v[16:17], v[16:17], v[18:19]
	v_mul_f32_e32 v18, v59, v59
	v_mul_f32_e32 v24, v53, v53
	v_pk_fma_f32 v[18:19], v[58:59], v[58:59], v[18:19] op_sel_hi:[1,1,0]
	v_pk_fma_f32 v[24:25], v[52:53], v[52:53], v[24:25] op_sel_hi:[1,1,0]
	v_mov_b32_e32 v30, v18
	v_mov_b32_e32 v100, v24
	v_mov_b32_e32 v61, v67
	v_mov_b32_e32 v23, v99
	v_mov_b32_e32 v31, v101
	v_pk_add_f32 v[18:19], v[24:25], v[18:19]
	v_pk_fma_f32 v[24:25], v[62:63], v[94:95], v[102:103]
	v_pk_mul_f32 v[40:41], v[102:103], v[102:103]
	v_pk_fma_f32 v[42:43], v[60:61], v[96:97], v[104:105]
	v_pk_mul_f32 v[44:45], v[104:105], v[104:105]
	v_pk_mul_f32 v[22:23], v[98:99], v[22:23]
	v_pk_mul_f32 v[30:31], v[100:101], v[30:31]
	v_mov_b32_e32 v25, v41
	v_mov_b32_e32 v43, v45
	v_mov_b32_e32 v17, v23
	v_mov_b32_e32 v19, v31
	v_pk_add_f32 v[22:23], v[24:25], v[42:43]
	v_pk_add_f32 v[16:17], v[16:17], v[18:19]
	v_mul_f32_e32 v48, v165, v165
	v_pk_add_f32 v[16:17], v[16:17], v[22:23]
	v_pk_mul_f32 v[22:23], v[160:161], v[160:161]
	v_pk_add_f32 v[30:31], v[16:17], v[16:17] op_sel:[0,1] op_sel_hi:[1,0]
	ds_read_b128 v[16:19], v152 offset:65280
	v_pk_fma_f32 v[22:23], v[108:109], v[108:109], v[22:23]
	v_mov_b32_e32 v44, v30
	v_pk_add_f32 v[40:41], v[22:23], v[22:23] op_sel:[0,1] op_sel_hi:[1,0]
	ds_read_b128 v[22:25], v152 offset:65344
	v_mov_b32_e32 v46, v40
	v_pk_add_f32 v[30:31], v[30:31], v[40:41]
	ds_read_b128 v[40:43], v152 offset:65408
	s_waitcnt lgkmcnt(2)
	v_mfma_f32_16x16x32_bf16 v[8:11], v[16:19], v[8:11], 0
	ds_read_b128 v[16:19], v152 offset:65472
	v_mul_f32_e32 v50, v163, v163
	v_pk_fma_f32 v[48:49], v[164:165], v[164:165], v[48:49] op_sel_hi:[1,1,0]
	s_waitcnt lgkmcnt(2)
	v_mfma_f32_16x16x32_bf16 v[0:3], v[22:25], v[0:3], v[8:11]
	v_mov_b32_e32 v22, v48
	s_waitcnt lgkmcnt(1)
	v_mfma_f32_16x16x32_bf16 v[0:3], v[40:43], v[12:15], v[0:3]
	v_fma_f32 v8, v162, v162, v50
	v_fma_f32 v9, v163, v163, v50
	v_mov_b32_e32 v12, v26
	v_mov_b32_e32 v14, v80
	s_waitcnt lgkmcnt(0)
	v_mfma_f32_16x16x32_bf16 v[0:3], v[16:19], v[4:7], v[0:3]
	v_mov_b32_e32 v10, v8
	v_pk_add_f32 v[8:9], v[8:9], v[48:49]
	s_waitcnt vmcnt(0)
	v_lshlrev_b32_e32 v13, 16, v85
	s_nop 3
	v_add_f32_e32 v0, v28, v0
	v_add_f32_e32 v1, v28, v1
	v_add_f32_e32 v27, v28, v2
	v_add_f32_e32 v81, v28, v3
	v_lshlrev_b32_e32 v2, 16, v84
	v_and_b32_e32 v3, 0xffff0000, v84
	v_and_b32_e32 v15, 0xffff0000, v85
	v_mul_f32_e32 v45, v0, v2
	v_mul_f32_e32 v11, v1, v3
	v_mov_b32_e32 v79, v27
	v_mov_b32_e32 v83, v81
	v_pk_mul_f32 v[0:1], v[26:27], v[12:13]
	v_mov_b32_e32 v12, v78
	v_pk_mul_f32 v[2:3], v[80:81], v[14:15]
	v_mov_b32_e32 v14, v82
	v_mov_b32_e32 v47, v45
	v_mov_b32_e32 v23, v11
	v_cvt_pk_bf16_f32 v7, v45, v11
	v_cvt_pk_bf16_f32 v6, v1, v3
	v_pk_fma_f32 v[4:5], v[78:79], v[12:13], v[0:1]
	v_pk_mul_f32 v[0:1], v[0:1], v[0:1]
	v_pk_fma_f32 v[12:13], v[82:83], v[14:15], v[2:3]
	v_pk_mul_f32 v[2:3], v[2:3], v[2:3]
	v_pk_mul_f32 v[14:15], v[44:45], v[46:47]
	v_pk_mul_f32 v[10:11], v[10:11], v[22:23]
	v_mov_b32_e32 v5, v1
	v_mov_b32_e32 v13, v3
	v_mov_b32_e32 v31, v15
	v_mov_b32_e32 v9, v11
	v_pk_add_f32 v[0:1], v[4:5], v[12:13]
	v_pk_add_f32 v[2:3], v[30:31], v[8:9]
	s_nop 0
	v_pk_add_f32 v[0:1], v[2:3], v[0:1]
	s_barrier
	v_add_f32_e32 v8, v0, v1
	v_lshl_add_u64 v[4:5], v[38:39], 0, s[10:11]
	v_lshl_add_u64 v[0:1], v[4:5], 0, v[32:33]
	global_load_dwordx2 v[0:1], v[0:1], off
	v_or_b32_e32 v160, 0x20, v32
	v_mov_b32_e32 v161, v33
	v_lshl_add_u64 v[160:161], v[4:5], 0, v[160:161]
	global_load_dwordx2 v[160:161], v[160:161], off
	v_or_b32_e32 v162, 0x40, v32
	v_mov_b32_e32 v163, v33
	v_lshl_add_u64 v[162:163], v[4:5], 0, v[162:163]
	global_load_dwordx2 v[162:163], v[162:163], off
	v_or_b32_e32 v164, 0x60, v32
	v_mov_b32_e32 v165, v33
	v_lshl_add_u64 v[164:165], v[4:5], 0, v[164:165]
	global_load_dwordx2 v[164:165], v[164:165], off
	v_or_b32_e32 v166, 0x80, v32
	v_mov_b32_e32 v167, v33
	v_lshl_add_u64 v[166:167], v[4:5], 0, v[166:167]
	global_load_dwordx2 v[166:167], v[166:167], off
	v_or_b32_e32 v168, 0xa0, v32
	v_mov_b32_e32 v169, v33
	v_lshl_add_u64 v[168:169], v[4:5], 0, v[168:169]
	global_load_dwordx2 v[168:169], v[168:169], off
	v_or_b32_e32 v170, 0xc0, v32
	v_mov_b32_e32 v171, v33
	v_lshl_add_u64 v[170:171], v[4:5], 0, v[170:171]
	global_load_dwordx2 v[170:171], v[170:171], off
	v_or_b32_e32 v172, 0xe0, v32
	v_mov_b32_e32 v173, v33
	v_lshl_add_u64 v[172:173], v[4:5], 0, v[172:173]
	global_load_dwordx2 v[172:173], v[172:173], off
	v_or_b32_e32 v174, 0x100, v32
	v_mov_b32_e32 v175, v33
	v_lshl_add_u64 v[174:175], v[4:5], 0, v[174:175]
	global_load_dwordx2 v[174:175], v[174:175], off
	v_or_b32_e32 v176, 0x120, v32
	v_mov_b32_e32 v177, v33
	v_lshl_add_u64 v[176:177], v[4:5], 0, v[176:177]
	global_load_dwordx2 v[176:177], v[176:177], off
	v_or_b32_e32 v178, 0x140, v32
	v_mov_b32_e32 v179, v33
	v_lshl_add_u64 v[178:179], v[4:5], 0, v[178:179]
	global_load_dwordx2 v[178:179], v[178:179], off
	v_or_b32_e32 v180, 0x160, v32
	v_mov_b32_e32 v181, v33
	v_lshl_add_u64 v[180:181], v[4:5], 0, v[180:181]
	global_load_dwordx2 v[180:181], v[180:181], off
	v_or_b32_e32 v182, 0x180, v32
	v_mov_b32_e32 v183, v33
	v_lshl_add_u64 v[182:183], v[4:5], 0, v[182:183]
	global_load_dwordx2 v[182:183], v[182:183], off
	v_or_b32_e32 v184, 0x1a0, v32
	v_mov_b32_e32 v185, v33
	v_lshl_add_u64 v[184:185], v[4:5], 0, v[184:185]
	global_load_dwordx2 v[184:185], v[184:185], off
	v_or_b32_e32 v186, 0x1c0, v32
	v_mov_b32_e32 v187, v33
	v_lshl_add_u64 v[186:187], v[4:5], 0, v[186:187]
	global_load_dwordx2 v[186:187], v[186:187], off
	v_or_b32_e32 v188, 0x1e0, v32
	v_mov_b32_e32 v189, v33
	v_lshl_add_u64 v[188:189], v[4:5], 0, v[188:189]
	global_load_dwordx2 v[188:189], v[188:189], off
	v_or_b32_e32 v190, 0x200, v32
	v_mov_b32_e32 v191, v33
	v_lshl_add_u64 v[190:191], v[4:5], 0, v[190:191]
	global_load_dwordx2 v[190:191], v[190:191], off
	v_or_b32_e32 v192, 0x220, v32
	v_mov_b32_e32 v193, v33
	v_lshl_add_u64 v[192:193], v[4:5], 0, v[192:193]
	global_load_dwordx2 v[192:193], v[192:193], off
	v_or_b32_e32 v194, 0x240, v32
	v_mov_b32_e32 v195, v33
	v_lshl_add_u64 v[194:195], v[4:5], 0, v[194:195]
	global_load_dwordx2 v[194:195], v[194:195], off
	v_or_b32_e32 v196, 0x260, v32
	v_mov_b32_e32 v197, v33
	v_lshl_add_u64 v[196:197], v[4:5], 0, v[196:197]
	global_load_dwordx2 v[196:197], v[196:197], off
	v_or_b32_e32 v198, 0x280, v32
	v_mov_b32_e32 v199, v33
	v_lshl_add_u64 v[198:199], v[4:5], 0, v[198:199]
	global_load_dwordx2 v[198:199], v[198:199], off
	v_or_b32_e32 v200, 0x2a0, v32
	v_mov_b32_e32 v201, v33
	v_lshl_add_u64 v[200:201], v[4:5], 0, v[200:201]
	global_load_dwordx2 v[200:201], v[200:201], off
	v_or_b32_e32 v202, 0x2c0, v32
	v_mov_b32_e32 v203, v33
	v_lshl_add_u64 v[202:203], v[4:5], 0, v[202:203]
	global_load_dwordx2 v[202:203], v[202:203], off
	v_or_b32_e32 v204, 0x2e0, v32
	v_mov_b32_e32 v205, v33
	v_lshl_add_u64 v[204:205], v[4:5], 0, v[204:205]
	global_load_dwordx2 v[204:205], v[204:205], off
	v_or_b32_e32 v206, 0x300, v32
	v_mov_b32_e32 v207, v33
	v_lshl_add_u64 v[206:207], v[4:5], 0, v[206:207]
	global_load_dwordx2 v[206:207], v[206:207], off
	v_or_b32_e32 v208, 0x320, v32
	v_mov_b32_e32 v209, v33
	v_lshl_add_u64 v[208:209], v[4:5], 0, v[208:209]
	global_load_dwordx2 v[208:209], v[208:209], off
	v_or_b32_e32 v210, 0x340, v32
	v_mov_b32_e32 v211, v33
	v_lshl_add_u64 v[210:211], v[4:5], 0, v[210:211]
	global_load_dwordx2 v[210:211], v[210:211], off
	v_or_b32_e32 v212, 0x360, v32
	v_mov_b32_e32 v213, v33
	v_lshl_add_u64 v[212:213], v[4:5], 0, v[212:213]
	global_load_dwordx2 v[212:213], v[212:213], off
	v_or_b32_e32 v214, 0x380, v32
	v_mov_b32_e32 v215, v33
	v_lshl_add_u64 v[214:215], v[4:5], 0, v[214:215]
	global_load_dwordx2 v[214:215], v[214:215], off
	v_or_b32_e32 v216, 0x3a0, v32
	v_mov_b32_e32 v217, v33
	v_lshl_add_u64 v[216:217], v[4:5], 0, v[216:217]
	global_load_dwordx2 v[216:217], v[216:217], off
	v_or_b32_e32 v218, 0x3c0, v32
	v_mov_b32_e32 v219, v33
	v_lshl_add_u64 v[218:219], v[4:5], 0, v[218:219]
	global_load_dwordx2 v[218:219], v[218:219], off
	v_or_b32_e32 v220, 0x3e0, v32
	v_mov_b32_e32 v221, v33
	v_lshl_add_u64 v[220:221], v[4:5], 0, v[220:221]
	global_load_dwordx2 v[220:221], v[220:221], off
	v_lshlrev_b64 v[2:3], 11, v[36:37]
	v_lshl_add_u64 v[18:19], s[86:87], 0, v[2:3]
	v_lshlrev_b32_e32 v9, 16, v150
	v_and_b32_e32 v11, 0xffff0000, v150
	s_waitcnt lgkmcnt(0)
	v_mov_b32_e32 v10, v8
	s_nop 1
	v_permlane16_swap_b32_e32 v8, v10
	v_add_f32_e32 v8, v8, v10
	v_mov_b32_e32 v10, v8
	s_nop 1
	v_permlane32_swap_b32_e32 v8, v10
	v_add_f32_e32 v8, v8, v10
	v_fmamk_f32 v8, v8, 0x3b000000, v124
	v_mul_f32_e32 v10, 0x4b800000, v8
	v_cmp_gt_f32_e32 vcc, s3, v8
	v_lshlrev_b32_e32 v13, 16, v148
	v_and_b32_e32 v15, 0xffff0000, v148
	v_cndmask_b32_e32 v8, v8, v10, vcc
	v_rsq_f32_e32 v8, v8
	v_or_b32_e32 v16, 32, v32
	v_mov_b32_e32 v17, v33
	v_lshl_add_u64 v[16:17], v[4:5], 0, v[16:17]
	v_mul_f32_e32 v2, 0x45800000, v8
	v_cndmask_b32_e32 v3, v8, v2, vcc
	v_mov_b32_e32 v24, v3
	v_mov_b32_e32 v26, v3
	v_mov_b32_e32 v30, v3
	s_add_i32 s54, s54, s52
	s_add_u32 s4, s4, s6
	s_addc_u32 s5, s5, s7
	s_cmpk_gt_i32 s54, 0xff
	s_waitcnt vmcnt(0)
	v_lshlrev_b32_e32 v8, 16, v0
	v_and_b32_e32 v10, 0xffff0000, v0
	v_mul_f32_e32 v0, 0xbfb8aa3b, v8
	v_exp_f32_e32 v0, v0
	v_lshlrev_b32_e32 v12, 16, v1
	v_and_b32_e32 v14, 0xffff0000, v1
	v_mul_f32_e32 v1, 0xbfb8aa3b, v10
	v_exp_f32_e32 v1, v1
	v_add_f32_e32 v0, 1.0, v0
	v_rcp_f32_e32 v2, v0
	v_mul_f32_e32 v0, 0xbfb8aa3b, v12
	v_exp_f32_e32 v0, v0
	v_add_f32_e32 v1, 1.0, v1
	v_pk_mul_f32 v[8:9], v[2:3], v[8:9]
	v_rcp_f32_e32 v2, v1
	v_mul_f32_e32 v1, 0xbfb8aa3b, v14
	v_exp_f32_e32 v22, v1
	v_add_f32_e32 v0, 1.0, v0
	v_pk_mul_f32 v[10:11], v[2:3], v[10:11]
	v_rcp_f32_e32 v2, v0
	v_lshl_add_u64 v[0:1], v[18:19], 0, v[32:33]
	v_add_f32_e32 v18, 1.0, v22
	v_mul_f32_e32 v19, v8, v9
	v_pk_mul_f32 v[8:9], v[2:3], v[12:13]
	v_rcp_f32_e32 v2, v18
	v_mul_f32_e32 v10, v10, v11
	v_mul_f32_e32 v11, v8, v9
	v_cvt_pk_bf16_f32 v10, v19, v10
	v_pk_mul_f32 v[8:9], v[2:3], v[14:15]
	v_and_b32_e32 v12, 0xffff0000, v145
	v_mul_f32_e32 v2, v8, v9
	v_cvt_pk_bf16_f32 v11, v11, v2
	global_store_dwordx2 v[0:1], v[10:11], off offset:1024
	v_mov_b64_e32 v[8:9], v[160:161]
	v_lshlrev_b32_e32 v10, 16, v145
	v_lshlrev_b32_e32 v14, 16, v142
	v_mov_b32_e32 v22, v3
	v_and_b32_e32 v16, 0xffff0000, v142
	v_or_b32_e32 v18, 64, v32
	v_mov_b32_e32 v19, v33
	v_lshl_add_u64 v[18:19], v[4:5], 0, v[18:19]
	v_lshlrev_b32_e32 v11, 16, v8
	v_and_b32_e32 v13, 0xffff0000, v8
	v_lshlrev_b32_e32 v15, 16, v9
	v_and_b32_e32 v17, 0xffff0000, v9
	v_mul_f32_e32 v2, 0xbfb8aa3b, v11
	v_mul_f32_e32 v8, 0xbfb8aa3b, v13
	v_mul_f32_e32 v9, 0xbfb8aa3b, v15
	v_mul_f32_e32 v23, 0xbfb8aa3b, v17
	v_exp_f32_e32 v2, v2
	v_exp_f32_e32 v8, v8
	v_exp_f32_e32 v9, v9
	v_exp_f32_e32 v23, v23
	v_add_f32_e32 v2, 1.0, v2
	v_add_f32_e32 v8, 1.0, v8
	v_add_f32_e32 v9, 1.0, v9
	v_add_f32_e32 v28, 1.0, v23
	v_rcp_f32_e32 v23, v2
	v_rcp_f32_e32 v25, v8
	v_rcp_f32_e32 v27, v9
	v_rcp_f32_e32 v31, v28
	v_pk_mul_f32 v[8:9], v[22:23], v[10:11]
	v_pk_mul_f32 v[10:11], v[24:25], v[12:13]
	v_pk_mul_f32 v[12:13], v[26:27], v[14:15]
	v_pk_mul_f32 v[14:15], v[30:31], v[16:17]
	v_mul_f32_e32 v2, v8, v9
	v_mul_f32_e32 v8, v10, v11
	v_mul_f32_e32 v9, v12, v13
	v_mul_f32_e32 v10, v14, v15
	v_cvt_pk_bf16_f32 v8, v2, v8
	v_cvt_pk_bf16_f32 v9, v9, v10
	global_store_dwordx2 v[0:1], v[8:9], off offset:1056
	v_mov_b64_e32 v[8:9], v[162:163]
	v_lshlrev_b32_e32 v10, 16, v139
	v_and_b32_e32 v12, 0xffff0000, v139
	v_lshlrev_b32_e32 v14, 16, v137
	v_and_b32_e32 v16, 0xffff0000, v137
	v_or_b32_e32 v18, 0x60, v32
	v_mov_b32_e32 v19, v33
	v_lshl_add_u64 v[18:19], v[4:5], 0, v[18:19]
	v_lshlrev_b32_e32 v11, 16, v8
	v_and_b32_e32 v13, 0xffff0000, v8
	v_lshlrev_b32_e32 v15, 16, v9
	v_and_b32_e32 v17, 0xffff0000, v9
	v_mul_f32_e32 v2, 0xbfb8aa3b, v11
	v_mul_f32_e32 v8, 0xbfb8aa3b, v13
	v_mul_f32_e32 v9, 0xbfb8aa3b, v15
	v_mul_f32_e32 v23, 0xbfb8aa3b, v17
	v_exp_f32_e32 v2, v2
	v_exp_f32_e32 v8, v8
	v_exp_f32_e32 v9, v9
	v_exp_f32_e32 v23, v23
	v_add_f32_e32 v2, 1.0, v2
	v_add_f32_e32 v8, 1.0, v8
	v_add_f32_e32 v9, 1.0, v9
	v_add_f32_e32 v28, 1.0, v23
	v_rcp_f32_e32 v23, v2
	v_rcp_f32_e32 v25, v8
	v_rcp_f32_e32 v27, v9
	v_rcp_f32_e32 v31, v28
	v_pk_mul_f32 v[8:9], v[22:23], v[10:11]
	v_pk_mul_f32 v[10:11], v[24:25], v[12:13]
	v_pk_mul_f32 v[12:13], v[26:27], v[14:15]
	v_pk_mul_f32 v[14:15], v[30:31], v[16:17]
	v_mul_f32_e32 v2, v8, v9
	v_mul_f32_e32 v8, v10, v11
	v_mul_f32_e32 v9, v12, v13
	v_mul_f32_e32 v10, v14, v15
	v_cvt_pk_bf16_f32 v8, v2, v8
	v_cvt_pk_bf16_f32 v9, v9, v10
	global_store_dwordx2 v[0:1], v[8:9], off offset:1088
	v_mov_b64_e32 v[8:9], v[164:165]
	v_lshlrev_b32_e32 v10, 16, v136
	v_and_b32_e32 v12, 0xffff0000, v136
	v_lshlrev_b32_e32 v14, 16, v133
	v_and_b32_e32 v16, 0xffff0000, v133
	v_or_b32_e32 v18, 0x80, v32
	v_mov_b32_e32 v19, v33
	v_lshl_add_u64 v[18:19], v[4:5], 0, v[18:19]
	v_lshlrev_b32_e32 v11, 16, v8
	v_and_b32_e32 v13, 0xffff0000, v8
	v_lshlrev_b32_e32 v15, 16, v9
	v_and_b32_e32 v17, 0xffff0000, v9
	v_mul_f32_e32 v2, 0xbfb8aa3b, v11
	v_mul_f32_e32 v8, 0xbfb8aa3b, v13
	v_mul_f32_e32 v9, 0xbfb8aa3b, v15
	v_mul_f32_e32 v23, 0xbfb8aa3b, v17
	v_exp_f32_e32 v2, v2
	v_exp_f32_e32 v8, v8
	v_exp_f32_e32 v9, v9
	v_exp_f32_e32 v23, v23
	v_add_f32_e32 v2, 1.0, v2
	v_add_f32_e32 v8, 1.0, v8
	v_add_f32_e32 v9, 1.0, v9
	v_add_f32_e32 v28, 1.0, v23
	v_rcp_f32_e32 v23, v2
	v_rcp_f32_e32 v25, v8
	v_rcp_f32_e32 v27, v9
	v_rcp_f32_e32 v31, v28
	v_pk_mul_f32 v[8:9], v[22:23], v[10:11]
	v_pk_mul_f32 v[10:11], v[24:25], v[12:13]
	v_pk_mul_f32 v[12:13], v[26:27], v[14:15]
	v_pk_mul_f32 v[14:15], v[30:31], v[16:17]
	v_mul_f32_e32 v2, v8, v9
	v_mul_f32_e32 v8, v10, v11
	v_mul_f32_e32 v9, v12, v13
	v_mul_f32_e32 v10, v14, v15
	v_cvt_pk_bf16_f32 v8, v2, v8
	v_cvt_pk_bf16_f32 v9, v9, v10
	global_store_dwordx2 v[0:1], v[8:9], off offset:1120
	v_mov_b64_e32 v[8:9], v[166:167]
	v_lshlrev_b32_e32 v10, 16, v134
	v_and_b32_e32 v12, 0xffff0000, v134
	v_lshlrev_b32_e32 v14, 16, v132
	v_and_b32_e32 v16, 0xffff0000, v132
	v_or_b32_e32 v18, 0xa0, v32
	v_mov_b32_e32 v19, v33
	v_lshl_add_u64 v[18:19], v[4:5], 0, v[18:19]
	v_lshlrev_b32_e32 v11, 16, v8
	v_and_b32_e32 v13, 0xffff0000, v8
	v_lshlrev_b32_e32 v15, 16, v9
	v_and_b32_e32 v17, 0xffff0000, v9
	v_mul_f32_e32 v2, 0xbfb8aa3b, v11
	v_mul_f32_e32 v8, 0xbfb8aa3b, v13
	v_mul_f32_e32 v9, 0xbfb8aa3b, v15
	v_mul_f32_e32 v23, 0xbfb8aa3b, v17
	v_exp_f32_e32 v2, v2
	v_exp_f32_e32 v8, v8
	v_exp_f32_e32 v9, v9
	v_exp_f32_e32 v23, v23
	v_add_f32_e32 v2, 1.0, v2
	v_add_f32_e32 v8, 1.0, v8
	v_add_f32_e32 v9, 1.0, v9
	v_add_f32_e32 v28, 1.0, v23
	v_rcp_f32_e32 v23, v2
	v_rcp_f32_e32 v25, v8
	v_rcp_f32_e32 v27, v9
	v_rcp_f32_e32 v31, v28
	v_pk_mul_f32 v[8:9], v[22:23], v[10:11]
	v_pk_mul_f32 v[10:11], v[24:25], v[12:13]
	v_pk_mul_f32 v[12:13], v[26:27], v[14:15]
	v_pk_mul_f32 v[14:15], v[30:31], v[16:17]
	v_mul_f32_e32 v2, v8, v9
	v_mul_f32_e32 v8, v10, v11
	v_mul_f32_e32 v9, v12, v13
	v_mul_f32_e32 v10, v14, v15
	v_cvt_pk_bf16_f32 v8, v2, v8
	v_cvt_pk_bf16_f32 v9, v9, v10
	global_store_dwordx2 v[0:1], v[8:9], off offset:1152
	v_mov_b64_e32 v[8:9], v[168:169]
	v_lshlrev_b32_e32 v10, 16, v130
	v_and_b32_e32 v12, 0xffff0000, v130
	v_lshlrev_b32_e32 v14, 16, v129
	v_and_b32_e32 v16, 0xffff0000, v129
	v_or_b32_e32 v18, 0xc0, v32
	v_mov_b32_e32 v19, v33
	v_lshl_add_u64 v[18:19], v[4:5], 0, v[18:19]
	v_lshlrev_b32_e32 v11, 16, v8
	v_and_b32_e32 v13, 0xffff0000, v8
	v_lshlrev_b32_e32 v15, 16, v9
	v_and_b32_e32 v17, 0xffff0000, v9
	v_mul_f32_e32 v2, 0xbfb8aa3b, v11
	v_mul_f32_e32 v8, 0xbfb8aa3b, v13
	v_mul_f32_e32 v9, 0xbfb8aa3b, v15
	v_mul_f32_e32 v23, 0xbfb8aa3b, v17
	v_exp_f32_e32 v2, v2
	v_exp_f32_e32 v8, v8
	v_exp_f32_e32 v9, v9
	v_exp_f32_e32 v23, v23
	v_add_f32_e32 v2, 1.0, v2
	v_add_f32_e32 v8, 1.0, v8
	v_add_f32_e32 v9, 1.0, v9
	v_add_f32_e32 v28, 1.0, v23
	v_rcp_f32_e32 v23, v2
	v_rcp_f32_e32 v25, v8
	v_rcp_f32_e32 v27, v9
	v_rcp_f32_e32 v31, v28
	v_pk_mul_f32 v[8:9], v[22:23], v[10:11]
	v_pk_mul_f32 v[10:11], v[24:25], v[12:13]
	v_pk_mul_f32 v[12:13], v[26:27], v[14:15]
	v_pk_mul_f32 v[14:15], v[30:31], v[16:17]
	v_mul_f32_e32 v2, v8, v9
	v_mul_f32_e32 v8, v10, v11
	v_mul_f32_e32 v9, v12, v13
	v_mul_f32_e32 v10, v14, v15
	v_cvt_pk_bf16_f32 v8, v2, v8
	v_cvt_pk_bf16_f32 v9, v9, v10
	global_store_dwordx2 v[0:1], v[8:9], off offset:1184
	v_mov_b64_e32 v[8:9], v[170:171]
	v_lshlrev_b32_e32 v10, 16, v128
	v_and_b32_e32 v12, 0xffff0000, v128
	v_lshlrev_b32_e32 v14, 16, v127
	v_and_b32_e32 v16, 0xffff0000, v127
	v_or_b32_e32 v18, 0xe0, v32
	v_mov_b32_e32 v19, v33
	v_lshl_add_u64 v[18:19], v[4:5], 0, v[18:19]
	v_lshlrev_b32_e32 v11, 16, v8
	v_and_b32_e32 v13, 0xffff0000, v8
	v_lshlrev_b32_e32 v15, 16, v9
	v_and_b32_e32 v17, 0xffff0000, v9
	v_mul_f32_e32 v2, 0xbfb8aa3b, v11
	v_mul_f32_e32 v8, 0xbfb8aa3b, v13
	v_mul_f32_e32 v9, 0xbfb8aa3b, v15
	v_mul_f32_e32 v23, 0xbfb8aa3b, v17
	v_exp_f32_e32 v2, v2
	v_exp_f32_e32 v8, v8
	v_exp_f32_e32 v9, v9
	v_exp_f32_e32 v23, v23
	v_add_f32_e32 v2, 1.0, v2
	v_add_f32_e32 v8, 1.0, v8
	v_add_f32_e32 v9, 1.0, v9
	v_add_f32_e32 v28, 1.0, v23
	v_rcp_f32_e32 v23, v2
	v_rcp_f32_e32 v25, v8
	v_rcp_f32_e32 v27, v9
	v_rcp_f32_e32 v31, v28
	v_pk_mul_f32 v[8:9], v[22:23], v[10:11]
	v_pk_mul_f32 v[10:11], v[24:25], v[12:13]
	v_pk_mul_f32 v[12:13], v[26:27], v[14:15]
	v_pk_mul_f32 v[14:15], v[30:31], v[16:17]
	v_mul_f32_e32 v2, v8, v9
	v_mul_f32_e32 v8, v10, v11
	v_mul_f32_e32 v9, v12, v13
	v_mul_f32_e32 v10, v14, v15
	v_cvt_pk_bf16_f32 v8, v2, v8
	v_cvt_pk_bf16_f32 v9, v9, v10
	global_store_dwordx2 v[0:1], v[8:9], off offset:1216
	v_mov_b64_e32 v[8:9], v[172:173]
	v_lshlrev_b32_e32 v10, 16, v126
	v_and_b32_e32 v12, 0xffff0000, v126
	v_lshlrev_b32_e32 v14, 16, v125
	v_and_b32_e32 v16, 0xffff0000, v125
	v_or_b32_e32 v18, 0x100, v32
	v_mov_b32_e32 v19, v33
	v_lshl_add_u64 v[18:19], v[4:5], 0, v[18:19]
	v_lshlrev_b32_e32 v11, 16, v8
	v_and_b32_e32 v13, 0xffff0000, v8
	v_lshlrev_b32_e32 v15, 16, v9
	v_and_b32_e32 v17, 0xffff0000, v9
	v_mul_f32_e32 v2, 0xbfb8aa3b, v11
	v_mul_f32_e32 v8, 0xbfb8aa3b, v13
	v_mul_f32_e32 v9, 0xbfb8aa3b, v15
	v_mul_f32_e32 v23, 0xbfb8aa3b, v17
	v_exp_f32_e32 v2, v2
	v_exp_f32_e32 v8, v8
	v_exp_f32_e32 v9, v9
	v_exp_f32_e32 v23, v23
	v_add_f32_e32 v2, 1.0, v2
	v_add_f32_e32 v8, 1.0, v8
	v_add_f32_e32 v9, 1.0, v9
	v_add_f32_e32 v28, 1.0, v23
	v_rcp_f32_e32 v23, v2
	v_rcp_f32_e32 v25, v8
	v_rcp_f32_e32 v27, v9
	v_rcp_f32_e32 v31, v28
	v_pk_mul_f32 v[8:9], v[22:23], v[10:11]
	v_pk_mul_f32 v[10:11], v[24:25], v[12:13]
	v_pk_mul_f32 v[12:13], v[26:27], v[14:15]
	v_pk_mul_f32 v[14:15], v[30:31], v[16:17]
	v_mul_f32_e32 v2, v8, v9
	v_mul_f32_e32 v8, v10, v11
	v_mul_f32_e32 v9, v12, v13
	v_mul_f32_e32 v10, v14, v15
	v_cvt_pk_bf16_f32 v8, v2, v8
	v_cvt_pk_bf16_f32 v9, v9, v10
	global_store_dwordx2 v[0:1], v[8:9], off offset:1248
	v_mov_b64_e32 v[8:9], v[174:175]
	v_lshlrev_b32_e32 v10, 16, v156
	v_and_b32_e32 v12, 0xffff0000, v156
	v_lshlrev_b32_e32 v14, 16, v154
	v_and_b32_e32 v16, 0xffff0000, v154
	v_or_b32_e32 v18, 0x120, v32
	v_mov_b32_e32 v19, v33
	v_lshl_add_u64 v[18:19], v[4:5], 0, v[18:19]
	v_lshlrev_b32_e32 v11, 16, v8
	v_and_b32_e32 v13, 0xffff0000, v8
	v_lshlrev_b32_e32 v15, 16, v9
	v_and_b32_e32 v17, 0xffff0000, v9
	v_mul_f32_e32 v2, 0xbfb8aa3b, v11
	v_mul_f32_e32 v8, 0xbfb8aa3b, v13
	v_mul_f32_e32 v9, 0xbfb8aa3b, v15
	v_mul_f32_e32 v23, 0xbfb8aa3b, v17
	v_exp_f32_e32 v2, v2
	v_exp_f32_e32 v8, v8
	v_exp_f32_e32 v9, v9
	v_exp_f32_e32 v23, v23
	v_add_f32_e32 v2, 1.0, v2
	v_add_f32_e32 v8, 1.0, v8
	v_add_f32_e32 v9, 1.0, v9
	v_add_f32_e32 v28, 1.0, v23
	v_rcp_f32_e32 v23, v2
	v_rcp_f32_e32 v25, v8
	v_rcp_f32_e32 v27, v9
	v_rcp_f32_e32 v31, v28
	v_pk_mul_f32 v[8:9], v[22:23], v[10:11]
	v_pk_mul_f32 v[10:11], v[24:25], v[12:13]
	v_pk_mul_f32 v[12:13], v[26:27], v[14:15]
	v_pk_mul_f32 v[14:15], v[30:31], v[16:17]
	v_mul_f32_e32 v2, v8, v9
	v_mul_f32_e32 v8, v10, v11
	v_mul_f32_e32 v9, v12, v13
	v_mul_f32_e32 v10, v14, v15
	v_cvt_pk_bf16_f32 v8, v2, v8
	v_cvt_pk_bf16_f32 v9, v9, v10
	global_store_dwordx2 v[0:1], v[8:9], off offset:1280
	v_mov_b64_e32 v[8:9], v[176:177]
	v_lshlrev_b32_e32 v10, 16, v153
	v_and_b32_e32 v12, 0xffff0000, v153
	v_lshlrev_b32_e32 v14, 16, v151
	v_and_b32_e32 v16, 0xffff0000, v151
	v_or_b32_e32 v18, 0x140, v32
	v_mov_b32_e32 v19, v33
	v_lshl_add_u64 v[18:19], v[4:5], 0, v[18:19]
	v_lshlrev_b32_e32 v11, 16, v8
	v_and_b32_e32 v13, 0xffff0000, v8
	v_lshlrev_b32_e32 v15, 16, v9
	v_and_b32_e32 v17, 0xffff0000, v9
	v_mul_f32_e32 v2, 0xbfb8aa3b, v11
	v_mul_f32_e32 v8, 0xbfb8aa3b, v13
	v_mul_f32_e32 v9, 0xbfb8aa3b, v15
	v_mul_f32_e32 v23, 0xbfb8aa3b, v17
	v_exp_f32_e32 v2, v2
	v_exp_f32_e32 v8, v8
	v_exp_f32_e32 v9, v9
	v_exp_f32_e32 v23, v23
	v_add_f32_e32 v2, 1.0, v2
	v_add_f32_e32 v8, 1.0, v8
	v_add_f32_e32 v9, 1.0, v9
	v_add_f32_e32 v28, 1.0, v23
	v_rcp_f32_e32 v23, v2
	v_rcp_f32_e32 v25, v8
	v_rcp_f32_e32 v27, v9
	v_rcp_f32_e32 v31, v28
	v_pk_mul_f32 v[8:9], v[22:23], v[10:11]
	v_pk_mul_f32 v[10:11], v[24:25], v[12:13]
	v_pk_mul_f32 v[12:13], v[26:27], v[14:15]
	v_pk_mul_f32 v[14:15], v[30:31], v[16:17]
	v_mul_f32_e32 v2, v8, v9
	v_mul_f32_e32 v8, v10, v11
	v_mul_f32_e32 v9, v12, v13
	v_mul_f32_e32 v10, v14, v15
	v_cvt_pk_bf16_f32 v8, v2, v8
	v_cvt_pk_bf16_f32 v9, v9, v10
	global_store_dwordx2 v[0:1], v[8:9], off offset:1312
	v_mov_b64_e32 v[8:9], v[178:179]
	v_lshlrev_b32_e32 v10, 16, v149
	v_and_b32_e32 v12, 0xffff0000, v149
	v_lshlrev_b32_e32 v14, 16, v147
	v_and_b32_e32 v16, 0xffff0000, v147
	v_or_b32_e32 v18, 0x160, v32
	v_mov_b32_e32 v19, v33
	v_lshl_add_u64 v[18:19], v[4:5], 0, v[18:19]
	v_lshlrev_b32_e32 v11, 16, v8
	v_and_b32_e32 v13, 0xffff0000, v8
	v_lshlrev_b32_e32 v15, 16, v9
	v_and_b32_e32 v17, 0xffff0000, v9
	v_mul_f32_e32 v2, 0xbfb8aa3b, v11
	v_mul_f32_e32 v8, 0xbfb8aa3b, v13
	v_mul_f32_e32 v9, 0xbfb8aa3b, v15
	v_mul_f32_e32 v23, 0xbfb8aa3b, v17
	v_exp_f32_e32 v2, v2
	v_exp_f32_e32 v8, v8
	v_exp_f32_e32 v9, v9
	v_exp_f32_e32 v23, v23
	v_add_f32_e32 v2, 1.0, v2
	v_add_f32_e32 v8, 1.0, v8
	v_add_f32_e32 v9, 1.0, v9
	v_add_f32_e32 v28, 1.0, v23
	v_rcp_f32_e32 v23, v2
	v_rcp_f32_e32 v25, v8
	v_rcp_f32_e32 v27, v9
	v_rcp_f32_e32 v31, v28
	v_pk_mul_f32 v[8:9], v[22:23], v[10:11]
	v_pk_mul_f32 v[10:11], v[24:25], v[12:13]
	v_pk_mul_f32 v[12:13], v[26:27], v[14:15]
	v_pk_mul_f32 v[14:15], v[30:31], v[16:17]
	v_mul_f32_e32 v2, v8, v9
	v_mul_f32_e32 v8, v10, v11
	v_mul_f32_e32 v9, v12, v13
	v_mul_f32_e32 v10, v14, v15
	v_cvt_pk_bf16_f32 v8, v2, v8
	v_cvt_pk_bf16_f32 v9, v9, v10
	global_store_dwordx2 v[0:1], v[8:9], off offset:1344
	v_mov_b64_e32 v[8:9], v[180:181]
	v_lshlrev_b32_e32 v10, 16, v146
	v_and_b32_e32 v12, 0xffff0000, v146
	v_lshlrev_b32_e32 v14, 16, v143
	v_and_b32_e32 v16, 0xffff0000, v143
	v_or_b32_e32 v18, 0x180, v32
	v_mov_b32_e32 v19, v33
	v_lshl_add_u64 v[18:19], v[4:5], 0, v[18:19]
	v_lshlrev_b32_e32 v11, 16, v8
	v_and_b32_e32 v13, 0xffff0000, v8
	v_lshlrev_b32_e32 v15, 16, v9
	v_and_b32_e32 v17, 0xffff0000, v9
	v_mul_f32_e32 v2, 0xbfb8aa3b, v11
	v_mul_f32_e32 v8, 0xbfb8aa3b, v13
	v_mul_f32_e32 v9, 0xbfb8aa3b, v15
	v_mul_f32_e32 v23, 0xbfb8aa3b, v17
	v_exp_f32_e32 v2, v2
	v_exp_f32_e32 v8, v8
	v_exp_f32_e32 v9, v9
	v_exp_f32_e32 v23, v23
	v_add_f32_e32 v2, 1.0, v2
	v_add_f32_e32 v8, 1.0, v8
	v_add_f32_e32 v9, 1.0, v9
	v_add_f32_e32 v28, 1.0, v23
	v_rcp_f32_e32 v23, v2
	v_rcp_f32_e32 v25, v8
	v_rcp_f32_e32 v27, v9
	v_rcp_f32_e32 v31, v28
	v_pk_mul_f32 v[8:9], v[22:23], v[10:11]
	v_pk_mul_f32 v[10:11], v[24:25], v[12:13]
	v_pk_mul_f32 v[12:13], v[26:27], v[14:15]
	v_pk_mul_f32 v[14:15], v[30:31], v[16:17]
	v_mul_f32_e32 v2, v8, v9
	v_mul_f32_e32 v8, v10, v11
	v_mul_f32_e32 v9, v12, v13
	v_mul_f32_e32 v10, v14, v15
	v_cvt_pk_bf16_f32 v8, v2, v8
	v_cvt_pk_bf16_f32 v9, v9, v10
	global_store_dwordx2 v[0:1], v[8:9], off offset:1376
	v_mov_b64_e32 v[8:9], v[182:183]
	v_lshlrev_b32_e32 v10, 16, v144
	v_and_b32_e32 v12, 0xffff0000, v144
	v_lshlrev_b32_e32 v14, 16, v141
	v_and_b32_e32 v16, 0xffff0000, v141
	v_or_b32_e32 v18, 0x1a0, v32
	v_mov_b32_e32 v19, v33
	v_lshl_add_u64 v[18:19], v[4:5], 0, v[18:19]
	v_lshlrev_b32_e32 v11, 16, v8
	v_and_b32_e32 v13, 0xffff0000, v8
	v_lshlrev_b32_e32 v15, 16, v9
	v_and_b32_e32 v17, 0xffff0000, v9
	v_mul_f32_e32 v2, 0xbfb8aa3b, v11
	v_mul_f32_e32 v8, 0xbfb8aa3b, v13
	v_mul_f32_e32 v9, 0xbfb8aa3b, v15
	v_mul_f32_e32 v23, 0xbfb8aa3b, v17
	v_exp_f32_e32 v2, v2
	v_exp_f32_e32 v8, v8
	v_exp_f32_e32 v9, v9
	v_exp_f32_e32 v23, v23
	v_add_f32_e32 v2, 1.0, v2
	v_add_f32_e32 v8, 1.0, v8
	v_add_f32_e32 v9, 1.0, v9
	v_add_f32_e32 v28, 1.0, v23
	v_rcp_f32_e32 v23, v2
	v_rcp_f32_e32 v25, v8
	v_rcp_f32_e32 v27, v9
	v_rcp_f32_e32 v31, v28
	v_pk_mul_f32 v[8:9], v[22:23], v[10:11]
	v_pk_mul_f32 v[10:11], v[24:25], v[12:13]
	v_pk_mul_f32 v[12:13], v[26:27], v[14:15]
	v_pk_mul_f32 v[14:15], v[30:31], v[16:17]
	v_mul_f32_e32 v2, v8, v9
	v_mul_f32_e32 v8, v10, v11
	v_mul_f32_e32 v9, v12, v13
	v_mul_f32_e32 v10, v14, v15
	v_cvt_pk_bf16_f32 v8, v2, v8
	v_cvt_pk_bf16_f32 v9, v9, v10
	global_store_dwordx2 v[0:1], v[8:9], off offset:1408
	v_mov_b64_e32 v[8:9], v[184:185]
	v_lshlrev_b32_e32 v10, 16, v140
	v_and_b32_e32 v12, 0xffff0000, v140
	v_lshlrev_b32_e32 v14, 16, v138
	v_and_b32_e32 v16, 0xffff0000, v138
	v_or_b32_e32 v18, 0x1c0, v32
	v_mov_b32_e32 v19, v33
	v_lshl_add_u64 v[18:19], v[4:5], 0, v[18:19]
	v_lshlrev_b32_e32 v11, 16, v8
	v_and_b32_e32 v13, 0xffff0000, v8
	v_lshlrev_b32_e32 v15, 16, v9
	v_and_b32_e32 v17, 0xffff0000, v9
	v_mul_f32_e32 v2, 0xbfb8aa3b, v11
	v_mul_f32_e32 v8, 0xbfb8aa3b, v13
	v_mul_f32_e32 v9, 0xbfb8aa3b, v15
	v_mul_f32_e32 v23, 0xbfb8aa3b, v17
	v_exp_f32_e32 v2, v2
	v_exp_f32_e32 v8, v8
	v_exp_f32_e32 v9, v9
	v_exp_f32_e32 v23, v23
	v_add_f32_e32 v2, 1.0, v2
	v_add_f32_e32 v8, 1.0, v8
	v_add_f32_e32 v9, 1.0, v9
	v_add_f32_e32 v28, 1.0, v23
	v_rcp_f32_e32 v23, v2
	v_rcp_f32_e32 v25, v8
	v_rcp_f32_e32 v27, v9
	v_rcp_f32_e32 v31, v28
	v_pk_mul_f32 v[8:9], v[22:23], v[10:11]
	v_pk_mul_f32 v[10:11], v[24:25], v[12:13]
	v_pk_mul_f32 v[12:13], v[26:27], v[14:15]
	v_pk_mul_f32 v[14:15], v[30:31], v[16:17]
	v_mul_f32_e32 v2, v8, v9
	v_mul_f32_e32 v8, v10, v11
	v_mul_f32_e32 v9, v12, v13
	v_mul_f32_e32 v10, v14, v15
	v_cvt_pk_bf16_f32 v8, v2, v8
	v_cvt_pk_bf16_f32 v9, v9, v10
	global_store_dwordx2 v[0:1], v[8:9], off offset:1440
	v_mov_b64_e32 v[8:9], v[186:187]
	v_lshlrev_b32_e32 v10, 16, v135
	v_and_b32_e32 v12, 0xffff0000, v135
	v_lshlrev_b32_e32 v14, 16, v131
	v_and_b32_e32 v16, 0xffff0000, v131
	v_or_b32_e32 v18, 0x1e0, v32
	v_mov_b32_e32 v19, v33
	v_lshl_add_u64 v[18:19], v[4:5], 0, v[18:19]
	v_lshlrev_b32_e32 v11, 16, v8
	v_and_b32_e32 v13, 0xffff0000, v8
	v_lshlrev_b32_e32 v15, 16, v9
	v_and_b32_e32 v17, 0xffff0000, v9
	v_mul_f32_e32 v2, 0xbfb8aa3b, v11
	v_mul_f32_e32 v8, 0xbfb8aa3b, v13
	v_mul_f32_e32 v9, 0xbfb8aa3b, v15
	v_mul_f32_e32 v23, 0xbfb8aa3b, v17
	v_exp_f32_e32 v2, v2
	v_exp_f32_e32 v8, v8
	v_exp_f32_e32 v9, v9
	v_exp_f32_e32 v23, v23
	v_add_f32_e32 v2, 1.0, v2
	v_add_f32_e32 v8, 1.0, v8
	v_add_f32_e32 v9, 1.0, v9
	v_add_f32_e32 v28, 1.0, v23
	v_rcp_f32_e32 v23, v2
	v_rcp_f32_e32 v25, v8
	v_rcp_f32_e32 v27, v9
	v_rcp_f32_e32 v31, v28
	v_pk_mul_f32 v[8:9], v[22:23], v[10:11]
	v_pk_mul_f32 v[10:11], v[24:25], v[12:13]
	v_pk_mul_f32 v[12:13], v[26:27], v[14:15]
	v_pk_mul_f32 v[14:15], v[30:31], v[16:17]
	v_mul_f32_e32 v2, v8, v9
	v_mul_f32_e32 v8, v10, v11
	v_mul_f32_e32 v9, v12, v13
	v_mul_f32_e32 v10, v14, v15
	v_cvt_pk_bf16_f32 v8, v2, v8
	v_cvt_pk_bf16_f32 v9, v9, v10
	global_store_dwordx2 v[0:1], v[8:9], off offset:1472
	v_mov_b64_e32 v[8:9], v[188:189]
	v_lshlrev_b32_e32 v10, 16, v122
	v_and_b32_e32 v12, 0xffff0000, v122
	v_lshlrev_b32_e32 v14, 16, v120
	v_and_b32_e32 v16, 0xffff0000, v120
	v_or_b32_e32 v18, 0x200, v32
	v_mov_b32_e32 v19, v33
	v_lshl_add_u64 v[18:19], v[4:5], 0, v[18:19]
	v_lshlrev_b32_e32 v11, 16, v8
	v_and_b32_e32 v13, 0xffff0000, v8
	v_lshlrev_b32_e32 v15, 16, v9
	v_and_b32_e32 v17, 0xffff0000, v9
	v_mul_f32_e32 v2, 0xbfb8aa3b, v11
	v_mul_f32_e32 v8, 0xbfb8aa3b, v13
	v_mul_f32_e32 v9, 0xbfb8aa3b, v15
	v_mul_f32_e32 v23, 0xbfb8aa3b, v17
	v_exp_f32_e32 v2, v2
	v_exp_f32_e32 v8, v8
	v_exp_f32_e32 v9, v9
	v_exp_f32_e32 v23, v23
	v_add_f32_e32 v2, 1.0, v2
	v_add_f32_e32 v8, 1.0, v8
	v_add_f32_e32 v9, 1.0, v9
	v_add_f32_e32 v28, 1.0, v23
	v_rcp_f32_e32 v23, v2
	v_rcp_f32_e32 v25, v8
	v_rcp_f32_e32 v27, v9
	v_rcp_f32_e32 v31, v28
	v_pk_mul_f32 v[8:9], v[22:23], v[10:11]
	v_pk_mul_f32 v[10:11], v[24:25], v[12:13]
	v_pk_mul_f32 v[12:13], v[26:27], v[14:15]
	v_pk_mul_f32 v[14:15], v[30:31], v[16:17]
	v_mul_f32_e32 v2, v8, v9
	v_mul_f32_e32 v8, v10, v11
	v_mul_f32_e32 v9, v12, v13
	v_mul_f32_e32 v10, v14, v15
	v_cvt_pk_bf16_f32 v8, v2, v8
	v_cvt_pk_bf16_f32 v9, v9, v10
	global_store_dwordx2 v[0:1], v[8:9], off offset:1504
	v_mov_b64_e32 v[8:9], v[190:191]
	v_lshlrev_b32_e32 v10, 16, v159
	v_and_b32_e32 v12, 0xffff0000, v159
	v_lshlrev_b32_e32 v14, 16, v158
	v_and_b32_e32 v16, 0xffff0000, v158
	v_or_b32_e32 v18, 0x220, v32
	v_mov_b32_e32 v19, v33
	v_lshl_add_u64 v[18:19], v[4:5], 0, v[18:19]
	v_lshlrev_b32_e32 v11, 16, v8
	v_and_b32_e32 v13, 0xffff0000, v8
	v_lshlrev_b32_e32 v15, 16, v9
	v_and_b32_e32 v17, 0xffff0000, v9
	v_mul_f32_e32 v2, 0xbfb8aa3b, v11
	v_mul_f32_e32 v8, 0xbfb8aa3b, v13
	v_mul_f32_e32 v9, 0xbfb8aa3b, v15
	v_mul_f32_e32 v23, 0xbfb8aa3b, v17
	v_exp_f32_e32 v2, v2
	v_exp_f32_e32 v8, v8
	v_exp_f32_e32 v9, v9
	v_exp_f32_e32 v23, v23
	v_add_f32_e32 v2, 1.0, v2
	v_add_f32_e32 v8, 1.0, v8
	v_add_f32_e32 v9, 1.0, v9
	v_add_f32_e32 v28, 1.0, v23
	v_rcp_f32_e32 v23, v2
	v_rcp_f32_e32 v25, v8
	v_rcp_f32_e32 v27, v9
	v_rcp_f32_e32 v31, v28
	v_pk_mul_f32 v[8:9], v[22:23], v[10:11]
	v_pk_mul_f32 v[10:11], v[24:25], v[12:13]
	v_pk_mul_f32 v[12:13], v[26:27], v[14:15]
	v_pk_mul_f32 v[14:15], v[30:31], v[16:17]
	v_mul_f32_e32 v2, v8, v9
	v_mul_f32_e32 v8, v10, v11
	v_mul_f32_e32 v9, v12, v13
	v_mul_f32_e32 v10, v14, v15
	v_cvt_pk_bf16_f32 v8, v2, v8
	v_cvt_pk_bf16_f32 v9, v9, v10
	global_store_dwordx2 v[0:1], v[8:9], off offset:1536
	v_mov_b64_e32 v[8:9], v[192:193]
	v_lshlrev_b32_e32 v10, 16, v123
	v_and_b32_e32 v12, 0xffff0000, v123
	v_lshlrev_b32_e32 v14, 16, v121
	v_and_b32_e32 v16, 0xffff0000, v121
	v_or_b32_e32 v18, 0x240, v32
	v_mov_b32_e32 v19, v33
	v_lshl_add_u64 v[18:19], v[4:5], 0, v[18:19]
	v_lshlrev_b32_e32 v11, 16, v8
	v_and_b32_e32 v13, 0xffff0000, v8
	v_lshlrev_b32_e32 v15, 16, v9
	v_and_b32_e32 v17, 0xffff0000, v9
	v_mul_f32_e32 v2, 0xbfb8aa3b, v11
	v_mul_f32_e32 v8, 0xbfb8aa3b, v13
	v_mul_f32_e32 v9, 0xbfb8aa3b, v15
	v_mul_f32_e32 v23, 0xbfb8aa3b, v17
	v_exp_f32_e32 v2, v2
	v_exp_f32_e32 v8, v8
	v_exp_f32_e32 v9, v9
	v_exp_f32_e32 v23, v23
	v_add_f32_e32 v2, 1.0, v2
	v_add_f32_e32 v8, 1.0, v8
	v_add_f32_e32 v9, 1.0, v9
	v_add_f32_e32 v28, 1.0, v23
	v_rcp_f32_e32 v23, v2
	v_rcp_f32_e32 v25, v8
	v_rcp_f32_e32 v27, v9
	v_rcp_f32_e32 v31, v28
	v_pk_mul_f32 v[8:9], v[22:23], v[10:11]
	v_pk_mul_f32 v[10:11], v[24:25], v[12:13]
	v_pk_mul_f32 v[12:13], v[26:27], v[14:15]
	v_pk_mul_f32 v[14:15], v[30:31], v[16:17]
	v_mul_f32_e32 v2, v8, v9
	v_mul_f32_e32 v8, v10, v11
	v_mul_f32_e32 v9, v12, v13
	v_mul_f32_e32 v10, v14, v15
	v_cvt_pk_bf16_f32 v8, v2, v8
	v_cvt_pk_bf16_f32 v9, v9, v10
	global_store_dwordx2 v[0:1], v[8:9], off offset:1568
	v_mov_b64_e32 v[8:9], v[194:195]
	v_lshlrev_b32_e32 v10, 16, v119
	v_and_b32_e32 v12, 0xffff0000, v119
	v_lshlrev_b32_e32 v14, 16, v118
	v_and_b32_e32 v16, 0xffff0000, v118
	v_or_b32_e32 v18, 0x260, v32
	v_mov_b32_e32 v19, v33
	v_lshl_add_u64 v[18:19], v[4:5], 0, v[18:19]
	v_lshlrev_b32_e32 v11, 16, v8
	v_and_b32_e32 v13, 0xffff0000, v8
	v_lshlrev_b32_e32 v15, 16, v9
	v_and_b32_e32 v17, 0xffff0000, v9
	v_mul_f32_e32 v2, 0xbfb8aa3b, v11
	v_mul_f32_e32 v8, 0xbfb8aa3b, v13
	v_mul_f32_e32 v9, 0xbfb8aa3b, v15
	v_mul_f32_e32 v23, 0xbfb8aa3b, v17
	v_exp_f32_e32 v2, v2
	v_exp_f32_e32 v8, v8
	v_exp_f32_e32 v9, v9
	v_exp_f32_e32 v23, v23
	v_add_f32_e32 v2, 1.0, v2
	v_add_f32_e32 v8, 1.0, v8
	v_add_f32_e32 v9, 1.0, v9
	v_add_f32_e32 v28, 1.0, v23
	v_rcp_f32_e32 v23, v2
	v_rcp_f32_e32 v25, v8
	v_rcp_f32_e32 v27, v9
	v_rcp_f32_e32 v31, v28
	v_pk_mul_f32 v[8:9], v[22:23], v[10:11]
	v_pk_mul_f32 v[10:11], v[24:25], v[12:13]
	v_pk_mul_f32 v[12:13], v[26:27], v[14:15]
	v_pk_mul_f32 v[14:15], v[30:31], v[16:17]
	v_mul_f32_e32 v2, v8, v9
	v_mul_f32_e32 v8, v10, v11
	v_mul_f32_e32 v9, v12, v13
	v_mul_f32_e32 v10, v14, v15
	v_cvt_pk_bf16_f32 v8, v2, v8
	v_cvt_pk_bf16_f32 v9, v9, v10
	global_store_dwordx2 v[0:1], v[8:9], off offset:1600
	v_mov_b64_e32 v[8:9], v[196:197]
	v_lshlrev_b32_e32 v10, 16, v117
	v_and_b32_e32 v12, 0xffff0000, v117
	v_lshlrev_b32_e32 v14, 16, v115
	v_and_b32_e32 v16, 0xffff0000, v115
	v_or_b32_e32 v18, 0x280, v32
	v_mov_b32_e32 v19, v33
	v_lshl_add_u64 v[18:19], v[4:5], 0, v[18:19]
	v_lshlrev_b32_e32 v11, 16, v8
	v_and_b32_e32 v13, 0xffff0000, v8
	v_lshlrev_b32_e32 v15, 16, v9
	v_and_b32_e32 v17, 0xffff0000, v9
	v_mul_f32_e32 v2, 0xbfb8aa3b, v11
	v_mul_f32_e32 v8, 0xbfb8aa3b, v13
	v_mul_f32_e32 v9, 0xbfb8aa3b, v15
	v_mul_f32_e32 v23, 0xbfb8aa3b, v17
	v_exp_f32_e32 v2, v2
	v_exp_f32_e32 v8, v8
	v_exp_f32_e32 v9, v9
	v_exp_f32_e32 v23, v23
	v_add_f32_e32 v2, 1.0, v2
	v_add_f32_e32 v8, 1.0, v8
	v_add_f32_e32 v9, 1.0, v9
	v_add_f32_e32 v28, 1.0, v23
	v_rcp_f32_e32 v23, v2
	v_rcp_f32_e32 v25, v8
	v_rcp_f32_e32 v27, v9
	v_rcp_f32_e32 v31, v28
	v_pk_mul_f32 v[8:9], v[22:23], v[10:11]
	v_pk_mul_f32 v[10:11], v[24:25], v[12:13]
	v_pk_mul_f32 v[12:13], v[26:27], v[14:15]
	v_pk_mul_f32 v[14:15], v[30:31], v[16:17]
	v_mul_f32_e32 v2, v8, v9
	v_mul_f32_e32 v8, v10, v11
	v_mul_f32_e32 v9, v12, v13
	v_mul_f32_e32 v10, v14, v15
	v_cvt_pk_bf16_f32 v8, v2, v8
	v_cvt_pk_bf16_f32 v9, v9, v10
	global_store_dwordx2 v[0:1], v[8:9], off offset:1632
	v_mov_b64_e32 v[8:9], v[198:199]
	v_lshlrev_b32_e32 v10, 16, v116
	v_and_b32_e32 v12, 0xffff0000, v116
	v_lshlrev_b32_e32 v14, 16, v114
	v_and_b32_e32 v16, 0xffff0000, v114
	v_or_b32_e32 v18, 0x2a0, v32
	v_mov_b32_e32 v19, v33
	v_lshl_add_u64 v[18:19], v[4:5], 0, v[18:19]
	v_lshlrev_b32_e32 v11, 16, v8
	v_and_b32_e32 v13, 0xffff0000, v8
	v_lshlrev_b32_e32 v15, 16, v9
	v_and_b32_e32 v17, 0xffff0000, v9
	v_mul_f32_e32 v2, 0xbfb8aa3b, v11
	v_mul_f32_e32 v8, 0xbfb8aa3b, v13
	v_mul_f32_e32 v9, 0xbfb8aa3b, v15
	v_mul_f32_e32 v23, 0xbfb8aa3b, v17
	v_exp_f32_e32 v2, v2
	v_exp_f32_e32 v8, v8
	v_exp_f32_e32 v9, v9
	v_exp_f32_e32 v23, v23
	v_add_f32_e32 v2, 1.0, v2
	v_add_f32_e32 v8, 1.0, v8
	v_add_f32_e32 v9, 1.0, v9
	v_add_f32_e32 v28, 1.0, v23
	v_rcp_f32_e32 v23, v2
	v_rcp_f32_e32 v25, v8
	v_rcp_f32_e32 v27, v9
	v_rcp_f32_e32 v31, v28
	v_pk_mul_f32 v[8:9], v[22:23], v[10:11]
	v_pk_mul_f32 v[10:11], v[24:25], v[12:13]
	v_pk_mul_f32 v[12:13], v[26:27], v[14:15]
	v_pk_mul_f32 v[14:15], v[30:31], v[16:17]
	v_mul_f32_e32 v2, v8, v9
	v_mul_f32_e32 v8, v10, v11
	v_mul_f32_e32 v9, v12, v13
	v_mul_f32_e32 v10, v14, v15
	v_cvt_pk_bf16_f32 v8, v2, v8
	v_cvt_pk_bf16_f32 v9, v9, v10
	global_store_dwordx2 v[0:1], v[8:9], off offset:1664
	v_mov_b64_e32 v[8:9], v[200:201]
	v_lshlrev_b32_e32 v10, 16, v113
	v_and_b32_e32 v12, 0xffff0000, v113
	v_lshlrev_b32_e32 v14, 16, v112
	v_and_b32_e32 v16, 0xffff0000, v112
	v_or_b32_e32 v18, 0x2c0, v32
	v_mov_b32_e32 v19, v33
	v_lshl_add_u64 v[18:19], v[4:5], 0, v[18:19]
	v_lshlrev_b32_e32 v11, 16, v8
	v_and_b32_e32 v13, 0xffff0000, v8
	v_lshlrev_b32_e32 v15, 16, v9
	v_and_b32_e32 v17, 0xffff0000, v9
	v_mul_f32_e32 v2, 0xbfb8aa3b, v11
	v_mul_f32_e32 v8, 0xbfb8aa3b, v13
	v_mul_f32_e32 v9, 0xbfb8aa3b, v15
	v_mul_f32_e32 v23, 0xbfb8aa3b, v17
	v_exp_f32_e32 v2, v2
	v_exp_f32_e32 v8, v8
	v_exp_f32_e32 v9, v9
	v_exp_f32_e32 v23, v23
	v_add_f32_e32 v2, 1.0, v2
	v_add_f32_e32 v8, 1.0, v8
	v_add_f32_e32 v9, 1.0, v9
	v_add_f32_e32 v28, 1.0, v23
	v_rcp_f32_e32 v23, v2
	v_rcp_f32_e32 v25, v8
	v_rcp_f32_e32 v27, v9
	v_rcp_f32_e32 v31, v28
	v_pk_mul_f32 v[8:9], v[22:23], v[10:11]
	v_pk_mul_f32 v[10:11], v[24:25], v[12:13]
	v_pk_mul_f32 v[12:13], v[26:27], v[14:15]
	v_pk_mul_f32 v[14:15], v[30:31], v[16:17]
	v_mul_f32_e32 v2, v8, v9
	v_mul_f32_e32 v8, v10, v11
	v_mul_f32_e32 v9, v12, v13
	v_mul_f32_e32 v10, v14, v15
	v_cvt_pk_bf16_f32 v8, v2, v8
	v_cvt_pk_bf16_f32 v9, v9, v10
	global_store_dwordx2 v[0:1], v[8:9], off offset:1696
	v_mov_b64_e32 v[8:9], v[202:203]
	v_lshlrev_b32_e32 v10, 16, v111
	v_and_b32_e32 v12, 0xffff0000, v111
	v_lshlrev_b32_e32 v14, 16, v110
	v_and_b32_e32 v16, 0xffff0000, v110
	v_or_b32_e32 v18, 0x2e0, v32
	v_mov_b32_e32 v19, v33
	v_lshl_add_u64 v[18:19], v[4:5], 0, v[18:19]
	v_lshlrev_b32_e32 v11, 16, v8
	v_and_b32_e32 v13, 0xffff0000, v8
	v_lshlrev_b32_e32 v15, 16, v9
	v_and_b32_e32 v17, 0xffff0000, v9
	v_mul_f32_e32 v2, 0xbfb8aa3b, v11
	v_mul_f32_e32 v8, 0xbfb8aa3b, v13
	v_mul_f32_e32 v9, 0xbfb8aa3b, v15
	v_mul_f32_e32 v23, 0xbfb8aa3b, v17
	v_exp_f32_e32 v2, v2
	v_exp_f32_e32 v8, v8
	v_exp_f32_e32 v9, v9
	v_exp_f32_e32 v23, v23
	v_add_f32_e32 v2, 1.0, v2
	v_add_f32_e32 v8, 1.0, v8
	v_add_f32_e32 v9, 1.0, v9
	v_add_f32_e32 v28, 1.0, v23
	v_rcp_f32_e32 v23, v2
	v_rcp_f32_e32 v25, v8
	v_rcp_f32_e32 v27, v9
	v_rcp_f32_e32 v31, v28
	v_pk_mul_f32 v[8:9], v[22:23], v[10:11]
	v_pk_mul_f32 v[10:11], v[24:25], v[12:13]
	v_pk_mul_f32 v[12:13], v[26:27], v[14:15]
	v_pk_mul_f32 v[14:15], v[30:31], v[16:17]
	v_mul_f32_e32 v2, v8, v9
	v_mul_f32_e32 v8, v10, v11
	v_mul_f32_e32 v9, v12, v13
	v_mul_f32_e32 v10, v14, v15
	v_cvt_pk_bf16_f32 v8, v2, v8
	v_cvt_pk_bf16_f32 v9, v9, v10
	global_store_dwordx2 v[0:1], v[8:9], off offset:1728
	v_mov_b64_e32 v[8:9], v[204:205]
	v_lshlrev_b32_e32 v14, 16, v29
	v_and_b32_e32 v16, 0xffff0000, v29
	v_lshlrev_b32_e32 v10, 16, v106
	v_and_b32_e32 v12, 0xffff0000, v106
	v_mov_b32_e32 v28, v3
	v_or_b32_e32 v18, 0x300, v32
	v_mov_b32_e32 v19, v33
	v_lshl_add_u64 v[18:19], v[4:5], 0, v[18:19]
	v_lshlrev_b32_e32 v11, 16, v8
	v_and_b32_e32 v13, 0xffff0000, v8
	v_lshlrev_b32_e32 v15, 16, v9
	v_and_b32_e32 v17, 0xffff0000, v9
	v_mul_f32_e32 v2, 0xbfb8aa3b, v11
	v_mul_f32_e32 v8, 0xbfb8aa3b, v13
	v_mul_f32_e32 v9, 0xbfb8aa3b, v15
	v_mul_f32_e32 v23, 0xbfb8aa3b, v17
	v_exp_f32_e32 v2, v2
	v_exp_f32_e32 v8, v8
	v_exp_f32_e32 v9, v9
	v_exp_f32_e32 v23, v23
	v_add_f32_e32 v2, 1.0, v2
	v_add_f32_e32 v8, 1.0, v8
	v_add_f32_e32 v9, 1.0, v9
	v_add_f32_e32 v29, 1.0, v23
	v_rcp_f32_e32 v23, v2
	v_rcp_f32_e32 v25, v8
	v_rcp_f32_e32 v27, v9
	v_rcp_f32_e32 v29, v29
	v_pk_mul_f32 v[8:9], v[22:23], v[10:11]
	v_pk_mul_f32 v[10:11], v[24:25], v[12:13]
	v_pk_mul_f32 v[12:13], v[26:27], v[14:15]
	v_pk_mul_f32 v[14:15], v[28:29], v[16:17]
	v_mul_f32_e32 v2, v8, v9
	v_mul_f32_e32 v8, v10, v11
	v_mul_f32_e32 v9, v12, v13
	v_mul_f32_e32 v10, v14, v15
	v_cvt_pk_bf16_f32 v8, v2, v8
	v_cvt_pk_bf16_f32 v9, v9, v10
	global_store_dwordx2 v[0:1], v[8:9], off offset:1760
	v_mov_b64_e32 v[8:9], v[206:207]
	v_lshlrev_b32_e32 v10, 16, v77
	v_and_b32_e32 v12, 0xffff0000, v77
	v_lshlrev_b32_e32 v14, 16, v76
	v_and_b32_e32 v16, 0xffff0000, v76
	v_or_b32_e32 v18, 0x320, v32
	v_mov_b32_e32 v19, v33
	v_lshl_add_u64 v[18:19], v[4:5], 0, v[18:19]
	v_lshlrev_b32_e32 v11, 16, v8
	v_and_b32_e32 v13, 0xffff0000, v8
	v_lshlrev_b32_e32 v15, 16, v9
	v_and_b32_e32 v17, 0xffff0000, v9
	v_mul_f32_e32 v2, 0xbfb8aa3b, v11
	v_mul_f32_e32 v8, 0xbfb8aa3b, v13
	v_mul_f32_e32 v9, 0xbfb8aa3b, v15
	v_mul_f32_e32 v23, 0xbfb8aa3b, v17
	v_exp_f32_e32 v2, v2
	v_exp_f32_e32 v8, v8
	v_exp_f32_e32 v9, v9
	v_exp_f32_e32 v23, v23
	v_add_f32_e32 v2, 1.0, v2
	v_add_f32_e32 v8, 1.0, v8
	v_add_f32_e32 v9, 1.0, v9
	v_add_f32_e32 v29, 1.0, v23
	v_rcp_f32_e32 v23, v2
	v_rcp_f32_e32 v25, v8
	v_rcp_f32_e32 v27, v9
	v_rcp_f32_e32 v29, v29
	v_pk_mul_f32 v[8:9], v[22:23], v[10:11]
	v_pk_mul_f32 v[10:11], v[24:25], v[12:13]
	v_pk_mul_f32 v[12:13], v[26:27], v[14:15]
	v_pk_mul_f32 v[14:15], v[28:29], v[16:17]
	v_mul_f32_e32 v2, v8, v9
	v_mul_f32_e32 v8, v10, v11
	v_mul_f32_e32 v9, v12, v13
	v_mul_f32_e32 v10, v14, v15
	v_cvt_pk_bf16_f32 v8, v2, v8
	v_cvt_pk_bf16_f32 v9, v9, v10
	global_store_dwordx2 v[0:1], v[8:9], off offset:1792
	v_mov_b64_e32 v[8:9], v[208:209]
	v_lshlrev_b32_e32 v10, 16, v75
	v_and_b32_e32 v12, 0xffff0000, v75
	v_lshlrev_b32_e32 v14, 16, v74
	v_and_b32_e32 v16, 0xffff0000, v74
	v_or_b32_e32 v18, 0x340, v32
	v_mov_b32_e32 v19, v33
	v_lshl_add_u64 v[18:19], v[4:5], 0, v[18:19]
	v_lshlrev_b32_e32 v11, 16, v8
	v_and_b32_e32 v13, 0xffff0000, v8
	v_lshlrev_b32_e32 v15, 16, v9
	v_and_b32_e32 v17, 0xffff0000, v9
	v_mul_f32_e32 v2, 0xbfb8aa3b, v11
	v_mul_f32_e32 v8, 0xbfb8aa3b, v13
	v_mul_f32_e32 v9, 0xbfb8aa3b, v15
	v_mul_f32_e32 v23, 0xbfb8aa3b, v17
	v_exp_f32_e32 v2, v2
	v_exp_f32_e32 v8, v8
	v_exp_f32_e32 v9, v9
	v_exp_f32_e32 v23, v23
	v_add_f32_e32 v2, 1.0, v2
	v_add_f32_e32 v8, 1.0, v8
	v_add_f32_e32 v9, 1.0, v9
	v_add_f32_e32 v29, 1.0, v23
	v_rcp_f32_e32 v23, v2
	v_rcp_f32_e32 v25, v8
	v_rcp_f32_e32 v27, v9
	v_rcp_f32_e32 v29, v29
	v_pk_mul_f32 v[8:9], v[22:23], v[10:11]
	v_pk_mul_f32 v[10:11], v[24:25], v[12:13]
	v_pk_mul_f32 v[12:13], v[26:27], v[14:15]
	v_pk_mul_f32 v[14:15], v[28:29], v[16:17]
	v_mul_f32_e32 v2, v8, v9
	v_mul_f32_e32 v8, v10, v11
	v_mul_f32_e32 v9, v12, v13
	v_mul_f32_e32 v10, v14, v15
	v_cvt_pk_bf16_f32 v8, v2, v8
	v_cvt_pk_bf16_f32 v9, v9, v10
	global_store_dwordx2 v[0:1], v[8:9], off offset:1824
	v_mov_b64_e32 v[8:9], v[210:211]
	v_lshlrev_b32_e32 v10, 16, v73
	v_and_b32_e32 v12, 0xffff0000, v73
	v_lshlrev_b32_e32 v14, 16, v72
	v_and_b32_e32 v16, 0xffff0000, v72
	v_or_b32_e32 v18, 0x360, v32
	v_mov_b32_e32 v19, v33
	v_lshl_add_u64 v[18:19], v[4:5], 0, v[18:19]
	v_lshlrev_b32_e32 v11, 16, v8
	v_and_b32_e32 v13, 0xffff0000, v8
	v_lshlrev_b32_e32 v15, 16, v9
	v_and_b32_e32 v17, 0xffff0000, v9
	v_mul_f32_e32 v2, 0xbfb8aa3b, v11
	v_mul_f32_e32 v8, 0xbfb8aa3b, v13
	v_mul_f32_e32 v9, 0xbfb8aa3b, v15
	v_mul_f32_e32 v23, 0xbfb8aa3b, v17
	v_exp_f32_e32 v2, v2
	v_exp_f32_e32 v8, v8
	v_exp_f32_e32 v9, v9
	v_exp_f32_e32 v23, v23
	v_add_f32_e32 v2, 1.0, v2
	v_add_f32_e32 v8, 1.0, v8
	v_add_f32_e32 v9, 1.0, v9
	v_add_f32_e32 v29, 1.0, v23
	v_rcp_f32_e32 v23, v2
	v_rcp_f32_e32 v25, v8
	v_rcp_f32_e32 v27, v9
	v_rcp_f32_e32 v29, v29
	v_pk_mul_f32 v[8:9], v[22:23], v[10:11]
	v_pk_mul_f32 v[10:11], v[24:25], v[12:13]
	v_pk_mul_f32 v[12:13], v[26:27], v[14:15]
	v_pk_mul_f32 v[14:15], v[28:29], v[16:17]
	v_mul_f32_e32 v2, v8, v9
	v_mul_f32_e32 v8, v10, v11
	v_mul_f32_e32 v9, v12, v13
	v_mul_f32_e32 v10, v14, v15
	v_cvt_pk_bf16_f32 v8, v2, v8
	v_cvt_pk_bf16_f32 v9, v9, v10
	global_store_dwordx2 v[0:1], v[8:9], off offset:1856
	v_mov_b64_e32 v[8:9], v[212:213]
	v_lshlrev_b32_e32 v10, 16, v71
	v_and_b32_e32 v12, 0xffff0000, v71
	v_lshlrev_b32_e32 v14, 16, v69
	v_and_b32_e32 v16, 0xffff0000, v69
	v_or_b32_e32 v18, 0x380, v32
	v_mov_b32_e32 v19, v33
	v_lshl_add_u64 v[18:19], v[4:5], 0, v[18:19]
	v_lshlrev_b32_e32 v11, 16, v8
	v_and_b32_e32 v13, 0xffff0000, v8
	v_lshlrev_b32_e32 v15, 16, v9
	v_and_b32_e32 v17, 0xffff0000, v9
	v_mul_f32_e32 v2, 0xbfb8aa3b, v11
	v_mul_f32_e32 v8, 0xbfb8aa3b, v13
	v_mul_f32_e32 v9, 0xbfb8aa3b, v15
	v_mul_f32_e32 v23, 0xbfb8aa3b, v17
	v_exp_f32_e32 v2, v2
	v_exp_f32_e32 v8, v8
	v_exp_f32_e32 v9, v9
	v_exp_f32_e32 v23, v23
	v_add_f32_e32 v2, 1.0, v2
	v_add_f32_e32 v8, 1.0, v8
	v_add_f32_e32 v9, 1.0, v9
	v_add_f32_e32 v29, 1.0, v23
	v_rcp_f32_e32 v23, v2
	v_rcp_f32_e32 v25, v8
	v_rcp_f32_e32 v27, v9
	v_rcp_f32_e32 v29, v29
	v_pk_mul_f32 v[8:9], v[22:23], v[10:11]
	v_pk_mul_f32 v[10:11], v[24:25], v[12:13]
	v_pk_mul_f32 v[12:13], v[26:27], v[14:15]
	v_pk_mul_f32 v[14:15], v[28:29], v[16:17]
	v_mul_f32_e32 v2, v8, v9
	v_mul_f32_e32 v8, v10, v11
	v_mul_f32_e32 v9, v12, v13
	v_mul_f32_e32 v10, v14, v15
	v_cvt_pk_bf16_f32 v8, v2, v8
	v_cvt_pk_bf16_f32 v9, v9, v10
	global_store_dwordx2 v[0:1], v[8:9], off offset:1888
	v_mov_b64_e32 v[8:9], v[214:215]
	v_lshlrev_b32_e32 v10, 16, v70
	v_and_b32_e32 v12, 0xffff0000, v70
	v_lshlrev_b32_e32 v14, 16, v68
	v_and_b32_e32 v16, 0xffff0000, v68
	v_or_b32_e32 v18, 0x3a0, v32
	v_mov_b32_e32 v19, v33
	v_lshl_add_u64 v[18:19], v[4:5], 0, v[18:19]
	v_lshlrev_b32_e32 v11, 16, v8
	v_and_b32_e32 v13, 0xffff0000, v8
	v_lshlrev_b32_e32 v15, 16, v9
	v_and_b32_e32 v17, 0xffff0000, v9
	v_mul_f32_e32 v2, 0xbfb8aa3b, v11
	v_mul_f32_e32 v8, 0xbfb8aa3b, v13
	v_mul_f32_e32 v9, 0xbfb8aa3b, v15
	v_mul_f32_e32 v23, 0xbfb8aa3b, v17
	v_exp_f32_e32 v2, v2
	v_exp_f32_e32 v8, v8
	v_exp_f32_e32 v9, v9
	v_exp_f32_e32 v23, v23
	v_add_f32_e32 v2, 1.0, v2
	v_add_f32_e32 v8, 1.0, v8
	v_add_f32_e32 v9, 1.0, v9
	v_add_f32_e32 v29, 1.0, v23
	v_rcp_f32_e32 v23, v2
	v_rcp_f32_e32 v25, v8
	v_rcp_f32_e32 v27, v9
	v_rcp_f32_e32 v29, v29
	v_pk_mul_f32 v[8:9], v[22:23], v[10:11]
	v_pk_mul_f32 v[10:11], v[24:25], v[12:13]
	v_pk_mul_f32 v[12:13], v[26:27], v[14:15]
	v_pk_mul_f32 v[14:15], v[28:29], v[16:17]
	v_mul_f32_e32 v2, v8, v9
	v_mul_f32_e32 v8, v10, v11
	v_mul_f32_e32 v9, v12, v13
	v_mul_f32_e32 v10, v14, v15
	v_cvt_pk_bf16_f32 v8, v2, v8
	v_cvt_pk_bf16_f32 v9, v9, v10
	global_store_dwordx2 v[0:1], v[8:9], off offset:1920
	v_mov_b64_e32 v[8:9], v[216:217]
	v_lshlrev_b32_e32 v10, 16, v66
	v_and_b32_e32 v12, 0xffff0000, v66
	v_lshlrev_b32_e32 v14, 16, v64
	v_and_b32_e32 v16, 0xffff0000, v64
	v_or_b32_e32 v18, 0x3c0, v32
	v_mov_b32_e32 v19, v33
	v_lshl_add_u64 v[18:19], v[4:5], 0, v[18:19]
	v_or_b32_e32 v32, 0x3e0, v32
	v_lshl_add_u64 v[4:5], v[4:5], 0, v[32:33]
	v_lshlrev_b32_e32 v11, 16, v8
	v_and_b32_e32 v13, 0xffff0000, v8
	v_lshlrev_b32_e32 v15, 16, v9
	v_and_b32_e32 v17, 0xffff0000, v9
	v_mul_f32_e32 v2, 0xbfb8aa3b, v11
	v_mul_f32_e32 v8, 0xbfb8aa3b, v13
	v_mul_f32_e32 v9, 0xbfb8aa3b, v15
	v_mul_f32_e32 v23, 0xbfb8aa3b, v17
	v_exp_f32_e32 v2, v2
	v_exp_f32_e32 v8, v8
	v_exp_f32_e32 v9, v9
	v_exp_f32_e32 v23, v23
	v_add_f32_e32 v2, 1.0, v2
	v_add_f32_e32 v8, 1.0, v8
	v_add_f32_e32 v9, 1.0, v9
	v_add_f32_e32 v29, 1.0, v23
	v_rcp_f32_e32 v23, v2
	v_rcp_f32_e32 v25, v8
	v_rcp_f32_e32 v27, v9
	v_rcp_f32_e32 v29, v29
	v_pk_mul_f32 v[8:9], v[22:23], v[10:11]
	v_pk_mul_f32 v[10:11], v[24:25], v[12:13]
	v_pk_mul_f32 v[12:13], v[26:27], v[14:15]
	v_pk_mul_f32 v[14:15], v[28:29], v[16:17]
	v_mul_f32_e32 v2, v8, v9
	v_mul_f32_e32 v8, v10, v11
	v_mul_f32_e32 v9, v12, v13
	v_mul_f32_e32 v10, v14, v15
	v_cvt_pk_bf16_f32 v8, v2, v8
	v_cvt_pk_bf16_f32 v9, v9, v10
	global_store_dwordx2 v[0:1], v[8:9], off offset:1952
	v_mov_b64_e32 v[8:9], v[218:219]
	v_lshlrev_b32_e32 v10, 16, v21
	v_and_b32_e32 v12, 0xffff0000, v21
	v_lshlrev_b32_e32 v14, 16, v20
	v_and_b32_e32 v16, 0xffff0000, v20
	v_mov_b32_e32 v18, v3
	v_mov_b32_e32 v20, v3
	v_lshlrev_b32_e32 v11, 16, v8
	v_and_b32_e32 v13, 0xffff0000, v8
	v_lshlrev_b32_e32 v15, 16, v9
	v_and_b32_e32 v17, 0xffff0000, v9
	v_mul_f32_e32 v2, 0xbfb8aa3b, v11
	v_mul_f32_e32 v8, 0xbfb8aa3b, v13
	v_mul_f32_e32 v9, 0xbfb8aa3b, v15
	v_mul_f32_e32 v19, 0xbfb8aa3b, v17
	v_exp_f32_e32 v2, v2
	v_exp_f32_e32 v8, v8
	v_exp_f32_e32 v9, v9
	v_exp_f32_e32 v19, v19
	v_add_f32_e32 v2, 1.0, v2
	v_add_f32_e32 v8, 1.0, v8
	v_add_f32_e32 v9, 1.0, v9
	v_add_f32_e32 v25, 1.0, v19
	v_rcp_f32_e32 v19, v2
	v_rcp_f32_e32 v21, v8
	v_rcp_f32_e32 v23, v9
	v_rcp_f32_e32 v25, v25
	v_pk_mul_f32 v[8:9], v[18:19], v[10:11]
	v_pk_mul_f32 v[10:11], v[20:21], v[12:13]
	v_pk_mul_f32 v[12:13], v[22:23], v[14:15]
	v_pk_mul_f32 v[14:15], v[24:25], v[16:17]
	v_mul_f32_e32 v2, v8, v9
	v_mul_f32_e32 v8, v10, v11
	v_mul_f32_e32 v9, v12, v13
	v_mul_f32_e32 v10, v14, v15
	v_cvt_pk_bf16_f32 v8, v2, v8
	v_cvt_pk_bf16_f32 v9, v9, v10
	global_store_dwordx2 v[0:1], v[8:9], off offset:1984
	v_mov_b64_e32 v[4:5], v[220:221]
	v_mov_b32_e32 v12, v3
	v_mov_b32_e32 v14, v3
	v_mov_b32_e32 v16, v3
	v_lshlrev_b32_e32 v2, 16, v7
	v_and_b32_e32 v8, 0xffff0000, v7
	v_lshlrev_b32_e32 v10, 16, v6
	v_and_b32_e32 v6, 0xffff0000, v6
	v_lshlrev_b32_e32 v3, 16, v4
	v_and_b32_e32 v9, 0xffff0000, v4
	v_lshlrev_b32_e32 v11, 16, v5
	v_and_b32_e32 v7, 0xffff0000, v5
	v_mul_f32_e32 v4, 0xbfb8aa3b, v3
	v_mul_f32_e32 v5, 0xbfb8aa3b, v9
	v_mul_f32_e32 v13, 0xbfb8aa3b, v11
	v_mul_f32_e32 v15, 0xbfb8aa3b, v7
	v_exp_f32_e32 v4, v4
	v_exp_f32_e32 v5, v5
	v_exp_f32_e32 v13, v13
	v_exp_f32_e32 v15, v15
	v_add_f32_e32 v4, 1.0, v4
	v_add_f32_e32 v5, 1.0, v5
	v_add_f32_e32 v17, 1.0, v13
	v_add_f32_e32 v19, 1.0, v15
	v_rcp_f32_e32 v13, v4
	v_rcp_f32_e32 v15, v5
	v_rcp_f32_e32 v17, v17
	v_rcp_f32_e32 v19, v19
	v_pk_mul_f32 v[2:3], v[12:13], v[2:3]
	v_pk_mul_f32 v[4:5], v[14:15], v[8:9]
	v_pk_mul_f32 v[8:9], v[16:17], v[10:11]
	v_pk_mul_f32 v[6:7], v[18:19], v[6:7]
	v_mul_f32_e32 v2, v2, v3
	v_mul_f32_e32 v3, v4, v5
	v_mul_f32_e32 v4, v8, v9
	v_mul_f32_e32 v5, v6, v7
	v_cvt_pk_bf16_f32 v2, v2, v3
	v_cvt_pk_bf16_f32 v3, v4, v5
	global_store_dwordx2 v[0:1], v[2:3], off offset:2016
	s_cbranch_scc1 .LBB0_900
